# waves 4-7 defer their last in-loop barrier of a unit to the next K-loop entry instead of waves 0-3 waiting at loop exit
# speedup vs baseline: 1.0076x; 1.0076x over previous
; #define PG8_STAGE(bufoff, gbase, voff) do { _Pragma("unroll") for (int _i = 0; _i < 2; ++_i) \
;         __builtin_amdgcn_global_load_lds((const unsigned*)((const char*)(gbase) + (voff)[_i]), (PG8_LAS unsigned*)(lds + (bufoff) + ldsw + _i * 8192), 16, 0, 0); } while (0)
; #define PG8_LDA(dst, b, h) do { _Pragma("unroll") for (int m = 0; m < 4; ++m) _Pragma("unroll") for (int k = 0; k < 2; ++k) dst[m][k] = *(const PG8_LAS bf16x8*)(lds + PG8_SA(b, h) + aoff + m * 2048 + k * 1024); } while (0)
; #define PG8_LDB(dst, b, h) do { _Pragma("unroll") for (int n = 0; n < 2; ++n) _Pragma("unroll") for (int k = 0; k < 2; ++k) dst[n][k] = *(const PG8_LAS bf16x8*)(lds + PG8_SB(b, h) + boff + n * 2048 + k * 1024); } while (0)
; #define PG8_MMA(ai, bj, At, Bt) do { __builtin_amdgcn_s_setprio(1); _Pragma("unroll") for (int m = 0; m < 4; ++m) _Pragma("unroll") for (int n = 0; n < 2; ++n) _Pragma("unroll") for (int k = 0; k < 2; ++k) \
;         acc[ai][bj][m][n] = __builtin_amdgcn_mfma_f32_16x16x32_bf16(Bt[n][k], At[m][k], acc[ai][bj][m][n], 0, 0, 0); __builtin_amdgcn_s_setprio(0); } while (0)
; #define PG8_WAIT_V(n) asm volatile("s_waitcnt vmcnt(" #n ")" ::: "memory")
; #define PG8_WAIT_L(n) asm volatile("s_waitcnt lgkmcnt(" #n ")" ::: "memory")
; template <class Epi, class Sched>
; __device__ __forceinline__ void gemm_phase(PG8_LAS unsigned char* lds, const Gemm g, const Sched& S, const Epi& E) {
;     ...
;             const bool last = (t == nt - 2);
;             const char* a1 = cA + (size_t)(t + 1) * kstep;
;             const char* a2 = last ? nA : cA + (size_t)(t + 2) * kstep; const char* b2 = last ? nB : cB + (size_t)(t + 2) * kstepB;
;             const char* a3 = a2 + kstep; const char* b3 = b2 + kstepB;
;             if (last && has_next) S.a_ready(nxt);
;             PG8_LDB(B0, 0, 0); PG8_SCHED; PG8_LDA(At, 0, 0); PG8_STAGE(PG8_SA(1, 1), a1 + hstep, voffA);
;             PG8_WAIT_L(8); PG8_BAR; PG8_WAIT_L(0); PG8_MMA(0, 0, At, B0); PG8_BAR; PG8_SCHED;
;             PG8_LDB(B1, 0, 1); PG8_STAGE(PG8_SB(0, 0), b2, voffB);
;             PG8_BAR; PG8_WAIT_L(0); PG8_MMA(0, 1, At, B1); PG8_BAR;
;             PG8_LDA(At, 0, 1); PG8_STAGE(PG8_SA(0, 0), a2, voffA);
;             PG8_BAR; PG8_WAIT_L(0); PG8_MMA(1, 0, At, B0); PG8_BAR; PG8_SCHED;
;             PG8_STAGE(PG8_SB(0, 1), b2 + hstepB, voffB);
;             PG8_WAIT_V(6); PG8_BAR; PG8_MMA(1, 1, At, B1); PG8_BAR;
.Lhalf_skip_y_0:
.LBB0_79:
	ds_read_b128 v[152:155], v149
	ds_read_b128 v[156:159], v149 offset:1024
	ds_read_b128 v[160:163], v149 offset:2048
	ds_read_b128 v[164:167], v149 offset:3072
	s_add_u32 s24, s22, 0xfff80080
	s_addc_u32 s25, s23, -1
	s_cmp_eq_u32 s61, 28
	s_cselect_b32 s27, s13, s25
	s_cselect_b32 s26, s57, s24
	s_cselect_b32 s25, s15, s60
	s_cselect_b32 s24, s58, s59
	v_lshl_add_u64 v[144:145], s[22:23], 0, v[136:137]
	s_add_i32 m0, s21, 0xc000
	ds_read_b128 v[168:171], v150
	ds_read_b128 v[172:175], v150 offset:1024
	ds_read_b128 v[176:179], v150 offset:2048
	ds_read_b128 v[180:183], v150 offset:3072
	ds_read_b128 v[184:187], v150 offset:4096
	ds_read_b128 v[188:191], v150 offset:5120
	ds_read_b128 v[192:195], v150 offset:6144
	ds_read_b128 v[196:199], v150 offset:7168
	global_load_lds_dwordx4 v[144:145], off
	v_lshl_add_u64 v[144:145], s[22:23], 0, v[138:139]
	s_add_i32 m0, s21, 0xe000
	s_nop 0
	global_load_lds_dwordx4 v[144:145], off
	s_add_i32 s62, s53, s38
	v_lshl_add_u64 v[144:145], s[24:25], 0, v[128:129]
	s_mov_b32 m0, s62
	ds_read_b128 v[200:203], v151
	ds_read_b128 v[204:207], v151 offset:1024
	ds_read_b128 v[208:211], v151 offset:2048
	ds_read_b128 v[212:215], v151 offset:3072
	s_waitcnt vmcnt(8)
	s_waitcnt lgkmcnt(0)
	s_barrier
	v_mfma_f32_16x16x32_bf16 v[124:127], v[152:155], v[168:171], v[124:127]
	v_mfma_f32_16x16x32_bf16 v[120:123], v[160:163], v[168:171], v[120:123]
	v_mfma_f32_16x16x32_bf16 v[108:111], v[152:155], v[176:179], v[108:111]
	v_mfma_f32_16x16x32_bf16 v[104:107], v[160:163], v[176:179], v[104:107]
	v_mfma_f32_16x16x32_bf16 v[92:95], v[152:155], v[184:187], v[92:95]
	v_mfma_f32_16x16x32_bf16 v[88:91], v[160:163], v[184:187], v[88:91]
	v_mfma_f32_16x16x32_bf16 v[76:79], v[152:155], v[192:195], v[76:79]
	v_mfma_f32_16x16x32_bf16 v[72:75], v[160:163], v[192:195], v[72:75]
	v_mfma_f32_16x16x32_bf16 v[124:127], v[156:159], v[172:175], v[124:127]
	v_mfma_f32_16x16x32_bf16 v[120:123], v[164:167], v[172:175], v[120:123]
	v_mfma_f32_16x16x32_bf16 v[108:111], v[156:159], v[180:183], v[108:111]
	v_mfma_f32_16x16x32_bf16 v[104:107], v[164:167], v[180:183], v[104:107]
	v_mfma_f32_16x16x32_bf16 v[92:95], v[156:159], v[188:191], v[92:95]
	v_mfma_f32_16x16x32_bf16 v[88:91], v[164:167], v[188:191], v[88:91]
	v_mfma_f32_16x16x32_bf16 v[76:79], v[156:159], v[196:199], v[76:79]
	v_mfma_f32_16x16x32_bf16 v[72:75], v[164:167], v[196:199], v[72:75]
	v_mfma_f32_16x16x32_bf16 v[116:119], v[200:203], v[168:171], v[116:119]
	v_mfma_f32_16x16x32_bf16 v[112:115], v[208:211], v[168:171], v[112:115]
	v_mfma_f32_16x16x32_bf16 v[100:103], v[200:203], v[176:179], v[100:103]
	v_mfma_f32_16x16x32_bf16 v[96:99], v[208:211], v[176:179], v[96:99]
	v_mfma_f32_16x16x32_bf16 v[84:87], v[200:203], v[184:187], v[84:87]
	v_mfma_f32_16x16x32_bf16 v[80:83], v[208:211], v[184:187], v[80:83]
	v_mfma_f32_16x16x32_bf16 v[68:71], v[200:203], v[192:195], v[68:71]
	v_mfma_f32_16x16x32_bf16 v[64:67], v[208:211], v[192:195], v[64:67]
	v_mfma_f32_16x16x32_bf16 v[116:119], v[204:207], v[172:175], v[116:119]
	v_mfma_f32_16x16x32_bf16 v[112:115], v[212:215], v[172:175], v[112:115]
	v_mfma_f32_16x16x32_bf16 v[100:103], v[204:207], v[180:183], v[100:103]
	v_mfma_f32_16x16x32_bf16 v[96:99], v[212:215], v[180:183], v[96:99]
	v_mfma_f32_16x16x32_bf16 v[84:87], v[204:207], v[188:191], v[84:87]
	v_mfma_f32_16x16x32_bf16 v[80:83], v[212:215], v[188:191], v[80:83]
	v_mfma_f32_16x16x32_bf16 v[68:71], v[204:207], v[196:199], v[68:71]
	v_mfma_f32_16x16x32_bf16 v[64:67], v[212:215], v[196:199], v[64:67]
	s_barrier
	global_load_lds_dwordx4 v[144:145], off
	v_lshl_add_u64 v[144:145], s[24:25], 0, v[130:131]
	s_add_i32 m0, s62, 0x2000
	s_nop 0
	global_load_lds_dwordx4 v[144:145], off
	s_mov_b32 m0, s21
	v_lshl_add_u64 v[144:145], s[26:27], 0, v[134:135]
	ds_read_b128 v[168:171], v150 offset:16384
	ds_read_b128 v[172:175], v150 offset:17408
	ds_read_b128 v[176:179], v150 offset:18432
	ds_read_b128 v[180:183], v150 offset:19456
	ds_read_b128 v[184:187], v150 offset:20480
	ds_read_b128 v[188:191], v150 offset:21504
	ds_read_b128 v[192:195], v150 offset:22528
	ds_read_b128 v[196:199], v150 offset:23552
	global_load_lds_dwordx4 v[144:145], off
	v_lshl_add_u64 v[216:217], s[26:27], 0, v[132:133]
	s_mov_b32 m0, s46
	s_nop 0
	global_load_lds_dwordx4 v[216:217], off
	s_add_u32 s62, s24, 0x4000
	s_addc_u32 s63, s25, 0
	s_add_i32 s64, s54, s38
	v_lshl_add_u64 v[250:251], s[62:63], 0, v[128:129]
	s_mov_b32 m0, s64
	s_nop 0
	global_load_lds_dwordx4 v[250:251], off
	v_lshl_add_u64 v[250:251], s[62:63], 0, v[130:131]
	s_add_i32 m0, s64, 0x2000
	s_nop 0
	global_load_lds_dwordx4 v[250:251], off
	s_waitcnt vmcnt(8)
	s_waitcnt lgkmcnt(0)
	s_barrier
; #define PG8_STAGE(bufoff, gbase, voff) do { _Pragma("unroll") for (int _i = 0; _i < 2; ++_i) \
;         __builtin_amdgcn_global_load_lds((const unsigned*)((const char*)(gbase) + (voff)[_i]), (PG8_LAS unsigned*)(lds + (bufoff) + ldsw + _i * 8192), 16, 0, 0); } while (0)
; #define PG8_LDA(dst, b, h) do { _Pragma("unroll") for (int m = 0; m < 4; ++m) _Pragma("unroll") for (int k = 0; k < 2; ++k) dst[m][k] = *(const PG8_LAS bf16x8*)(lds + PG8_SA(b, h) + aoff + m * 2048 + k * 1024); } while (0)
; #define PG8_LDB(dst, b, h) do { _Pragma("unroll") for (int n = 0; n < 2; ++n) _Pragma("unroll") for (int k = 0; k < 2; ++k) dst[n][k] = *(const PG8_LAS bf16x8*)(lds + PG8_SB(b, h) + boff + n * 2048 + k * 1024); } while (0)
; #define PG8_MMA(ai, bj, At, Bt) do { __builtin_amdgcn_s_setprio(1); _Pragma("unroll") for (int m = 0; m < 4; ++m) _Pragma("unroll") for (int n = 0; n < 2; ++n) _Pragma("unroll") for (int k = 0; k < 2; ++k) \
;         acc[ai][bj][m][n] = __builtin_amdgcn_mfma_f32_16x16x32_bf16(Bt[n][k], At[m][k], acc[ai][bj][m][n], 0, 0, 0); __builtin_amdgcn_s_setprio(0); } while (0)
; #define PG8_WAIT_V(n) asm volatile("s_waitcnt vmcnt(" #n ")" ::: "memory")
; #define PG8_WAIT_L(n) asm volatile("s_waitcnt lgkmcnt(" #n ")" ::: "memory")
; #define PG8_BAR __builtin_amdgcn_s_barrier()
; #define PG8_SCHED __builtin_amdgcn_sched_barrier(0)
; template <class Epi, class Sched>
; __device__ __forceinline__ void gemm_phase(PG8_LAS unsigned char* lds, const Gemm g, const Sched& S, const Epi& E) {
;     ...
;             PG8_BAR; PG8_WAIT_L(0); PG8_MMA(1, 0, At, B0); PG8_BAR; PG8_SCHED;
;             PG8_STAGE(PG8_SB(0, 1), b2 + hstepB, voffB);
;             PG8_WAIT_V(6); PG8_BAR; PG8_MMA(1, 1, At, B1); PG8_BAR;
;             PG8_LDB(B0, 1, 0); PG8_SCHED; PG8_LDA(At, 1, 0); PG8_STAGE(PG8_SA(0, 1), a2 + hstep, voffA);
;             PG8_WAIT_L(8); PG8_BAR; PG8_WAIT_L(0); PG8_MMA(0, 0, At, B0); PG8_BAR; PG8_SCHED;
;             PG8_LDB(B1, 1, 1); PG8_STAGE(PG8_SB(1, 0), b3, voffB);
;             PG8_BAR; PG8_WAIT_L(0); PG8_MMA(0, 1, At, B1); PG8_BAR;
;             PG8_LDA(At, 1, 1); PG8_STAGE(PG8_SA(1, 0), a3, voffA);
;             PG8_BAR; PG8_WAIT_L(0); PG8_MMA(1, 0, At, B0); PG8_BAR; PG8_SCHED;
	v_mfma_f32_16x16x32_bf16 v[60:63], v[152:155], v[168:171], v[60:63]
	v_mfma_f32_16x16x32_bf16 v[56:59], v[160:163], v[168:171], v[56:59]
	v_mfma_f32_16x16x32_bf16 v[44:47], v[152:155], v[176:179], v[44:47]
	v_mfma_f32_16x16x32_bf16 v[40:43], v[160:163], v[176:179], v[40:43]
	v_mfma_f32_16x16x32_bf16 v[28:31], v[152:155], v[184:187], v[28:31]
	v_mfma_f32_16x16x32_bf16 v[24:27], v[160:163], v[184:187], v[24:27]
	v_mfma_f32_16x16x32_bf16 v[12:15], v[152:155], v[192:195], v[12:15]
	v_mfma_f32_16x16x32_bf16 v[8:11], v[160:163], v[192:195], v[8:11]
	v_mfma_f32_16x16x32_bf16 v[60:63], v[156:159], v[172:175], v[60:63]
	v_mfma_f32_16x16x32_bf16 v[56:59], v[164:167], v[172:175], v[56:59]
	v_mfma_f32_16x16x32_bf16 v[44:47], v[156:159], v[180:183], v[44:47]
	v_mfma_f32_16x16x32_bf16 v[40:43], v[164:167], v[180:183], v[40:43]
	v_mfma_f32_16x16x32_bf16 v[28:31], v[156:159], v[188:191], v[28:31]
	v_mfma_f32_16x16x32_bf16 v[24:27], v[164:167], v[188:191], v[24:27]
	v_mfma_f32_16x16x32_bf16 v[12:15], v[156:159], v[196:199], v[12:15]
	v_mfma_f32_16x16x32_bf16 v[8:11], v[164:167], v[196:199], v[8:11]
	v_mfma_f32_16x16x32_bf16 v[52:55], v[200:203], v[168:171], v[52:55]
	v_mfma_f32_16x16x32_bf16 v[48:51], v[208:211], v[168:171], v[48:51]
	v_mfma_f32_16x16x32_bf16 v[36:39], v[200:203], v[176:179], v[36:39]
	v_mfma_f32_16x16x32_bf16 v[32:35], v[208:211], v[176:179], v[32:35]
	v_mfma_f32_16x16x32_bf16 v[20:23], v[200:203], v[184:187], v[20:23]
	v_mfma_f32_16x16x32_bf16 v[16:19], v[208:211], v[184:187], v[16:19]
	v_mfma_f32_16x16x32_bf16 v[4:7], v[200:203], v[192:195], v[4:7]
	v_mfma_f32_16x16x32_bf16 v[0:3], v[208:211], v[192:195], v[0:3]
	v_mfma_f32_16x16x32_bf16 v[52:55], v[204:207], v[172:175], v[52:55]
	v_mfma_f32_16x16x32_bf16 v[48:51], v[212:215], v[172:175], v[48:51]
	v_mfma_f32_16x16x32_bf16 v[36:39], v[204:207], v[180:183], v[36:39]
	v_mfma_f32_16x16x32_bf16 v[32:35], v[212:215], v[180:183], v[32:35]
	v_mfma_f32_16x16x32_bf16 v[20:23], v[204:207], v[188:191], v[20:23]
	v_mfma_f32_16x16x32_bf16 v[16:19], v[212:215], v[188:191], v[16:19]
	v_mfma_f32_16x16x32_bf16 v[4:7], v[204:207], v[196:199], v[4:7]
	v_mfma_f32_16x16x32_bf16 v[0:3], v[212:215], v[196:199], v[0:3]
	s_barrier
	s_add_i32 s62, 0, 0x18000
	v_add_u32_e32 v164, s62, v147
	ds_read_b128 v[152:155], v164
	ds_read_b128 v[156:159], v164 offset:1024
	ds_read_b128 v[160:163], v164 offset:2048
	ds_read_b128 v[164:167], v164 offset:3072
	s_add_u32 s26, s26, 0x80000
	s_addc_u32 s27, s27, 0
	s_mov_b32 m0, s47
	v_lshl_add_u64 v[200:201], s[26:27], 0, v[134:135]
	ds_read_b128 v[168:171], v150 offset:32768
	ds_read_b128 v[172:175], v150 offset:33792
	ds_read_b128 v[176:179], v150 offset:34816
	ds_read_b128 v[180:183], v150 offset:35840
	ds_read_b128 v[184:187], v150 offset:36864
	ds_read_b128 v[188:191], v150 offset:37888
	ds_read_b128 v[192:195], v150 offset:38912
	ds_read_b128 v[196:199], v150 offset:39936
	global_load_lds_dwordx4 v[200:201], off
	v_lshl_add_u64 v[200:201], s[26:27], 0, v[132:133]
	s_mov_b32 m0, s48
	s_nop 0
	global_load_lds_dwordx4 v[200:201], off
	s_add_i32 s63, 0, 0x1c000
	s_add_u32 s26, s24, 0x8000
	s_addc_u32 s27, s25, 0
	s_add_i32 s62, s62, s38
	v_add_u32_e32 v212, s63, v147
	v_lshl_add_u64 v[218:219], s[26:27], 0, v[128:129]
	s_mov_b32 m0, s62
	ds_read_b128 v[200:203], v212
	ds_read_b128 v[204:207], v212 offset:1024
	ds_read_b128 v[208:211], v212 offset:2048
	ds_read_b128 v[212:215], v212 offset:3072
	s_waitcnt vmcnt(8)
	s_waitcnt lgkmcnt(0)
	s_barrier
	v_mfma_f32_16x16x32_bf16 v[124:127], v[152:155], v[168:171], v[124:127]
	v_mfma_f32_16x16x32_bf16 v[120:123], v[160:163], v[168:171], v[120:123]
	v_mfma_f32_16x16x32_bf16 v[108:111], v[152:155], v[176:179], v[108:111]
	v_mfma_f32_16x16x32_bf16 v[104:107], v[160:163], v[176:179], v[104:107]
	v_mfma_f32_16x16x32_bf16 v[92:95], v[152:155], v[184:187], v[92:95]
	v_mfma_f32_16x16x32_bf16 v[88:91], v[160:163], v[184:187], v[88:91]
	v_mfma_f32_16x16x32_bf16 v[76:79], v[152:155], v[192:195], v[76:79]
	v_mfma_f32_16x16x32_bf16 v[72:75], v[160:163], v[192:195], v[72:75]
	v_mfma_f32_16x16x32_bf16 v[124:127], v[156:159], v[172:175], v[124:127]
	v_mfma_f32_16x16x32_bf16 v[120:123], v[164:167], v[172:175], v[120:123]
	v_mfma_f32_16x16x32_bf16 v[108:111], v[156:159], v[180:183], v[108:111]
	v_mfma_f32_16x16x32_bf16 v[104:107], v[164:167], v[180:183], v[104:107]
	v_mfma_f32_16x16x32_bf16 v[92:95], v[156:159], v[188:191], v[92:95]
	v_mfma_f32_16x16x32_bf16 v[88:91], v[164:167], v[188:191], v[88:91]
	v_mfma_f32_16x16x32_bf16 v[76:79], v[156:159], v[196:199], v[76:79]
	v_mfma_f32_16x16x32_bf16 v[72:75], v[164:167], v[196:199], v[72:75]
	v_mfma_f32_16x16x32_bf16 v[116:119], v[200:203], v[168:171], v[116:119]
	v_mfma_f32_16x16x32_bf16 v[112:115], v[208:211], v[168:171], v[112:115]
	v_mfma_f32_16x16x32_bf16 v[100:103], v[200:203], v[176:179], v[100:103]
	v_mfma_f32_16x16x32_bf16 v[96:99], v[208:211], v[176:179], v[96:99]
	v_mfma_f32_16x16x32_bf16 v[84:87], v[200:203], v[184:187], v[84:87]
	v_mfma_f32_16x16x32_bf16 v[80:83], v[208:211], v[184:187], v[80:83]
	v_mfma_f32_16x16x32_bf16 v[68:71], v[200:203], v[192:195], v[68:71]
	v_mfma_f32_16x16x32_bf16 v[64:67], v[208:211], v[192:195], v[64:67]
	v_mfma_f32_16x16x32_bf16 v[116:119], v[204:207], v[172:175], v[116:119]
	v_mfma_f32_16x16x32_bf16 v[112:115], v[212:215], v[172:175], v[112:115]
	v_mfma_f32_16x16x32_bf16 v[100:103], v[204:207], v[180:183], v[100:103]
	v_mfma_f32_16x16x32_bf16 v[96:99], v[212:215], v[180:183], v[96:99]
	v_mfma_f32_16x16x32_bf16 v[84:87], v[204:207], v[188:191], v[84:87]
	v_mfma_f32_16x16x32_bf16 v[80:83], v[212:215], v[188:191], v[80:83]
	v_mfma_f32_16x16x32_bf16 v[68:71], v[204:207], v[196:199], v[68:71]
	v_mfma_f32_16x16x32_bf16 v[64:67], v[212:215], v[196:199], v[64:67]
	s_barrier
; #define PG8_STAGE(bufoff, gbase, voff) do { _Pragma("unroll") for (int _i = 0; _i < 2; ++_i) \
;         __builtin_amdgcn_global_load_lds((const unsigned*)((const char*)(gbase) + (voff)[_i]), (PG8_LAS unsigned*)(lds + (bufoff) + ldsw + _i * 8192), 16, 0, 0); } while (0)
; #define PG8_LDA(dst, b, h) do { _Pragma("unroll") for (int m = 0; m < 4; ++m) _Pragma("unroll") for (int k = 0; k < 2; ++k) dst[m][k] = *(const PG8_LAS bf16x8*)(lds + PG8_SA(b, h) + aoff + m * 2048 + k * 1024); } while (0)
; #define PG8_MMA(ai, bj, At, Bt) do { __builtin_amdgcn_s_setprio(1); _Pragma("unroll") for (int m = 0; m < 4; ++m) _Pragma("unroll") for (int n = 0; n < 2; ++n) _Pragma("unroll") for (int k = 0; k < 2; ++k) \
;         acc[ai][bj][m][n] = __builtin_amdgcn_mfma_f32_16x16x32_bf16(Bt[n][k], At[m][k], acc[ai][bj][m][n], 0, 0, 0); __builtin_amdgcn_s_setprio(0); } while (0)
; #define PG8_WAIT_V(n) asm volatile("s_waitcnt vmcnt(" #n ")" ::: "memory")
; #define PG8_WAIT_L(n) asm volatile("s_waitcnt lgkmcnt(" #n ")" ::: "memory")
; #define PG8_BAR __builtin_amdgcn_s_barrier()
; #define PG8_SCHED __builtin_amdgcn_sched_barrier(0)
; template <class Epi, class Sched>
; __device__ __forceinline__ void gemm_phase(PG8_LAS unsigned char* lds, const Gemm g, const Sched& S, const Epi& E) {
;     ...
;             PG8_LDA(At, 1, 1); PG8_STAGE(PG8_SA(1, 0), a3, voffA);
;             PG8_BAR; PG8_WAIT_L(0); PG8_MMA(1, 0, At, B0); PG8_BAR; PG8_SCHED;
;             PG8_STAGE(PG8_SB(1, 1), b3 + hstepB, voffB);
;             PG8_WAIT_V(6); PG8_BAR; PG8_MMA(1, 1, At, B1); PG8_BAR;
;     ...
;     PG8_WAIT_V(0);
;     if (wr == 0) PG8_BAR;
;     PG8_BAR;
	global_load_lds_dwordx4 v[218:219], off
	v_lshl_add_u64 v[218:219], s[26:27], 0, v[130:131]
	s_add_i32 m0, s62, 0x2000
	s_nop 0
	global_load_lds_dwordx4 v[218:219], off
	s_mov_b32 m0, s50
	v_lshl_add_u64 v[144:145], v[144:145], 0, s[10:11]
	ds_read_b128 v[168:171], v150 offset:49152
	ds_read_b128 v[172:175], v150 offset:50176
	ds_read_b128 v[176:179], v150 offset:51200
	ds_read_b128 v[180:183], v150 offset:52224
	ds_read_b128 v[184:187], v150 offset:53248
	ds_read_b128 v[188:191], v150 offset:54272
	ds_read_b128 v[192:195], v150 offset:55296
	ds_read_b128 v[196:199], v150 offset:56320
	global_load_lds_dwordx4 v[144:145], off
	v_lshl_add_u64 v[144:145], v[216:217], 0, s[10:11]
	s_mov_b32 m0, s51
	s_nop 0
	global_load_lds_dwordx4 v[144:145], off
	s_add_u32 s24, s24, 0xc000
	s_addc_u32 s25, s25, 0
	s_add_i32 s26, s63, s38
	v_lshl_add_u64 v[144:145], s[24:25], 0, v[128:129]
	s_mov_b32 m0, s26
	s_nop 0
	global_load_lds_dwordx4 v[144:145], off
	v_lshl_add_u64 v[144:145], s[24:25], 0, v[130:131]
	s_add_i32 m0, s26, 0x2000
	s_nop 0
	global_load_lds_dwordx4 v[144:145], off
	s_add_i32 s61, s61, 2
	s_add_u32 s59, s59, 0x10000
	s_addc_u32 s60, s60, 0
	s_add_u32 s22, s22, 0x100
	s_addc_u32 s23, s23, 0
	s_cmp_gt_u32 s61, 29
	s_waitcnt vmcnt(8)
	s_waitcnt lgkmcnt(0)
	s_barrier
	v_mfma_f32_16x16x32_bf16 v[60:63], v[152:155], v[168:171], v[60:63]
	v_mfma_f32_16x16x32_bf16 v[56:59], v[160:163], v[168:171], v[56:59]
	v_mfma_f32_16x16x32_bf16 v[44:47], v[152:155], v[176:179], v[44:47]
	v_mfma_f32_16x16x32_bf16 v[40:43], v[160:163], v[176:179], v[40:43]
	v_mfma_f32_16x16x32_bf16 v[28:31], v[152:155], v[184:187], v[28:31]
	v_mfma_f32_16x16x32_bf16 v[24:27], v[160:163], v[184:187], v[24:27]
	v_mfma_f32_16x16x32_bf16 v[12:15], v[152:155], v[192:195], v[12:15]
	v_mfma_f32_16x16x32_bf16 v[8:11], v[160:163], v[192:195], v[8:11]
	v_mfma_f32_16x16x32_bf16 v[60:63], v[156:159], v[172:175], v[60:63]
	v_mfma_f32_16x16x32_bf16 v[56:59], v[164:167], v[172:175], v[56:59]
	v_mfma_f32_16x16x32_bf16 v[44:47], v[156:159], v[180:183], v[44:47]
	v_mfma_f32_16x16x32_bf16 v[40:43], v[164:167], v[180:183], v[40:43]
	v_mfma_f32_16x16x32_bf16 v[28:31], v[156:159], v[188:191], v[28:31]
	v_mfma_f32_16x16x32_bf16 v[24:27], v[164:167], v[188:191], v[24:27]
	v_mfma_f32_16x16x32_bf16 v[12:15], v[156:159], v[196:199], v[12:15]
	v_mfma_f32_16x16x32_bf16 v[8:11], v[164:167], v[196:199], v[8:11]
	v_mfma_f32_16x16x32_bf16 v[52:55], v[200:203], v[168:171], v[52:55]
	v_mfma_f32_16x16x32_bf16 v[48:51], v[208:211], v[168:171], v[48:51]
	v_mfma_f32_16x16x32_bf16 v[36:39], v[200:203], v[176:179], v[36:39]
	v_mfma_f32_16x16x32_bf16 v[32:35], v[208:211], v[176:179], v[32:35]
	v_mfma_f32_16x16x32_bf16 v[20:23], v[200:203], v[184:187], v[20:23]
	v_mfma_f32_16x16x32_bf16 v[16:19], v[208:211], v[184:187], v[16:19]
	v_mfma_f32_16x16x32_bf16 v[4:7], v[200:203], v[192:195], v[4:7]
	v_mfma_f32_16x16x32_bf16 v[0:3], v[208:211], v[192:195], v[0:3]
	v_mfma_f32_16x16x32_bf16 v[52:55], v[204:207], v[172:175], v[52:55]
	v_mfma_f32_16x16x32_bf16 v[48:51], v[212:215], v[172:175], v[48:51]
	v_mfma_f32_16x16x32_bf16 v[36:39], v[204:207], v[180:183], v[36:39]
	v_mfma_f32_16x16x32_bf16 v[32:35], v[212:215], v[180:183], v[32:35]
	v_mfma_f32_16x16x32_bf16 v[20:23], v[204:207], v[188:191], v[20:23]
	v_mfma_f32_16x16x32_bf16 v[16:19], v[212:215], v[188:191], v[16:19]
	v_mfma_f32_16x16x32_bf16 v[4:7], v[204:207], v[196:199], v[4:7]
	v_mfma_f32_16x16x32_bf16 v[0:3], v[212:215], v[196:199], v[0:3]
	s_cbranch_scc1 .Lunit_exit_0
	s_barrier
	s_branch .LBB0_79
.Lunit_exit_0:
	s_cmp_eq_u32 s78, 1
	s_cbranch_scc1 .Lunit_skipb_0
	s_barrier

; #define PG8_STAGE(bufoff, gbase, voff) do { _Pragma("unroll") for (int _i = 0; _i < 2; ++_i) \
;         __builtin_amdgcn_global_load_lds((const unsigned*)((const char*)(gbase) + (voff)[_i]), (PG8_LAS unsigned*)(lds + (bufoff) + ldsw + _i * 8192), 16, 0, 0); } while (0)
; #define PG8_LDA(dst, b, h) do { _Pragma("unroll") for (int m = 0; m < 4; ++m) _Pragma("unroll") for (int k = 0; k < 2; ++k) dst[m][k] = *(const PG8_LAS bf16x8*)(lds + PG8_SA(b, h) + aoff + m * 2048 + k * 1024); } while (0)
; #define PG8_LDB(dst, b, h) do { _Pragma("unroll") for (int n = 0; n < 2; ++n) _Pragma("unroll") for (int k = 0; k < 2; ++k) dst[n][k] = *(const PG8_LAS bf16x8*)(lds + PG8_SB(b, h) + boff + n * 2048 + k * 1024); } while (0)
; #define PG8_MMA(ai, bj, At, Bt) do { __builtin_amdgcn_s_setprio(1); _Pragma("unroll") for (int m = 0; m < 4; ++m) _Pragma("unroll") for (int n = 0; n < 2; ++n) _Pragma("unroll") for (int k = 0; k < 2; ++k) \
;         acc[ai][bj][m][n] = __builtin_amdgcn_mfma_f32_16x16x32_bf16(Bt[n][k], At[m][k], acc[ai][bj][m][n], 0, 0, 0); __builtin_amdgcn_s_setprio(0); } while (0)
; #define PG8_WAIT_V(n) asm volatile("s_waitcnt vmcnt(" #n ")" ::: "memory")
; #define PG8_WAIT_L(n) asm volatile("s_waitcnt lgkmcnt(" #n ")" ::: "memory")
; template <class Epi, class Sched>
; __device__ __forceinline__ void gemm_phase(PG8_LAS unsigned char* lds, const Gemm g, const Sched& S, const Epi& E) {
;     ...
;             const bool last = (t == nt - 2);
;             const char* a1 = cA + (size_t)(t + 1) * kstep;
;             const char* a2 = last ? nA : cA + (size_t)(t + 2) * kstep; const char* b2 = last ? nB : cB + (size_t)(t + 2) * kstepB;
;             const char* a3 = a2 + kstep; const char* b3 = b2 + kstepB;
;             if (last && has_next) S.a_ready(nxt);
;             PG8_LDB(B0, 0, 0); PG8_SCHED; PG8_LDA(At, 0, 0); PG8_STAGE(PG8_SA(1, 1), a1 + hstep, voffA);
;             PG8_WAIT_L(8); PG8_BAR; PG8_WAIT_L(0); PG8_MMA(0, 0, At, B0); PG8_BAR; PG8_SCHED;
;             PG8_LDB(B1, 0, 1); PG8_STAGE(PG8_SB(0, 0), b2, voffB);
;             PG8_BAR; PG8_WAIT_L(0); PG8_MMA(0, 1, At, B1); PG8_BAR;
;             PG8_LDA(At, 0, 1); PG8_STAGE(PG8_SA(0, 0), a2, voffA);
;             PG8_BAR; PG8_WAIT_L(0); PG8_MMA(1, 0, At, B0); PG8_BAR; PG8_SCHED;
;             PG8_STAGE(PG8_SB(0, 1), b2 + hstepB, voffB);
;             PG8_WAIT_V(6); PG8_BAR; PG8_MMA(1, 1, At, B1); PG8_BAR;
.Lhalf_skip_y_1:
.LBB0_155:
	ds_read_b128 v[144:147], v153
	ds_read_b128 v[156:159], v153 offset:1024
	ds_read_b128 v[160:163], v153 offset:2048
	ds_read_b128 v[164:167], v153 offset:3072
	s_add_u32 s26, s24, 0x100
	s_addc_u32 s27, s25, 0
	s_cmpk_eq_i32 s67, 0x52
	s_cselect_b32 s31, s7, s27
	s_cselect_b32 s30, s6, s26
	s_cselect_b32 s29, s9, s66
	s_cselect_b32 s28, s8, s65
	v_lshl_add_u64 v[148:149], s[24:25], 0, v[136:137]
	s_add_i32 m0, s51, 0xc000
	ds_read_b128 v[168:171], v154
	ds_read_b128 v[172:175], v154 offset:1024
	ds_read_b128 v[176:179], v154 offset:2048
	ds_read_b128 v[180:183], v154 offset:3072
	ds_read_b128 v[184:187], v154 offset:4096
	ds_read_b128 v[188:191], v154 offset:5120
	ds_read_b128 v[192:195], v154 offset:6144
	ds_read_b128 v[196:199], v154 offset:7168
	global_load_lds_dwordx4 v[148:149], off
	v_lshl_add_u64 v[148:149], s[24:25], 0, v[138:139]
	s_add_i32 m0, s51, 0xe000
	s_nop 0
	global_load_lds_dwordx4 v[148:149], off
	s_add_i32 s24, s59, s50
	v_lshl_add_u64 v[148:149], s[28:29], 0, v[128:129]
	s_mov_b32 m0, s24
	ds_read_b128 v[200:203], v155
	ds_read_b128 v[204:207], v155 offset:1024
	ds_read_b128 v[208:211], v155 offset:2048
	ds_read_b128 v[212:215], v155 offset:3072
	s_waitcnt vmcnt(8)
	s_waitcnt lgkmcnt(0)
	s_barrier
	v_mfma_f32_16x16x32_bf16 v[124:127], v[144:147], v[168:171], v[124:127]
	v_mfma_f32_16x16x32_bf16 v[120:123], v[160:163], v[168:171], v[120:123]
	v_mfma_f32_16x16x32_bf16 v[108:111], v[144:147], v[176:179], v[108:111]
	v_mfma_f32_16x16x32_bf16 v[104:107], v[160:163], v[176:179], v[104:107]
	v_mfma_f32_16x16x32_bf16 v[92:95], v[144:147], v[184:187], v[92:95]
	v_mfma_f32_16x16x32_bf16 v[88:91], v[160:163], v[184:187], v[88:91]
	v_mfma_f32_16x16x32_bf16 v[76:79], v[144:147], v[192:195], v[76:79]
	v_mfma_f32_16x16x32_bf16 v[72:75], v[160:163], v[192:195], v[72:75]
	v_mfma_f32_16x16x32_bf16 v[124:127], v[156:159], v[172:175], v[124:127]
	v_mfma_f32_16x16x32_bf16 v[120:123], v[164:167], v[172:175], v[120:123]
	v_mfma_f32_16x16x32_bf16 v[108:111], v[156:159], v[180:183], v[108:111]
	v_mfma_f32_16x16x32_bf16 v[104:107], v[164:167], v[180:183], v[104:107]
	v_mfma_f32_16x16x32_bf16 v[92:95], v[156:159], v[188:191], v[92:95]
	v_mfma_f32_16x16x32_bf16 v[88:91], v[164:167], v[188:191], v[88:91]
	v_mfma_f32_16x16x32_bf16 v[76:79], v[156:159], v[196:199], v[76:79]
	v_mfma_f32_16x16x32_bf16 v[72:75], v[164:167], v[196:199], v[72:75]
	v_mfma_f32_16x16x32_bf16 v[116:119], v[200:203], v[168:171], v[116:119]
	v_mfma_f32_16x16x32_bf16 v[112:115], v[208:211], v[168:171], v[112:115]
	v_mfma_f32_16x16x32_bf16 v[100:103], v[200:203], v[176:179], v[100:103]
	v_mfma_f32_16x16x32_bf16 v[96:99], v[208:211], v[176:179], v[96:99]
	v_mfma_f32_16x16x32_bf16 v[84:87], v[200:203], v[184:187], v[84:87]
	v_mfma_f32_16x16x32_bf16 v[80:83], v[208:211], v[184:187], v[80:83]
	v_mfma_f32_16x16x32_bf16 v[68:71], v[200:203], v[192:195], v[68:71]
	v_mfma_f32_16x16x32_bf16 v[64:67], v[208:211], v[192:195], v[64:67]
	v_mfma_f32_16x16x32_bf16 v[116:119], v[204:207], v[172:175], v[116:119]
	v_mfma_f32_16x16x32_bf16 v[112:115], v[212:215], v[172:175], v[112:115]
	v_mfma_f32_16x16x32_bf16 v[100:103], v[204:207], v[180:183], v[100:103]
	v_mfma_f32_16x16x32_bf16 v[96:99], v[212:215], v[180:183], v[96:99]
	v_mfma_f32_16x16x32_bf16 v[84:87], v[204:207], v[188:191], v[84:87]
	v_mfma_f32_16x16x32_bf16 v[80:83], v[212:215], v[188:191], v[80:83]
	v_mfma_f32_16x16x32_bf16 v[68:71], v[204:207], v[196:199], v[68:71]
	v_mfma_f32_16x16x32_bf16 v[64:67], v[212:215], v[196:199], v[64:67]
	s_barrier
	global_load_lds_dwordx4 v[148:149], off
	v_lshl_add_u64 v[148:149], s[28:29], 0, v[132:133]
	s_add_i32 m0, s24, 0x2000
	s_nop 0
	global_load_lds_dwordx4 v[148:149], off
	s_mov_b32 m0, s51
	v_lshl_add_u64 v[148:149], s[30:31], 0, v[130:131]
	ds_read_b128 v[168:171], v154 offset:16384
	ds_read_b128 v[172:175], v154 offset:17408
	ds_read_b128 v[176:179], v154 offset:18432
	ds_read_b128 v[180:183], v154 offset:19456
	ds_read_b128 v[184:187], v154 offset:20480
	ds_read_b128 v[188:191], v154 offset:21504
	ds_read_b128 v[192:195], v154 offset:22528
	ds_read_b128 v[196:199], v154 offset:23552
	global_load_lds_dwordx4 v[148:149], off
	v_lshl_add_u64 v[216:217], s[30:31], 0, v[134:135]
	s_mov_b32 m0, s52
	s_nop 0
	global_load_lds_dwordx4 v[216:217], off
	s_add_u32 s24, s28, 0x4000
	s_addc_u32 s25, s29, 0
	s_add_i32 s68, s60, s50
	v_lshl_add_u64 v[250:251], s[24:25], 0, v[128:129]
	s_mov_b32 m0, s68
	s_nop 0
	global_load_lds_dwordx4 v[250:251], off
	v_lshl_add_u64 v[250:251], s[24:25], 0, v[132:133]
	s_add_i32 m0, s68, 0x2000
	s_nop 0
	global_load_lds_dwordx4 v[250:251], off
	s_waitcnt vmcnt(8)
	s_waitcnt lgkmcnt(0)
	s_barrier
; #define PG8_STAGE(bufoff, gbase, voff) do { _Pragma("unroll") for (int _i = 0; _i < 2; ++_i) \
;         __builtin_amdgcn_global_load_lds((const unsigned*)((const char*)(gbase) + (voff)[_i]), (PG8_LAS unsigned*)(lds + (bufoff) + ldsw + _i * 8192), 16, 0, 0); } while (0)
; #define PG8_LDA(dst, b, h) do { _Pragma("unroll") for (int m = 0; m < 4; ++m) _Pragma("unroll") for (int k = 0; k < 2; ++k) dst[m][k] = *(const PG8_LAS bf16x8*)(lds + PG8_SA(b, h) + aoff + m * 2048 + k * 1024); } while (0)
; #define PG8_LDB(dst, b, h) do { _Pragma("unroll") for (int n = 0; n < 2; ++n) _Pragma("unroll") for (int k = 0; k < 2; ++k) dst[n][k] = *(const PG8_LAS bf16x8*)(lds + PG8_SB(b, h) + boff + n * 2048 + k * 1024); } while (0)
; #define PG8_MMA(ai, bj, At, Bt) do { __builtin_amdgcn_s_setprio(1); _Pragma("unroll") for (int m = 0; m < 4; ++m) _Pragma("unroll") for (int n = 0; n < 2; ++n) _Pragma("unroll") for (int k = 0; k < 2; ++k) \
;         acc[ai][bj][m][n] = __builtin_amdgcn_mfma_f32_16x16x32_bf16(Bt[n][k], At[m][k], acc[ai][bj][m][n], 0, 0, 0); __builtin_amdgcn_s_setprio(0); } while (0)
; #define PG8_WAIT_V(n) asm volatile("s_waitcnt vmcnt(" #n ")" ::: "memory")
; #define PG8_WAIT_L(n) asm volatile("s_waitcnt lgkmcnt(" #n ")" ::: "memory")
; #define PG8_BAR __builtin_amdgcn_s_barrier()
; #define PG8_SCHED __builtin_amdgcn_sched_barrier(0)
; template <class Epi, class Sched>
; __device__ __forceinline__ void gemm_phase(PG8_LAS unsigned char* lds, const Gemm g, const Sched& S, const Epi& E) {
;     ...
;             PG8_BAR; PG8_WAIT_L(0); PG8_MMA(1, 0, At, B0); PG8_BAR; PG8_SCHED;
;             PG8_STAGE(PG8_SB(0, 1), b2 + hstepB, voffB);
;             PG8_WAIT_V(6); PG8_BAR; PG8_MMA(1, 1, At, B1); PG8_BAR;
;             PG8_LDB(B0, 1, 0); PG8_SCHED; PG8_LDA(At, 1, 0); PG8_STAGE(PG8_SA(0, 1), a2 + hstep, voffA);
;             PG8_WAIT_L(8); PG8_BAR; PG8_WAIT_L(0); PG8_MMA(0, 0, At, B0); PG8_BAR; PG8_SCHED;
;             PG8_LDB(B1, 1, 1); PG8_STAGE(PG8_SB(1, 0), b3, voffB);
;             PG8_BAR; PG8_WAIT_L(0); PG8_MMA(0, 1, At, B1); PG8_BAR;
	v_mfma_f32_16x16x32_bf16 v[60:63], v[144:147], v[168:171], v[60:63]
	v_mfma_f32_16x16x32_bf16 v[56:59], v[160:163], v[168:171], v[56:59]
	v_mfma_f32_16x16x32_bf16 v[44:47], v[144:147], v[176:179], v[44:47]
	v_mfma_f32_16x16x32_bf16 v[40:43], v[160:163], v[176:179], v[40:43]
	v_mfma_f32_16x16x32_bf16 v[28:31], v[144:147], v[184:187], v[28:31]
	v_mfma_f32_16x16x32_bf16 v[24:27], v[160:163], v[184:187], v[24:27]
	v_mfma_f32_16x16x32_bf16 v[12:15], v[144:147], v[192:195], v[12:15]
	v_mfma_f32_16x16x32_bf16 v[8:11], v[160:163], v[192:195], v[8:11]
	v_mfma_f32_16x16x32_bf16 v[60:63], v[156:159], v[172:175], v[60:63]
	v_mfma_f32_16x16x32_bf16 v[56:59], v[164:167], v[172:175], v[56:59]
	v_mfma_f32_16x16x32_bf16 v[44:47], v[156:159], v[180:183], v[44:47]
	v_mfma_f32_16x16x32_bf16 v[40:43], v[164:167], v[180:183], v[40:43]
	v_mfma_f32_16x16x32_bf16 v[28:31], v[156:159], v[188:191], v[28:31]
	v_mfma_f32_16x16x32_bf16 v[24:27], v[164:167], v[188:191], v[24:27]
	v_mfma_f32_16x16x32_bf16 v[12:15], v[156:159], v[196:199], v[12:15]
	v_mfma_f32_16x16x32_bf16 v[8:11], v[164:167], v[196:199], v[8:11]
	v_mfma_f32_16x16x32_bf16 v[52:55], v[200:203], v[168:171], v[52:55]
	v_mfma_f32_16x16x32_bf16 v[48:51], v[208:211], v[168:171], v[48:51]
	v_mfma_f32_16x16x32_bf16 v[36:39], v[200:203], v[176:179], v[36:39]
	v_mfma_f32_16x16x32_bf16 v[32:35], v[208:211], v[176:179], v[32:35]
	v_mfma_f32_16x16x32_bf16 v[20:23], v[200:203], v[184:187], v[20:23]
	v_mfma_f32_16x16x32_bf16 v[16:19], v[208:211], v[184:187], v[16:19]
	v_mfma_f32_16x16x32_bf16 v[4:7], v[200:203], v[192:195], v[4:7]
	v_mfma_f32_16x16x32_bf16 v[0:3], v[208:211], v[192:195], v[0:3]
	v_mfma_f32_16x16x32_bf16 v[52:55], v[204:207], v[172:175], v[52:55]
	v_mfma_f32_16x16x32_bf16 v[48:51], v[212:215], v[172:175], v[48:51]
	v_mfma_f32_16x16x32_bf16 v[36:39], v[204:207], v[180:183], v[36:39]
	v_mfma_f32_16x16x32_bf16 v[32:35], v[212:215], v[180:183], v[32:35]
	v_mfma_f32_16x16x32_bf16 v[20:23], v[204:207], v[188:191], v[20:23]
	v_mfma_f32_16x16x32_bf16 v[16:19], v[212:215], v[188:191], v[16:19]
	v_mfma_f32_16x16x32_bf16 v[4:7], v[204:207], v[196:199], v[4:7]
	v_mfma_f32_16x16x32_bf16 v[0:3], v[212:215], v[196:199], v[0:3]
	s_barrier
	s_add_i32 s68, 0, 0x18000
	v_add_u32_e32 v164, s68, v151
	ds_read_b128 v[144:147], v164
	ds_read_b128 v[156:159], v164 offset:1024
	ds_read_b128 v[160:163], v164 offset:2048
	ds_read_b128 v[164:167], v164 offset:3072
	s_add_u32 s24, s30, 0x158000
	s_addc_u32 s25, s31, 0
	s_mov_b32 m0, s53
	v_lshl_add_u64 v[200:201], s[24:25], 0, v[130:131]
	ds_read_b128 v[168:171], v154 offset:32768
	ds_read_b128 v[172:175], v154 offset:33792
	ds_read_b128 v[176:179], v154 offset:34816
	ds_read_b128 v[180:183], v154 offset:35840
	ds_read_b128 v[184:187], v154 offset:36864
	ds_read_b128 v[188:191], v154 offset:37888
	ds_read_b128 v[192:195], v154 offset:38912
	ds_read_b128 v[196:199], v154 offset:39936
	global_load_lds_dwordx4 v[200:201], off
	v_lshl_add_u64 v[200:201], s[24:25], 0, v[134:135]
	s_mov_b32 m0, s54
	s_nop 0
	global_load_lds_dwordx4 v[200:201], off
	s_add_i32 s30, 0, 0x1c000
	s_add_u32 s24, s28, 0x8000
	s_addc_u32 s25, s29, 0
	s_add_i32 s31, s68, s50
	v_add_u32_e32 v212, s30, v151
	v_lshl_add_u64 v[218:219], s[24:25], 0, v[128:129]
	s_mov_b32 m0, s31
	ds_read_b128 v[200:203], v212
	ds_read_b128 v[204:207], v212 offset:1024
	ds_read_b128 v[208:211], v212 offset:2048
	ds_read_b128 v[212:215], v212 offset:3072
	s_waitcnt vmcnt(8)
	s_waitcnt lgkmcnt(0)
	s_barrier
	v_mfma_f32_16x16x32_bf16 v[124:127], v[144:147], v[168:171], v[124:127]
	v_mfma_f32_16x16x32_bf16 v[120:123], v[160:163], v[168:171], v[120:123]
	v_mfma_f32_16x16x32_bf16 v[108:111], v[144:147], v[176:179], v[108:111]
	v_mfma_f32_16x16x32_bf16 v[104:107], v[160:163], v[176:179], v[104:107]
	v_mfma_f32_16x16x32_bf16 v[92:95], v[144:147], v[184:187], v[92:95]
	v_mfma_f32_16x16x32_bf16 v[88:91], v[160:163], v[184:187], v[88:91]
	v_mfma_f32_16x16x32_bf16 v[76:79], v[144:147], v[192:195], v[76:79]
	v_mfma_f32_16x16x32_bf16 v[72:75], v[160:163], v[192:195], v[72:75]
	v_mfma_f32_16x16x32_bf16 v[124:127], v[156:159], v[172:175], v[124:127]
	v_mfma_f32_16x16x32_bf16 v[120:123], v[164:167], v[172:175], v[120:123]
	v_mfma_f32_16x16x32_bf16 v[108:111], v[156:159], v[180:183], v[108:111]
	v_mfma_f32_16x16x32_bf16 v[104:107], v[164:167], v[180:183], v[104:107]
	v_mfma_f32_16x16x32_bf16 v[92:95], v[156:159], v[188:191], v[92:95]
	v_mfma_f32_16x16x32_bf16 v[88:91], v[164:167], v[188:191], v[88:91]
	v_mfma_f32_16x16x32_bf16 v[76:79], v[156:159], v[196:199], v[76:79]
	v_mfma_f32_16x16x32_bf16 v[72:75], v[164:167], v[196:199], v[72:75]
	v_mfma_f32_16x16x32_bf16 v[116:119], v[200:203], v[168:171], v[116:119]
	v_mfma_f32_16x16x32_bf16 v[112:115], v[208:211], v[168:171], v[112:115]
	v_mfma_f32_16x16x32_bf16 v[100:103], v[200:203], v[176:179], v[100:103]
	v_mfma_f32_16x16x32_bf16 v[96:99], v[208:211], v[176:179], v[96:99]
	v_mfma_f32_16x16x32_bf16 v[84:87], v[200:203], v[184:187], v[84:87]
	v_mfma_f32_16x16x32_bf16 v[80:83], v[208:211], v[184:187], v[80:83]
	v_mfma_f32_16x16x32_bf16 v[68:71], v[200:203], v[192:195], v[68:71]
	v_mfma_f32_16x16x32_bf16 v[64:67], v[208:211], v[192:195], v[64:67]
	v_mfma_f32_16x16x32_bf16 v[116:119], v[204:207], v[172:175], v[116:119]
	v_mfma_f32_16x16x32_bf16 v[112:115], v[212:215], v[172:175], v[112:115]
	v_mfma_f32_16x16x32_bf16 v[100:103], v[204:207], v[180:183], v[100:103]
	v_mfma_f32_16x16x32_bf16 v[96:99], v[212:215], v[180:183], v[96:99]
	v_mfma_f32_16x16x32_bf16 v[84:87], v[204:207], v[188:191], v[84:87]
	v_mfma_f32_16x16x32_bf16 v[80:83], v[212:215], v[188:191], v[80:83]
	v_mfma_f32_16x16x32_bf16 v[68:71], v[204:207], v[196:199], v[68:71]
	v_mfma_f32_16x16x32_bf16 v[64:67], v[212:215], v[196:199], v[64:67]
	s_barrier
; #define PG8_STAGE(bufoff, gbase, voff) do { _Pragma("unroll") for (int _i = 0; _i < 2; ++_i) \
;         __builtin_amdgcn_global_load_lds((const unsigned*)((const char*)(gbase) + (voff)[_i]), (PG8_LAS unsigned*)(lds + (bufoff) + ldsw + _i * 8192), 16, 0, 0); } while (0)
; #define PG8_LDA(dst, b, h) do { _Pragma("unroll") for (int m = 0; m < 4; ++m) _Pragma("unroll") for (int k = 0; k < 2; ++k) dst[m][k] = *(const PG8_LAS bf16x8*)(lds + PG8_SA(b, h) + aoff + m * 2048 + k * 1024); } while (0)
; #define PG8_MMA(ai, bj, At, Bt) do { __builtin_amdgcn_s_setprio(1); _Pragma("unroll") for (int m = 0; m < 4; ++m) _Pragma("unroll") for (int n = 0; n < 2; ++n) _Pragma("unroll") for (int k = 0; k < 2; ++k) \
;         acc[ai][bj][m][n] = __builtin_amdgcn_mfma_f32_16x16x32_bf16(Bt[n][k], At[m][k], acc[ai][bj][m][n], 0, 0, 0); __builtin_amdgcn_s_setprio(0); } while (0)
; #define PG8_WAIT_V(n) asm volatile("s_waitcnt vmcnt(" #n ")" ::: "memory")
; #define PG8_WAIT_L(n) asm volatile("s_waitcnt lgkmcnt(" #n ")" ::: "memory")
; #define PG8_BAR __builtin_amdgcn_s_barrier()
; #define PG8_SCHED __builtin_amdgcn_sched_barrier(0)
; template <class Epi, class Sched>
; __device__ __forceinline__ void gemm_phase(PG8_LAS unsigned char* lds, const Gemm g, const Sched& S, const Epi& E) {
;     ...
;             PG8_LDA(At, 1, 1); PG8_STAGE(PG8_SA(1, 0), a3, voffA);
;             PG8_BAR; PG8_WAIT_L(0); PG8_MMA(1, 0, At, B0); PG8_BAR; PG8_SCHED;
;             PG8_STAGE(PG8_SB(1, 1), b3 + hstepB, voffB);
;             PG8_WAIT_V(6); PG8_BAR; PG8_MMA(1, 1, At, B1); PG8_BAR;
	global_load_lds_dwordx4 v[218:219], off
	v_lshl_add_u64 v[218:219], s[24:25], 0, v[132:133]
	s_add_i32 m0, s31, 0x2000
	s_nop 0
	global_load_lds_dwordx4 v[218:219], off
	s_mov_b32 m0, s56
	v_lshl_add_u64 v[148:149], v[148:149], 0, s[14:15]
	ds_read_b128 v[168:171], v154 offset:49152
	ds_read_b128 v[172:175], v154 offset:50176
	ds_read_b128 v[176:179], v154 offset:51200
	ds_read_b128 v[180:183], v154 offset:52224
	ds_read_b128 v[184:187], v154 offset:53248
	ds_read_b128 v[188:191], v154 offset:54272
	ds_read_b128 v[192:195], v154 offset:55296
	ds_read_b128 v[196:199], v154 offset:56320
	global_load_lds_dwordx4 v[148:149], off
	v_lshl_add_u64 v[148:149], v[216:217], 0, s[14:15]
	s_mov_b32 m0, s57
	s_nop 0
	global_load_lds_dwordx4 v[148:149], off
	s_add_u32 s24, s28, 0xc000
	s_addc_u32 s25, s29, 0
	s_add_i32 s28, s30, s50
	v_lshl_add_u64 v[252:253], s[24:25], 0, v[128:129]
	s_mov_b32 m0, s28
	s_nop 0
	global_load_lds_dwordx4 v[252:253], off
	v_lshl_add_u64 v[252:253], s[24:25], 0, v[132:133]
	s_add_i32 m0, s28, 0x2000
	s_nop 0
	global_load_lds_dwordx4 v[252:253], off
	s_add_i32 s67, s67, 2
	s_add_u32 s65, s65, 0x10000
	s_addc_u32 s66, s66, 0
	s_cmpk_gt_u32 s67, 0x53
	s_mov_b64 s[24:25], s[26:27]
	s_waitcnt vmcnt(8)
	s_waitcnt lgkmcnt(0)
	s_barrier
	v_mfma_f32_16x16x32_bf16 v[60:63], v[144:147], v[168:171], v[60:63]
	v_mfma_f32_16x16x32_bf16 v[56:59], v[160:163], v[168:171], v[56:59]
	v_mfma_f32_16x16x32_bf16 v[44:47], v[144:147], v[176:179], v[44:47]
	v_mfma_f32_16x16x32_bf16 v[40:43], v[160:163], v[176:179], v[40:43]
	v_mfma_f32_16x16x32_bf16 v[28:31], v[144:147], v[184:187], v[28:31]
	v_mfma_f32_16x16x32_bf16 v[24:27], v[160:163], v[184:187], v[24:27]
	v_mfma_f32_16x16x32_bf16 v[12:15], v[144:147], v[192:195], v[12:15]
	v_mfma_f32_16x16x32_bf16 v[8:11], v[160:163], v[192:195], v[8:11]
	v_mfma_f32_16x16x32_bf16 v[60:63], v[156:159], v[172:175], v[60:63]
	v_mfma_f32_16x16x32_bf16 v[56:59], v[164:167], v[172:175], v[56:59]
	v_mfma_f32_16x16x32_bf16 v[44:47], v[156:159], v[180:183], v[44:47]
	v_mfma_f32_16x16x32_bf16 v[40:43], v[164:167], v[180:183], v[40:43]
	v_mfma_f32_16x16x32_bf16 v[28:31], v[156:159], v[188:191], v[28:31]
	v_mfma_f32_16x16x32_bf16 v[24:27], v[164:167], v[188:191], v[24:27]
	v_mfma_f32_16x16x32_bf16 v[12:15], v[156:159], v[196:199], v[12:15]
	v_mfma_f32_16x16x32_bf16 v[8:11], v[164:167], v[196:199], v[8:11]
	v_mfma_f32_16x16x32_bf16 v[52:55], v[200:203], v[168:171], v[52:55]
	v_mfma_f32_16x16x32_bf16 v[48:51], v[208:211], v[168:171], v[48:51]
	v_mfma_f32_16x16x32_bf16 v[36:39], v[200:203], v[176:179], v[36:39]
	v_mfma_f32_16x16x32_bf16 v[32:35], v[208:211], v[176:179], v[32:35]
	v_mfma_f32_16x16x32_bf16 v[20:23], v[200:203], v[184:187], v[20:23]
	v_mfma_f32_16x16x32_bf16 v[16:19], v[208:211], v[184:187], v[16:19]
	v_mfma_f32_16x16x32_bf16 v[4:7], v[200:203], v[192:195], v[4:7]
	v_mfma_f32_16x16x32_bf16 v[0:3], v[208:211], v[192:195], v[0:3]
	v_mfma_f32_16x16x32_bf16 v[52:55], v[204:207], v[172:175], v[52:55]
	v_mfma_f32_16x16x32_bf16 v[48:51], v[212:215], v[172:175], v[48:51]
	v_mfma_f32_16x16x32_bf16 v[36:39], v[204:207], v[180:183], v[36:39]
	v_mfma_f32_16x16x32_bf16 v[32:35], v[212:215], v[180:183], v[32:35]
	v_mfma_f32_16x16x32_bf16 v[20:23], v[204:207], v[188:191], v[20:23]
	v_mfma_f32_16x16x32_bf16 v[16:19], v[212:215], v[188:191], v[16:19]
	v_mfma_f32_16x16x32_bf16 v[4:7], v[204:207], v[196:199], v[4:7]
	v_mfma_f32_16x16x32_bf16 v[0:3], v[212:215], v[196:199], v[0:3]
	s_cbranch_scc1 .Lunit_exit_1
	s_barrier
	s_branch .LBB0_155

; #define PG8_STAGE(bufoff, gbase, voff) do { _Pragma("unroll") for (int _i = 0; _i < 2; ++_i) \
;         __builtin_amdgcn_global_load_lds((const unsigned*)((const char*)(gbase) + (voff)[_i]), (PG8_LAS unsigned*)(lds + (bufoff) + ldsw + _i * 8192), 16, 0, 0); } while (0)
; #define PG8_LDA(dst, b, h) do { _Pragma("unroll") for (int m = 0; m < 4; ++m) _Pragma("unroll") for (int k = 0; k < 2; ++k) dst[m][k] = *(const PG8_LAS bf16x8*)(lds + PG8_SA(b, h) + aoff + m * 2048 + k * 1024); } while (0)
; #define PG8_LDB(dst, b, h) do { _Pragma("unroll") for (int n = 0; n < 2; ++n) _Pragma("unroll") for (int k = 0; k < 2; ++k) dst[n][k] = *(const PG8_LAS bf16x8*)(lds + PG8_SB(b, h) + boff + n * 2048 + k * 1024); } while (0)
; #define PG8_MMA(ai, bj, At, Bt) do { __builtin_amdgcn_s_setprio(1); _Pragma("unroll") for (int m = 0; m < 4; ++m) _Pragma("unroll") for (int n = 0; n < 2; ++n) _Pragma("unroll") for (int k = 0; k < 2; ++k) \
;         acc[ai][bj][m][n] = __builtin_amdgcn_mfma_f32_16x16x32_bf16(Bt[n][k], At[m][k], acc[ai][bj][m][n], 0, 0, 0); __builtin_amdgcn_s_setprio(0); } while (0)
; #define PG8_WAIT_L(n) asm volatile("s_waitcnt lgkmcnt(" #n ")" ::: "memory")
; #define PG8_BAR __builtin_amdgcn_s_barrier()
; #define PG8_SCHED __builtin_amdgcn_sched_barrier(0)
; template <class Epi, class Sched>
; __device__ __forceinline__ void gemm_phase(PG8_LAS unsigned char* lds, const Gemm g, const Sched& S, const Epi& E) {
;     ...
;         for (int t = 0; t < nt; t += 2) {
;             const bool last = (t == nt - 2);
;             const char* a1 = cA + (size_t)(t + 1) * kstep;
;             const char* a2 = last ? nA : cA + (size_t)(t + 2) * kstep; const char* b2 = last ? nB : cB + (size_t)(t + 2) * kstepB;
;             const char* a3 = a2 + kstep; const char* b3 = b2 + kstepB;
;             if (last && has_next) S.a_ready(nxt);
;             PG8_LDB(B0, 0, 0); PG8_SCHED; PG8_LDA(At, 0, 0); PG8_STAGE(PG8_SA(1, 1), a1 + hstep, voffA);
;             PG8_WAIT_L(8); PG8_BAR; PG8_WAIT_L(0); PG8_MMA(0, 0, At, B0); PG8_BAR; PG8_SCHED;
;             PG8_LDB(B1, 0, 1); PG8_STAGE(PG8_SB(0, 0), b2, voffB);
;             PG8_BAR; PG8_WAIT_L(0); PG8_MMA(0, 1, At, B1); PG8_BAR;
;             PG8_LDA(At, 0, 1); PG8_STAGE(PG8_SA(0, 0), a2, voffA);
;             PG8_BAR; PG8_WAIT_L(0); PG8_MMA(1, 0, At, B0); PG8_BAR; PG8_SCHED;
;             PG8_STAGE(PG8_SB(0, 1), b2 + hstepB, voffB);
.Lhalf_skip_y_2:
.LBB0_280:
	ds_read_b128 v[150:153], v147
	ds_read_b128 v[154:157], v147 offset:1024
	ds_read_b128 v[158:161], v147 offset:2048
	ds_read_b128 v[162:165], v147 offset:3072
	s_add_u32 s48, s6, 0xfff80080
	s_addc_u32 s49, s7, -1
	s_cmp_eq_u32 s69, 28
	s_cselect_b32 s51, s9, s49
	s_cselect_b32 s50, s29, s48
	s_cselect_b32 s49, s31, s68
	s_cselect_b32 s48, s47, s67
	v_lshl_add_u64 v[198:199], s[6:7], 0, v[136:137]
	s_add_i32 m0, s54, 0xc000
	ds_read_b128 v[166:169], v148
	ds_read_b128 v[170:173], v148 offset:1024
	ds_read_b128 v[174:177], v148 offset:2048
	ds_read_b128 v[178:181], v148 offset:3072
	ds_read_b128 v[182:185], v148 offset:4096
	ds_read_b128 v[186:189], v148 offset:5120
	ds_read_b128 v[190:193], v148 offset:6144
	ds_read_b128 v[194:197], v148 offset:7168
	global_load_lds_dwordx4 v[198:199], off
	v_lshl_add_u64 v[198:199], s[6:7], 0, v[138:139]
	s_add_i32 m0, s54, 0xe000
	s_nop 0
	global_load_lds_dwordx4 v[198:199], off
	s_add_i32 s70, s63, s53
	v_lshl_add_u64 v[214:215], s[48:49], 0, v[128:129]
	s_mov_b32 m0, s70
	ds_read_b128 v[198:201], v149
	ds_read_b128 v[202:205], v149 offset:1024
	ds_read_b128 v[206:209], v149 offset:2048
	ds_read_b128 v[210:213], v149 offset:3072
	s_waitcnt vmcnt(8)
	s_waitcnt lgkmcnt(0)
	s_barrier
	v_mfma_f32_16x16x32_bf16 v[124:127], v[150:153], v[166:169], v[124:127]
	v_mfma_f32_16x16x32_bf16 v[120:123], v[158:161], v[166:169], v[120:123]
	v_mfma_f32_16x16x32_bf16 v[108:111], v[150:153], v[174:177], v[108:111]
	v_mfma_f32_16x16x32_bf16 v[104:107], v[158:161], v[174:177], v[104:107]
	v_mfma_f32_16x16x32_bf16 v[92:95], v[150:153], v[182:185], v[92:95]
	v_mfma_f32_16x16x32_bf16 v[88:91], v[158:161], v[182:185], v[88:91]
	v_mfma_f32_16x16x32_bf16 v[76:79], v[150:153], v[190:193], v[76:79]
	v_mfma_f32_16x16x32_bf16 v[72:75], v[158:161], v[190:193], v[72:75]
	v_mfma_f32_16x16x32_bf16 v[124:127], v[154:157], v[170:173], v[124:127]
	v_mfma_f32_16x16x32_bf16 v[120:123], v[162:165], v[170:173], v[120:123]
	v_mfma_f32_16x16x32_bf16 v[108:111], v[154:157], v[178:181], v[108:111]
	v_mfma_f32_16x16x32_bf16 v[104:107], v[162:165], v[178:181], v[104:107]
	v_mfma_f32_16x16x32_bf16 v[92:95], v[154:157], v[186:189], v[92:95]
	v_mfma_f32_16x16x32_bf16 v[88:91], v[162:165], v[186:189], v[88:91]
	v_mfma_f32_16x16x32_bf16 v[76:79], v[154:157], v[194:197], v[76:79]
	v_mfma_f32_16x16x32_bf16 v[72:75], v[162:165], v[194:197], v[72:75]
	v_mfma_f32_16x16x32_bf16 v[116:119], v[198:201], v[166:169], v[116:119]
	v_mfma_f32_16x16x32_bf16 v[112:115], v[206:209], v[166:169], v[112:115]
	v_mfma_f32_16x16x32_bf16 v[100:103], v[198:201], v[174:177], v[100:103]
	v_mfma_f32_16x16x32_bf16 v[96:99], v[206:209], v[174:177], v[96:99]
	v_mfma_f32_16x16x32_bf16 v[84:87], v[198:201], v[182:185], v[84:87]
	v_mfma_f32_16x16x32_bf16 v[80:83], v[206:209], v[182:185], v[80:83]
	v_mfma_f32_16x16x32_bf16 v[68:71], v[198:201], v[190:193], v[68:71]
	v_mfma_f32_16x16x32_bf16 v[64:67], v[206:209], v[190:193], v[64:67]
	v_mfma_f32_16x16x32_bf16 v[116:119], v[202:205], v[170:173], v[116:119]
	v_mfma_f32_16x16x32_bf16 v[112:115], v[210:213], v[170:173], v[112:115]
	v_mfma_f32_16x16x32_bf16 v[100:103], v[202:205], v[178:181], v[100:103]
	v_mfma_f32_16x16x32_bf16 v[96:99], v[210:213], v[178:181], v[96:99]
	v_mfma_f32_16x16x32_bf16 v[84:87], v[202:205], v[186:189], v[84:87]
	v_mfma_f32_16x16x32_bf16 v[80:83], v[210:213], v[186:189], v[80:83]
	v_mfma_f32_16x16x32_bf16 v[68:71], v[202:205], v[194:197], v[68:71]
	v_mfma_f32_16x16x32_bf16 v[64:67], v[210:213], v[194:197], v[64:67]
	s_barrier
	global_load_lds_dwordx4 v[214:215], off
	v_lshl_add_u64 v[214:215], s[48:49], 0, v[132:133]
	s_add_i32 m0, s70, 0x2000
	s_nop 0
	global_load_lds_dwordx4 v[214:215], off
	s_mov_b32 m0, s54
	v_lshl_add_u64 v[214:215], s[50:51], 0, v[130:131]
	ds_read_b128 v[166:169], v148 offset:16384
	ds_read_b128 v[170:173], v148 offset:17408
	ds_read_b128 v[174:177], v148 offset:18432
	ds_read_b128 v[178:181], v148 offset:19456
	ds_read_b128 v[182:185], v148 offset:20480
	ds_read_b128 v[186:189], v148 offset:21504
	ds_read_b128 v[190:193], v148 offset:22528
	ds_read_b128 v[194:197], v148 offset:23552
	global_load_lds_dwordx4 v[214:215], off
	v_lshl_add_u64 v[216:217], s[50:51], 0, v[134:135]
	s_mov_b32 m0, s55
	s_nop 0
	global_load_lds_dwordx4 v[216:217], off
	s_add_u32 s70, s48, 0x4000
	s_addc_u32 s71, s49, 0
	s_add_i32 s72, s64, s53
	v_lshl_add_u64 v[250:251], s[70:71], 0, v[128:129]
	s_mov_b32 m0, s72
	s_nop 0
	global_load_lds_dwordx4 v[250:251], off
	v_lshl_add_u64 v[250:251], s[70:71], 0, v[132:133]
	s_add_i32 m0, s72, 0x2000
	s_nop 0
	global_load_lds_dwordx4 v[250:251], off
	s_waitcnt vmcnt(8)
	s_waitcnt lgkmcnt(0)
	s_barrier
; #define PG8_STAGE(bufoff, gbase, voff) do { _Pragma("unroll") for (int _i = 0; _i < 2; ++_i) \
;         __builtin_amdgcn_global_load_lds((const unsigned*)((const char*)(gbase) + (voff)[_i]), (PG8_LAS unsigned*)(lds + (bufoff) + ldsw + _i * 8192), 16, 0, 0); } while (0)
; #define PG8_LDA(dst, b, h) do { _Pragma("unroll") for (int m = 0; m < 4; ++m) _Pragma("unroll") for (int k = 0; k < 2; ++k) dst[m][k] = *(const PG8_LAS bf16x8*)(lds + PG8_SA(b, h) + aoff + m * 2048 + k * 1024); } while (0)
; #define PG8_LDB(dst, b, h) do { _Pragma("unroll") for (int n = 0; n < 2; ++n) _Pragma("unroll") for (int k = 0; k < 2; ++k) dst[n][k] = *(const PG8_LAS bf16x8*)(lds + PG8_SB(b, h) + boff + n * 2048 + k * 1024); } while (0)
; #define PG8_MMA(ai, bj, At, Bt) do { __builtin_amdgcn_s_setprio(1); _Pragma("unroll") for (int m = 0; m < 4; ++m) _Pragma("unroll") for (int n = 0; n < 2; ++n) _Pragma("unroll") for (int k = 0; k < 2; ++k) \
;         acc[ai][bj][m][n] = __builtin_amdgcn_mfma_f32_16x16x32_bf16(Bt[n][k], At[m][k], acc[ai][bj][m][n], 0, 0, 0); __builtin_amdgcn_s_setprio(0); } while (0)
; #define PG8_WAIT_V(n) asm volatile("s_waitcnt vmcnt(" #n ")" ::: "memory")
; #define PG8_WAIT_L(n) asm volatile("s_waitcnt lgkmcnt(" #n ")" ::: "memory")
; #define PG8_BAR __builtin_amdgcn_s_barrier()
; #define PG8_SCHED __builtin_amdgcn_sched_barrier(0)
; template <class Epi, class Sched>
; __device__ __forceinline__ void gemm_phase(PG8_LAS unsigned char* lds, const Gemm g, const Sched& S, const Epi& E) {
;     ...
;             PG8_WAIT_V(6); PG8_BAR; PG8_MMA(1, 1, At, B1); PG8_BAR;
;             PG8_LDB(B0, 1, 0); PG8_SCHED; PG8_LDA(At, 1, 0); PG8_STAGE(PG8_SA(0, 1), a2 + hstep, voffA);
;             PG8_WAIT_L(8); PG8_BAR; PG8_WAIT_L(0); PG8_MMA(0, 0, At, B0); PG8_BAR; PG8_SCHED;
;             PG8_LDB(B1, 1, 1); PG8_STAGE(PG8_SB(1, 0), b3, voffB);
;             PG8_BAR; PG8_WAIT_L(0); PG8_MMA(0, 1, At, B1); PG8_BAR;
	v_mfma_f32_16x16x32_bf16 v[60:63], v[150:153], v[166:169], v[60:63]
	v_mfma_f32_16x16x32_bf16 v[56:59], v[158:161], v[166:169], v[56:59]
	v_mfma_f32_16x16x32_bf16 v[44:47], v[150:153], v[174:177], v[44:47]
	v_mfma_f32_16x16x32_bf16 v[40:43], v[158:161], v[174:177], v[40:43]
	v_mfma_f32_16x16x32_bf16 v[28:31], v[150:153], v[182:185], v[28:31]
	v_mfma_f32_16x16x32_bf16 v[24:27], v[158:161], v[182:185], v[24:27]
	v_mfma_f32_16x16x32_bf16 v[12:15], v[150:153], v[190:193], v[12:15]
	v_mfma_f32_16x16x32_bf16 v[8:11], v[158:161], v[190:193], v[8:11]
	v_mfma_f32_16x16x32_bf16 v[60:63], v[154:157], v[170:173], v[60:63]
	v_mfma_f32_16x16x32_bf16 v[56:59], v[162:165], v[170:173], v[56:59]
	v_mfma_f32_16x16x32_bf16 v[44:47], v[154:157], v[178:181], v[44:47]
	v_mfma_f32_16x16x32_bf16 v[40:43], v[162:165], v[178:181], v[40:43]
	v_mfma_f32_16x16x32_bf16 v[28:31], v[154:157], v[186:189], v[28:31]
	v_mfma_f32_16x16x32_bf16 v[24:27], v[162:165], v[186:189], v[24:27]
	v_mfma_f32_16x16x32_bf16 v[12:15], v[154:157], v[194:197], v[12:15]
	v_mfma_f32_16x16x32_bf16 v[8:11], v[162:165], v[194:197], v[8:11]
	v_mfma_f32_16x16x32_bf16 v[52:55], v[198:201], v[166:169], v[52:55]
	v_mfma_f32_16x16x32_bf16 v[48:51], v[206:209], v[166:169], v[48:51]
	v_mfma_f32_16x16x32_bf16 v[36:39], v[198:201], v[174:177], v[36:39]
	v_mfma_f32_16x16x32_bf16 v[32:35], v[206:209], v[174:177], v[32:35]
	v_mfma_f32_16x16x32_bf16 v[20:23], v[198:201], v[182:185], v[20:23]
	v_mfma_f32_16x16x32_bf16 v[16:19], v[206:209], v[182:185], v[16:19]
	v_mfma_f32_16x16x32_bf16 v[4:7], v[198:201], v[190:193], v[4:7]
	v_mfma_f32_16x16x32_bf16 v[0:3], v[206:209], v[190:193], v[0:3]
	v_mfma_f32_16x16x32_bf16 v[52:55], v[202:205], v[170:173], v[52:55]
	v_mfma_f32_16x16x32_bf16 v[48:51], v[210:213], v[170:173], v[48:51]
	v_mfma_f32_16x16x32_bf16 v[36:39], v[202:205], v[178:181], v[36:39]
	v_mfma_f32_16x16x32_bf16 v[32:35], v[210:213], v[178:181], v[32:35]
	v_mfma_f32_16x16x32_bf16 v[20:23], v[202:205], v[186:189], v[20:23]
	v_mfma_f32_16x16x32_bf16 v[16:19], v[210:213], v[186:189], v[16:19]
	v_mfma_f32_16x16x32_bf16 v[4:7], v[202:205], v[194:197], v[4:7]
	v_mfma_f32_16x16x32_bf16 v[0:3], v[210:213], v[194:197], v[0:3]
	s_barrier
	s_add_i32 s70, 0, 0x18000
	v_add_u32_e32 v162, s70, v145
	ds_read_b128 v[150:153], v162
	ds_read_b128 v[154:157], v162 offset:1024
	ds_read_b128 v[158:161], v162 offset:2048
	ds_read_b128 v[162:165], v162 offset:3072
	s_add_u32 s50, s50, 0x80000
	s_addc_u32 s51, s51, 0
	s_mov_b32 m0, s56
	v_lshl_add_u64 v[198:199], s[50:51], 0, v[130:131]
	ds_read_b128 v[166:169], v148 offset:32768
	ds_read_b128 v[170:173], v148 offset:33792
	ds_read_b128 v[174:177], v148 offset:34816
	ds_read_b128 v[178:181], v148 offset:35840
	ds_read_b128 v[182:185], v148 offset:36864
	ds_read_b128 v[186:189], v148 offset:37888
	ds_read_b128 v[190:193], v148 offset:38912
	ds_read_b128 v[194:197], v148 offset:39936
	global_load_lds_dwordx4 v[198:199], off
	v_lshl_add_u64 v[198:199], s[50:51], 0, v[134:135]
	s_mov_b32 m0, s57
	s_nop 0
	global_load_lds_dwordx4 v[198:199], off
	s_add_i32 s71, 0, 0x1c000
	s_add_u32 s50, s48, 0x8000
	s_addc_u32 s51, s49, 0
	s_add_i32 s70, s70, s53
	v_add_u32_e32 v210, s71, v145
	v_lshl_add_u64 v[218:219], s[50:51], 0, v[128:129]
	s_mov_b32 m0, s70
	ds_read_b128 v[198:201], v210
	ds_read_b128 v[202:205], v210 offset:1024
	ds_read_b128 v[206:209], v210 offset:2048
	ds_read_b128 v[210:213], v210 offset:3072
	s_waitcnt vmcnt(8)
	s_waitcnt lgkmcnt(0)
	s_barrier
	v_mfma_f32_16x16x32_bf16 v[124:127], v[150:153], v[166:169], v[124:127]
	v_mfma_f32_16x16x32_bf16 v[120:123], v[158:161], v[166:169], v[120:123]
	v_mfma_f32_16x16x32_bf16 v[108:111], v[150:153], v[174:177], v[108:111]
	v_mfma_f32_16x16x32_bf16 v[104:107], v[158:161], v[174:177], v[104:107]
	v_mfma_f32_16x16x32_bf16 v[92:95], v[150:153], v[182:185], v[92:95]
	v_mfma_f32_16x16x32_bf16 v[88:91], v[158:161], v[182:185], v[88:91]
	v_mfma_f32_16x16x32_bf16 v[76:79], v[150:153], v[190:193], v[76:79]
	v_mfma_f32_16x16x32_bf16 v[72:75], v[158:161], v[190:193], v[72:75]
	v_mfma_f32_16x16x32_bf16 v[124:127], v[154:157], v[170:173], v[124:127]
	v_mfma_f32_16x16x32_bf16 v[120:123], v[162:165], v[170:173], v[120:123]
	v_mfma_f32_16x16x32_bf16 v[108:111], v[154:157], v[178:181], v[108:111]
	v_mfma_f32_16x16x32_bf16 v[104:107], v[162:165], v[178:181], v[104:107]
	v_mfma_f32_16x16x32_bf16 v[92:95], v[154:157], v[186:189], v[92:95]
	v_mfma_f32_16x16x32_bf16 v[88:91], v[162:165], v[186:189], v[88:91]
	v_mfma_f32_16x16x32_bf16 v[76:79], v[154:157], v[194:197], v[76:79]
	v_mfma_f32_16x16x32_bf16 v[72:75], v[162:165], v[194:197], v[72:75]
	v_mfma_f32_16x16x32_bf16 v[116:119], v[198:201], v[166:169], v[116:119]
	v_mfma_f32_16x16x32_bf16 v[112:115], v[206:209], v[166:169], v[112:115]
	v_mfma_f32_16x16x32_bf16 v[100:103], v[198:201], v[174:177], v[100:103]
	v_mfma_f32_16x16x32_bf16 v[96:99], v[206:209], v[174:177], v[96:99]
	v_mfma_f32_16x16x32_bf16 v[84:87], v[198:201], v[182:185], v[84:87]
	v_mfma_f32_16x16x32_bf16 v[80:83], v[206:209], v[182:185], v[80:83]
	v_mfma_f32_16x16x32_bf16 v[68:71], v[198:201], v[190:193], v[68:71]
	v_mfma_f32_16x16x32_bf16 v[64:67], v[206:209], v[190:193], v[64:67]
	v_mfma_f32_16x16x32_bf16 v[116:119], v[202:205], v[170:173], v[116:119]
	v_mfma_f32_16x16x32_bf16 v[112:115], v[210:213], v[170:173], v[112:115]
	v_mfma_f32_16x16x32_bf16 v[100:103], v[202:205], v[178:181], v[100:103]
	v_mfma_f32_16x16x32_bf16 v[96:99], v[210:213], v[178:181], v[96:99]
	v_mfma_f32_16x16x32_bf16 v[84:87], v[202:205], v[186:189], v[84:87]
	v_mfma_f32_16x16x32_bf16 v[80:83], v[210:213], v[186:189], v[80:83]
	v_mfma_f32_16x16x32_bf16 v[68:71], v[202:205], v[194:197], v[68:71]
	v_mfma_f32_16x16x32_bf16 v[64:67], v[210:213], v[194:197], v[64:67]
	s_barrier
; #define PG8_STAGE(bufoff, gbase, voff) do { _Pragma("unroll") for (int _i = 0; _i < 2; ++_i) \
;         __builtin_amdgcn_global_load_lds((const unsigned*)((const char*)(gbase) + (voff)[_i]), (PG8_LAS unsigned*)(lds + (bufoff) + ldsw + _i * 8192), 16, 0, 0); } while (0)
; #define PG8_LDA(dst, b, h) do { _Pragma("unroll") for (int m = 0; m < 4; ++m) _Pragma("unroll") for (int k = 0; k < 2; ++k) dst[m][k] = *(const PG8_LAS bf16x8*)(lds + PG8_SA(b, h) + aoff + m * 2048 + k * 1024); } while (0)
; #define PG8_MMA(ai, bj, At, Bt) do { __builtin_amdgcn_s_setprio(1); _Pragma("unroll") for (int m = 0; m < 4; ++m) _Pragma("unroll") for (int n = 0; n < 2; ++n) _Pragma("unroll") for (int k = 0; k < 2; ++k) \
;         acc[ai][bj][m][n] = __builtin_amdgcn_mfma_f32_16x16x32_bf16(Bt[n][k], At[m][k], acc[ai][bj][m][n], 0, 0, 0); __builtin_amdgcn_s_setprio(0); } while (0)
; #define PG8_WAIT_V(n) asm volatile("s_waitcnt vmcnt(" #n ")" ::: "memory")
; #define PG8_WAIT_L(n) asm volatile("s_waitcnt lgkmcnt(" #n ")" ::: "memory")
; #define PG8_BAR __builtin_amdgcn_s_barrier()
; #define PG8_SCHED __builtin_amdgcn_sched_barrier(0)
; template <class Epi, class Sched>
; __device__ __forceinline__ void gemm_phase(PG8_LAS unsigned char* lds, const Gemm g, const Sched& S, const Epi& E) {
;     ...
;             PG8_LDA(At, 1, 1); PG8_STAGE(PG8_SA(1, 0), a3, voffA);
;             PG8_BAR; PG8_WAIT_L(0); PG8_MMA(1, 0, At, B0); PG8_BAR; PG8_SCHED;
;             PG8_STAGE(PG8_SB(1, 1), b3 + hstepB, voffB);
;             PG8_WAIT_V(6); PG8_BAR; PG8_MMA(1, 1, At, B1); PG8_BAR;
	global_load_lds_dwordx4 v[218:219], off
	v_lshl_add_u64 v[218:219], s[50:51], 0, v[132:133]
	s_add_i32 m0, s70, 0x2000
	s_nop 0
	global_load_lds_dwordx4 v[218:219], off
	s_mov_b32 m0, s59
	v_lshl_add_u64 v[214:215], v[214:215], 0, s[12:13]
	ds_read_b128 v[166:169], v148 offset:49152
	ds_read_b128 v[170:173], v148 offset:50176
	ds_read_b128 v[174:177], v148 offset:51200
	ds_read_b128 v[178:181], v148 offset:52224
	ds_read_b128 v[182:185], v148 offset:53248
	ds_read_b128 v[186:189], v148 offset:54272
	ds_read_b128 v[190:193], v148 offset:55296
	ds_read_b128 v[194:197], v148 offset:56320
	global_load_lds_dwordx4 v[214:215], off
	v_lshl_add_u64 v[214:215], v[216:217], 0, s[12:13]
	s_mov_b32 m0, s60
	s_nop 0
	global_load_lds_dwordx4 v[214:215], off
	s_add_u32 s48, s48, 0xc000
	s_addc_u32 s49, s49, 0
	s_add_i32 s50, s71, s53
	v_lshl_add_u64 v[252:253], s[48:49], 0, v[128:129]
	s_mov_b32 m0, s50
	s_nop 0
	global_load_lds_dwordx4 v[252:253], off
	v_lshl_add_u64 v[252:253], s[48:49], 0, v[132:133]
	s_add_i32 m0, s50, 0x2000
	s_nop 0
	global_load_lds_dwordx4 v[252:253], off
	s_add_i32 s69, s69, 2
	s_add_u32 s67, s67, 0x10000
	s_addc_u32 s68, s68, 0
	s_add_u32 s6, s6, 0x100
	s_addc_u32 s7, s7, 0
	s_cmp_gt_u32 s69, 29
	s_waitcnt vmcnt(8)
	s_waitcnt lgkmcnt(0)
	s_barrier
	v_mfma_f32_16x16x32_bf16 v[60:63], v[150:153], v[166:169], v[60:63]
	v_mfma_f32_16x16x32_bf16 v[56:59], v[158:161], v[166:169], v[56:59]
	v_mfma_f32_16x16x32_bf16 v[44:47], v[150:153], v[174:177], v[44:47]
	v_mfma_f32_16x16x32_bf16 v[40:43], v[158:161], v[174:177], v[40:43]
	v_mfma_f32_16x16x32_bf16 v[28:31], v[150:153], v[182:185], v[28:31]
	v_mfma_f32_16x16x32_bf16 v[24:27], v[158:161], v[182:185], v[24:27]
	v_mfma_f32_16x16x32_bf16 v[12:15], v[150:153], v[190:193], v[12:15]
	v_mfma_f32_16x16x32_bf16 v[8:11], v[158:161], v[190:193], v[8:11]
	v_mfma_f32_16x16x32_bf16 v[60:63], v[154:157], v[170:173], v[60:63]
	v_mfma_f32_16x16x32_bf16 v[56:59], v[162:165], v[170:173], v[56:59]
	v_mfma_f32_16x16x32_bf16 v[44:47], v[154:157], v[178:181], v[44:47]
	v_mfma_f32_16x16x32_bf16 v[40:43], v[162:165], v[178:181], v[40:43]
	v_mfma_f32_16x16x32_bf16 v[28:31], v[154:157], v[186:189], v[28:31]
	v_mfma_f32_16x16x32_bf16 v[24:27], v[162:165], v[186:189], v[24:27]
	v_mfma_f32_16x16x32_bf16 v[12:15], v[154:157], v[194:197], v[12:15]
	v_mfma_f32_16x16x32_bf16 v[8:11], v[162:165], v[194:197], v[8:11]
	v_mfma_f32_16x16x32_bf16 v[52:55], v[198:201], v[166:169], v[52:55]
	v_mfma_f32_16x16x32_bf16 v[48:51], v[206:209], v[166:169], v[48:51]
	v_mfma_f32_16x16x32_bf16 v[36:39], v[198:201], v[174:177], v[36:39]
	v_mfma_f32_16x16x32_bf16 v[32:35], v[206:209], v[174:177], v[32:35]
	v_mfma_f32_16x16x32_bf16 v[20:23], v[198:201], v[182:185], v[20:23]
	v_mfma_f32_16x16x32_bf16 v[16:19], v[206:209], v[182:185], v[16:19]
	v_mfma_f32_16x16x32_bf16 v[4:7], v[198:201], v[190:193], v[4:7]
	v_mfma_f32_16x16x32_bf16 v[0:3], v[206:209], v[190:193], v[0:3]
	v_mfma_f32_16x16x32_bf16 v[52:55], v[202:205], v[170:173], v[52:55]
	v_mfma_f32_16x16x32_bf16 v[48:51], v[210:213], v[170:173], v[48:51]
	v_mfma_f32_16x16x32_bf16 v[36:39], v[202:205], v[178:181], v[36:39]
	v_mfma_f32_16x16x32_bf16 v[32:35], v[210:213], v[178:181], v[32:35]
	v_mfma_f32_16x16x32_bf16 v[20:23], v[202:205], v[186:189], v[20:23]
	v_mfma_f32_16x16x32_bf16 v[16:19], v[210:213], v[186:189], v[16:19]
	v_mfma_f32_16x16x32_bf16 v[4:7], v[202:205], v[194:197], v[4:7]
	v_mfma_f32_16x16x32_bf16 v[0:3], v[210:213], v[194:197], v[0:3]
	s_cbranch_scc1 .Lunit_exit_2
	s_barrier
	s_branch .LBB0_280

; #define PG8_STAGE(bufoff, gbase, voff) do { _Pragma("unroll") for (int _i = 0; _i < 2; ++_i) \
;         __builtin_amdgcn_global_load_lds((const unsigned*)((const char*)(gbase) + (voff)[_i]), (PG8_LAS unsigned*)(lds + (bufoff) + ldsw + _i * 8192), 16, 0, 0); } while (0)
; #define PG8_LDA(dst, b, h) do { _Pragma("unroll") for (int m = 0; m < 4; ++m) _Pragma("unroll") for (int k = 0; k < 2; ++k) dst[m][k] = *(const PG8_LAS bf16x8*)(lds + PG8_SA(b, h) + aoff + m * 2048 + k * 1024); } while (0)
; #define PG8_LDB(dst, b, h) do { _Pragma("unroll") for (int n = 0; n < 2; ++n) _Pragma("unroll") for (int k = 0; k < 2; ++k) dst[n][k] = *(const PG8_LAS bf16x8*)(lds + PG8_SB(b, h) + boff + n * 2048 + k * 1024); } while (0)
; #define PG8_MMA(ai, bj, At, Bt) do { __builtin_amdgcn_s_setprio(1); _Pragma("unroll") for (int m = 0; m < 4; ++m) _Pragma("unroll") for (int n = 0; n < 2; ++n) _Pragma("unroll") for (int k = 0; k < 2; ++k) \
;         acc[ai][bj][m][n] = __builtin_amdgcn_mfma_f32_16x16x32_bf16(Bt[n][k], At[m][k], acc[ai][bj][m][n], 0, 0, 0); __builtin_amdgcn_s_setprio(0); } while (0)
; #define PG8_WAIT_L(n) asm volatile("s_waitcnt lgkmcnt(" #n ")" ::: "memory")
; #define PG8_BAR __builtin_amdgcn_s_barrier()
; #define PG8_SCHED __builtin_amdgcn_sched_barrier(0)
; template <class Epi, class Sched>
; __device__ __forceinline__ void gemm_phase(PG8_LAS unsigned char* lds, const Gemm g, const Sched& S, const Epi& E) {
;     ...
;         for (int t = 0; t < nt; t += 2) {
;             const bool last = (t == nt - 2);
;             const char* a1 = cA + (size_t)(t + 1) * kstep;
;             const char* a2 = last ? nA : cA + (size_t)(t + 2) * kstep; const char* b2 = last ? nB : cB + (size_t)(t + 2) * kstepB;
;             const char* a3 = a2 + kstep; const char* b3 = b2 + kstepB;
;             if (last && has_next) S.a_ready(nxt);
;             PG8_LDB(B0, 0, 0); PG8_SCHED; PG8_LDA(At, 0, 0); PG8_STAGE(PG8_SA(1, 1), a1 + hstep, voffA);
;             PG8_WAIT_L(8); PG8_BAR; PG8_WAIT_L(0); PG8_MMA(0, 0, At, B0); PG8_BAR; PG8_SCHED;
;             PG8_LDB(B1, 0, 1); PG8_STAGE(PG8_SB(0, 0), b2, voffB);
;             PG8_BAR; PG8_WAIT_L(0); PG8_MMA(0, 1, At, B1); PG8_BAR;
;             PG8_LDA(At, 0, 1); PG8_STAGE(PG8_SA(0, 0), a2, voffA);
;             PG8_BAR; PG8_WAIT_L(0); PG8_MMA(1, 0, At, B0); PG8_BAR; PG8_SCHED;
;             PG8_STAGE(PG8_SB(0, 1), b2 + hstepB, voffB);
.Lhalf_skip_y_3:
.LBB0_397:
	ds_read_b128 v[142:145], v150
	ds_read_b128 v[154:157], v150 offset:1024
	ds_read_b128 v[158:161], v150 offset:2048
	ds_read_b128 v[162:165], v150 offset:3072
	s_add_u32 s26, s24, 0xfff80080
	s_addc_u32 s27, s25, -1
	s_cmp_eq_u32 s66, 28
	s_cselect_b32 s29, s5, s27
	s_cselect_b32 s28, s15, s26
	s_cselect_b32 s27, s17, s65
	s_cselect_b32 s26, s23, s64
	v_lshl_add_u64 v[198:199], s[24:25], 0, v[138:139]
	s_add_i32 m0, s48, 0xc000
	ds_read_b128 v[166:169], v151
	ds_read_b128 v[170:173], v151 offset:1024
	ds_read_b128 v[174:177], v151 offset:2048
	ds_read_b128 v[178:181], v151 offset:3072
	ds_read_b128 v[182:185], v151 offset:4096
	ds_read_b128 v[186:189], v151 offset:5120
	ds_read_b128 v[190:193], v151 offset:6144
	ds_read_b128 v[194:197], v151 offset:7168
	global_load_lds_dwordx4 v[198:199], off
	v_lshl_add_u64 v[198:199], s[24:25], 0, v[140:141]
	s_add_i32 m0, s48, 0xe000
	s_nop 0
	global_load_lds_dwordx4 v[198:199], off
	s_add_i32 s67, s59, s39
	v_lshl_add_u64 v[214:215], s[26:27], 0, v[128:129]
	s_mov_b32 m0, s67
	ds_read_b128 v[198:201], v152
	ds_read_b128 v[202:205], v152 offset:1024
	ds_read_b128 v[206:209], v152 offset:2048
	ds_read_b128 v[210:213], v152 offset:3072
	s_waitcnt vmcnt(8)
	s_waitcnt lgkmcnt(0)
	s_barrier
	v_mfma_f32_16x16x32_bf16 v[124:127], v[142:145], v[166:169], v[124:127]
	v_mfma_f32_16x16x32_bf16 v[120:123], v[158:161], v[166:169], v[120:123]
	v_mfma_f32_16x16x32_bf16 v[108:111], v[142:145], v[174:177], v[108:111]
	v_mfma_f32_16x16x32_bf16 v[104:107], v[158:161], v[174:177], v[104:107]
	v_mfma_f32_16x16x32_bf16 v[92:95], v[142:145], v[182:185], v[92:95]
	v_mfma_f32_16x16x32_bf16 v[88:91], v[158:161], v[182:185], v[88:91]
	v_mfma_f32_16x16x32_bf16 v[76:79], v[142:145], v[190:193], v[76:79]
	v_mfma_f32_16x16x32_bf16 v[72:75], v[158:161], v[190:193], v[72:75]
	v_mfma_f32_16x16x32_bf16 v[124:127], v[154:157], v[170:173], v[124:127]
	v_mfma_f32_16x16x32_bf16 v[120:123], v[162:165], v[170:173], v[120:123]
	v_mfma_f32_16x16x32_bf16 v[108:111], v[154:157], v[178:181], v[108:111]
	v_mfma_f32_16x16x32_bf16 v[104:107], v[162:165], v[178:181], v[104:107]
	v_mfma_f32_16x16x32_bf16 v[92:95], v[154:157], v[186:189], v[92:95]
	v_mfma_f32_16x16x32_bf16 v[88:91], v[162:165], v[186:189], v[88:91]
	v_mfma_f32_16x16x32_bf16 v[76:79], v[154:157], v[194:197], v[76:79]
	v_mfma_f32_16x16x32_bf16 v[72:75], v[162:165], v[194:197], v[72:75]
	v_mfma_f32_16x16x32_bf16 v[116:119], v[198:201], v[166:169], v[116:119]
	v_mfma_f32_16x16x32_bf16 v[112:115], v[206:209], v[166:169], v[112:115]
	v_mfma_f32_16x16x32_bf16 v[100:103], v[198:201], v[174:177], v[100:103]
	v_mfma_f32_16x16x32_bf16 v[96:99], v[206:209], v[174:177], v[96:99]
	v_mfma_f32_16x16x32_bf16 v[84:87], v[198:201], v[182:185], v[84:87]
	v_mfma_f32_16x16x32_bf16 v[80:83], v[206:209], v[182:185], v[80:83]
	v_mfma_f32_16x16x32_bf16 v[68:71], v[198:201], v[190:193], v[68:71]
	v_mfma_f32_16x16x32_bf16 v[64:67], v[206:209], v[190:193], v[64:67]
	v_mfma_f32_16x16x32_bf16 v[116:119], v[202:205], v[170:173], v[116:119]
	v_mfma_f32_16x16x32_bf16 v[112:115], v[210:213], v[170:173], v[112:115]
	v_mfma_f32_16x16x32_bf16 v[100:103], v[202:205], v[178:181], v[100:103]
	v_mfma_f32_16x16x32_bf16 v[96:99], v[210:213], v[178:181], v[96:99]
	v_mfma_f32_16x16x32_bf16 v[84:87], v[202:205], v[186:189], v[84:87]
	v_mfma_f32_16x16x32_bf16 v[80:83], v[210:213], v[186:189], v[80:83]
	v_mfma_f32_16x16x32_bf16 v[68:71], v[202:205], v[194:197], v[68:71]
	v_mfma_f32_16x16x32_bf16 v[64:67], v[210:213], v[194:197], v[64:67]
	s_barrier
	global_load_lds_dwordx4 v[214:215], off
	v_lshl_add_u64 v[214:215], s[26:27], 0, v[132:133]
	s_add_i32 m0, s67, 0x2000
	s_nop 0
	global_load_lds_dwordx4 v[214:215], off
	s_mov_b32 m0, s48
	v_lshl_add_u64 v[214:215], s[28:29], 0, v[130:131]
	ds_read_b128 v[166:169], v151 offset:16384
	ds_read_b128 v[170:173], v151 offset:17408
	ds_read_b128 v[174:177], v151 offset:18432
	ds_read_b128 v[178:181], v151 offset:19456
	ds_read_b128 v[182:185], v151 offset:20480
	ds_read_b128 v[186:189], v151 offset:21504
	ds_read_b128 v[190:193], v151 offset:22528
	ds_read_b128 v[194:197], v151 offset:23552
	global_load_lds_dwordx4 v[214:215], off
	v_lshl_add_u64 v[216:217], s[28:29], 0, v[134:135]
	s_mov_b32 m0, s49
	s_nop 0
	global_load_lds_dwordx4 v[216:217], off
	s_add_u32 s68, s26, 0x4000
	s_addc_u32 s69, s27, 0
	s_add_i32 s67, s60, s39
	v_lshl_add_u64 v[250:251], s[68:69], 0, v[128:129]
	s_mov_b32 m0, s67
	s_nop 0
	global_load_lds_dwordx4 v[250:251], off
	v_lshl_add_u64 v[250:251], s[68:69], 0, v[132:133]
	s_add_i32 m0, s67, 0x2000
	s_nop 0
	global_load_lds_dwordx4 v[250:251], off
	s_waitcnt vmcnt(8)
	s_waitcnt lgkmcnt(0)
	s_barrier
; #define PG8_STAGE(bufoff, gbase, voff) do { _Pragma("unroll") for (int _i = 0; _i < 2; ++_i) \
;         __builtin_amdgcn_global_load_lds((const unsigned*)((const char*)(gbase) + (voff)[_i]), (PG8_LAS unsigned*)(lds + (bufoff) + ldsw + _i * 8192), 16, 0, 0); } while (0)
; #define PG8_LDA(dst, b, h) do { _Pragma("unroll") for (int m = 0; m < 4; ++m) _Pragma("unroll") for (int k = 0; k < 2; ++k) dst[m][k] = *(const PG8_LAS bf16x8*)(lds + PG8_SA(b, h) + aoff + m * 2048 + k * 1024); } while (0)
; #define PG8_LDB(dst, b, h) do { _Pragma("unroll") for (int n = 0; n < 2; ++n) _Pragma("unroll") for (int k = 0; k < 2; ++k) dst[n][k] = *(const PG8_LAS bf16x8*)(lds + PG8_SB(b, h) + boff + n * 2048 + k * 1024); } while (0)
; #define PG8_MMA(ai, bj, At, Bt) do { __builtin_amdgcn_s_setprio(1); _Pragma("unroll") for (int m = 0; m < 4; ++m) _Pragma("unroll") for (int n = 0; n < 2; ++n) _Pragma("unroll") for (int k = 0; k < 2; ++k) \
;         acc[ai][bj][m][n] = __builtin_amdgcn_mfma_f32_16x16x32_bf16(Bt[n][k], At[m][k], acc[ai][bj][m][n], 0, 0, 0); __builtin_amdgcn_s_setprio(0); } while (0)
; #define PG8_WAIT_V(n) asm volatile("s_waitcnt vmcnt(" #n ")" ::: "memory")
; #define PG8_WAIT_L(n) asm volatile("s_waitcnt lgkmcnt(" #n ")" ::: "memory")
; #define PG8_BAR __builtin_amdgcn_s_barrier()
; #define PG8_SCHED __builtin_amdgcn_sched_barrier(0)
; template <class Epi, class Sched>
; __device__ __forceinline__ void gemm_phase(PG8_LAS unsigned char* lds, const Gemm g, const Sched& S, const Epi& E) {
;     ...
;             PG8_WAIT_V(6); PG8_BAR; PG8_MMA(1, 1, At, B1); PG8_BAR;
;             PG8_LDB(B0, 1, 0); PG8_SCHED; PG8_LDA(At, 1, 0); PG8_STAGE(PG8_SA(0, 1), a2 + hstep, voffA);
;             PG8_WAIT_L(8); PG8_BAR; PG8_WAIT_L(0); PG8_MMA(0, 0, At, B0); PG8_BAR; PG8_SCHED;
;             PG8_LDB(B1, 1, 1); PG8_STAGE(PG8_SB(1, 0), b3, voffB);
;             PG8_BAR; PG8_WAIT_L(0); PG8_MMA(0, 1, At, B1); PG8_BAR;
	v_mfma_f32_16x16x32_bf16 v[60:63], v[142:145], v[166:169], v[60:63]
	v_mfma_f32_16x16x32_bf16 v[56:59], v[158:161], v[166:169], v[56:59]
	v_mfma_f32_16x16x32_bf16 v[44:47], v[142:145], v[174:177], v[44:47]
	v_mfma_f32_16x16x32_bf16 v[40:43], v[158:161], v[174:177], v[40:43]
	v_mfma_f32_16x16x32_bf16 v[28:31], v[142:145], v[182:185], v[28:31]
	v_mfma_f32_16x16x32_bf16 v[24:27], v[158:161], v[182:185], v[24:27]
	v_mfma_f32_16x16x32_bf16 v[12:15], v[142:145], v[190:193], v[12:15]
	v_mfma_f32_16x16x32_bf16 v[8:11], v[158:161], v[190:193], v[8:11]
	v_mfma_f32_16x16x32_bf16 v[60:63], v[154:157], v[170:173], v[60:63]
	v_mfma_f32_16x16x32_bf16 v[56:59], v[162:165], v[170:173], v[56:59]
	v_mfma_f32_16x16x32_bf16 v[44:47], v[154:157], v[178:181], v[44:47]
	v_mfma_f32_16x16x32_bf16 v[40:43], v[162:165], v[178:181], v[40:43]
	v_mfma_f32_16x16x32_bf16 v[28:31], v[154:157], v[186:189], v[28:31]
	v_mfma_f32_16x16x32_bf16 v[24:27], v[162:165], v[186:189], v[24:27]
	v_mfma_f32_16x16x32_bf16 v[12:15], v[154:157], v[194:197], v[12:15]
	v_mfma_f32_16x16x32_bf16 v[8:11], v[162:165], v[194:197], v[8:11]
	v_mfma_f32_16x16x32_bf16 v[52:55], v[198:201], v[166:169], v[52:55]
	v_mfma_f32_16x16x32_bf16 v[48:51], v[206:209], v[166:169], v[48:51]
	v_mfma_f32_16x16x32_bf16 v[36:39], v[198:201], v[174:177], v[36:39]
	v_mfma_f32_16x16x32_bf16 v[32:35], v[206:209], v[174:177], v[32:35]
	v_mfma_f32_16x16x32_bf16 v[20:23], v[198:201], v[182:185], v[20:23]
	v_mfma_f32_16x16x32_bf16 v[16:19], v[206:209], v[182:185], v[16:19]
	v_mfma_f32_16x16x32_bf16 v[4:7], v[198:201], v[190:193], v[4:7]
	v_mfma_f32_16x16x32_bf16 v[0:3], v[206:209], v[190:193], v[0:3]
	v_mfma_f32_16x16x32_bf16 v[52:55], v[202:205], v[170:173], v[52:55]
	v_mfma_f32_16x16x32_bf16 v[48:51], v[210:213], v[170:173], v[48:51]
	v_mfma_f32_16x16x32_bf16 v[36:39], v[202:205], v[178:181], v[36:39]
	v_mfma_f32_16x16x32_bf16 v[32:35], v[210:213], v[178:181], v[32:35]
	v_mfma_f32_16x16x32_bf16 v[20:23], v[202:205], v[186:189], v[20:23]
	v_mfma_f32_16x16x32_bf16 v[16:19], v[210:213], v[186:189], v[16:19]
	v_mfma_f32_16x16x32_bf16 v[4:7], v[202:205], v[194:197], v[4:7]
	v_mfma_f32_16x16x32_bf16 v[0:3], v[210:213], v[194:197], v[0:3]
	s_barrier
	s_add_i32 s67, 0, 0x18000
	v_add_u32_e32 v136, s67, v148
	ds_read_b128 v[142:145], v136
	ds_read_b128 v[154:157], v136 offset:1024
	ds_read_b128 v[158:161], v136 offset:2048
	ds_read_b128 v[162:165], v136 offset:3072
	s_add_u32 s28, s28, 0x80000
	s_addc_u32 s29, s29, 0
	s_mov_b32 m0, s50
	v_lshl_add_u64 v[198:199], s[28:29], 0, v[130:131]
	ds_read_b128 v[166:169], v151 offset:32768
	ds_read_b128 v[170:173], v151 offset:33792
	ds_read_b128 v[174:177], v151 offset:34816
	ds_read_b128 v[178:181], v151 offset:35840
	ds_read_b128 v[182:185], v151 offset:36864
	ds_read_b128 v[186:189], v151 offset:37888
	ds_read_b128 v[190:193], v151 offset:38912
	ds_read_b128 v[194:197], v151 offset:39936
	global_load_lds_dwordx4 v[198:199], off
	v_lshl_add_u64 v[198:199], s[28:29], 0, v[134:135]
	s_mov_b32 m0, s51
	s_nop 0
	global_load_lds_dwordx4 v[198:199], off
	s_add_i32 s68, 0, 0x1c000
	s_add_u32 s28, s26, 0x8000
	s_addc_u32 s29, s27, 0
	s_add_i32 s67, s67, s39
	v_add_u32_e32 v136, s68, v148
	v_lshl_add_u64 v[218:219], s[28:29], 0, v[128:129]
	s_mov_b32 m0, s67
	ds_read_b128 v[198:201], v136
	ds_read_b128 v[202:205], v136 offset:1024
	ds_read_b128 v[206:209], v136 offset:2048
	ds_read_b128 v[210:213], v136 offset:3072
	s_waitcnt vmcnt(8)
	s_waitcnt lgkmcnt(0)
	s_barrier
	v_mfma_f32_16x16x32_bf16 v[124:127], v[142:145], v[166:169], v[124:127]
	v_mfma_f32_16x16x32_bf16 v[120:123], v[158:161], v[166:169], v[120:123]
	v_mfma_f32_16x16x32_bf16 v[108:111], v[142:145], v[174:177], v[108:111]
	v_mfma_f32_16x16x32_bf16 v[104:107], v[158:161], v[174:177], v[104:107]
	v_mfma_f32_16x16x32_bf16 v[92:95], v[142:145], v[182:185], v[92:95]
	v_mfma_f32_16x16x32_bf16 v[88:91], v[158:161], v[182:185], v[88:91]
	v_mfma_f32_16x16x32_bf16 v[76:79], v[142:145], v[190:193], v[76:79]
	v_mfma_f32_16x16x32_bf16 v[72:75], v[158:161], v[190:193], v[72:75]
	v_mfma_f32_16x16x32_bf16 v[124:127], v[154:157], v[170:173], v[124:127]
	v_mfma_f32_16x16x32_bf16 v[120:123], v[162:165], v[170:173], v[120:123]
	v_mfma_f32_16x16x32_bf16 v[108:111], v[154:157], v[178:181], v[108:111]
	v_mfma_f32_16x16x32_bf16 v[104:107], v[162:165], v[178:181], v[104:107]
	v_mfma_f32_16x16x32_bf16 v[92:95], v[154:157], v[186:189], v[92:95]
	v_mfma_f32_16x16x32_bf16 v[88:91], v[162:165], v[186:189], v[88:91]
	v_mfma_f32_16x16x32_bf16 v[76:79], v[154:157], v[194:197], v[76:79]
	v_mfma_f32_16x16x32_bf16 v[72:75], v[162:165], v[194:197], v[72:75]
	v_mfma_f32_16x16x32_bf16 v[116:119], v[198:201], v[166:169], v[116:119]
	v_mfma_f32_16x16x32_bf16 v[112:115], v[206:209], v[166:169], v[112:115]
	v_mfma_f32_16x16x32_bf16 v[100:103], v[198:201], v[174:177], v[100:103]
	v_mfma_f32_16x16x32_bf16 v[96:99], v[206:209], v[174:177], v[96:99]
	v_mfma_f32_16x16x32_bf16 v[84:87], v[198:201], v[182:185], v[84:87]
	v_mfma_f32_16x16x32_bf16 v[80:83], v[206:209], v[182:185], v[80:83]
	v_mfma_f32_16x16x32_bf16 v[68:71], v[198:201], v[190:193], v[68:71]
	v_mfma_f32_16x16x32_bf16 v[64:67], v[206:209], v[190:193], v[64:67]
	v_mfma_f32_16x16x32_bf16 v[116:119], v[202:205], v[170:173], v[116:119]
	v_mfma_f32_16x16x32_bf16 v[112:115], v[210:213], v[170:173], v[112:115]
	v_mfma_f32_16x16x32_bf16 v[100:103], v[202:205], v[178:181], v[100:103]
	v_mfma_f32_16x16x32_bf16 v[96:99], v[210:213], v[178:181], v[96:99]
	v_mfma_f32_16x16x32_bf16 v[84:87], v[202:205], v[186:189], v[84:87]
	v_mfma_f32_16x16x32_bf16 v[80:83], v[210:213], v[186:189], v[80:83]
	v_mfma_f32_16x16x32_bf16 v[68:71], v[202:205], v[194:197], v[68:71]
	v_mfma_f32_16x16x32_bf16 v[64:67], v[210:213], v[194:197], v[64:67]
	s_barrier
; #define PG8_STAGE(bufoff, gbase, voff) do { _Pragma("unroll") for (int _i = 0; _i < 2; ++_i) \
;         __builtin_amdgcn_global_load_lds((const unsigned*)((const char*)(gbase) + (voff)[_i]), (PG8_LAS unsigned*)(lds + (bufoff) + ldsw + _i * 8192), 16, 0, 0); } while (0)
; #define PG8_LDA(dst, b, h) do { _Pragma("unroll") for (int m = 0; m < 4; ++m) _Pragma("unroll") for (int k = 0; k < 2; ++k) dst[m][k] = *(const PG8_LAS bf16x8*)(lds + PG8_SA(b, h) + aoff + m * 2048 + k * 1024); } while (0)
; #define PG8_MMA(ai, bj, At, Bt) do { __builtin_amdgcn_s_setprio(1); _Pragma("unroll") for (int m = 0; m < 4; ++m) _Pragma("unroll") for (int n = 0; n < 2; ++n) _Pragma("unroll") for (int k = 0; k < 2; ++k) \
;         acc[ai][bj][m][n] = __builtin_amdgcn_mfma_f32_16x16x32_bf16(Bt[n][k], At[m][k], acc[ai][bj][m][n], 0, 0, 0); __builtin_amdgcn_s_setprio(0); } while (0)
; #define PG8_WAIT_V(n) asm volatile("s_waitcnt vmcnt(" #n ")" ::: "memory")
; #define PG8_WAIT_L(n) asm volatile("s_waitcnt lgkmcnt(" #n ")" ::: "memory")
; #define PG8_BAR __builtin_amdgcn_s_barrier()
; #define PG8_SCHED __builtin_amdgcn_sched_barrier(0)
; template <class Epi, class Sched>
; __device__ __forceinline__ void gemm_phase(PG8_LAS unsigned char* lds, const Gemm g, const Sched& S, const Epi& E) {
;     ...
;             PG8_LDA(At, 1, 1); PG8_STAGE(PG8_SA(1, 0), a3, voffA);
;             PG8_BAR; PG8_WAIT_L(0); PG8_MMA(1, 0, At, B0); PG8_BAR; PG8_SCHED;
;             PG8_STAGE(PG8_SB(1, 1), b3 + hstepB, voffB);
;             PG8_WAIT_V(6); PG8_BAR; PG8_MMA(1, 1, At, B1); PG8_BAR;
	global_load_lds_dwordx4 v[218:219], off
	v_lshl_add_u64 v[218:219], s[28:29], 0, v[132:133]
	s_add_i32 m0, s67, 0x2000
	s_nop 0
	global_load_lds_dwordx4 v[218:219], off
	s_mov_b32 m0, s55
	v_lshl_add_u64 v[214:215], v[214:215], 0, s[10:11]
	ds_read_b128 v[166:169], v151 offset:49152
	ds_read_b128 v[170:173], v151 offset:50176
	ds_read_b128 v[174:177], v151 offset:51200
	ds_read_b128 v[178:181], v151 offset:52224
	ds_read_b128 v[182:185], v151 offset:53248
	ds_read_b128 v[186:189], v151 offset:54272
	ds_read_b128 v[190:193], v151 offset:55296
	ds_read_b128 v[194:197], v151 offset:56320
	global_load_lds_dwordx4 v[214:215], off
	v_lshl_add_u64 v[214:215], v[216:217], 0, s[10:11]
	s_mov_b32 m0, s56
	s_nop 0
	global_load_lds_dwordx4 v[214:215], off
	s_add_u32 s26, s26, 0xc000
	s_addc_u32 s27, s27, 0
	s_add_i32 s28, s68, s39
	v_lshl_add_u64 v[252:253], s[26:27], 0, v[128:129]
	s_mov_b32 m0, s28
	s_nop 0
	global_load_lds_dwordx4 v[252:253], off
	v_lshl_add_u64 v[252:253], s[26:27], 0, v[132:133]
	s_add_i32 m0, s28, 0x2000
	s_nop 0
	global_load_lds_dwordx4 v[252:253], off
	s_add_i32 s66, s66, 2
	s_add_u32 s64, s64, 0x10000
	s_addc_u32 s65, s65, 0
	s_add_u32 s24, s24, 0x100
	s_addc_u32 s25, s25, 0
	s_cmp_gt_u32 s66, 29
	s_waitcnt vmcnt(8)
	s_waitcnt lgkmcnt(0)
	s_barrier
	v_mfma_f32_16x16x32_bf16 v[60:63], v[142:145], v[166:169], v[60:63]
	v_mfma_f32_16x16x32_bf16 v[56:59], v[158:161], v[166:169], v[56:59]
	v_mfma_f32_16x16x32_bf16 v[44:47], v[142:145], v[174:177], v[44:47]
	v_mfma_f32_16x16x32_bf16 v[40:43], v[158:161], v[174:177], v[40:43]
	v_mfma_f32_16x16x32_bf16 v[28:31], v[142:145], v[182:185], v[28:31]
	v_mfma_f32_16x16x32_bf16 v[24:27], v[158:161], v[182:185], v[24:27]
	v_mfma_f32_16x16x32_bf16 v[12:15], v[142:145], v[190:193], v[12:15]
	v_mfma_f32_16x16x32_bf16 v[8:11], v[158:161], v[190:193], v[8:11]
	v_mfma_f32_16x16x32_bf16 v[60:63], v[154:157], v[170:173], v[60:63]
	v_mfma_f32_16x16x32_bf16 v[56:59], v[162:165], v[170:173], v[56:59]
	v_mfma_f32_16x16x32_bf16 v[44:47], v[154:157], v[178:181], v[44:47]
	v_mfma_f32_16x16x32_bf16 v[40:43], v[162:165], v[178:181], v[40:43]
	v_mfma_f32_16x16x32_bf16 v[28:31], v[154:157], v[186:189], v[28:31]
	v_mfma_f32_16x16x32_bf16 v[24:27], v[162:165], v[186:189], v[24:27]
	v_mfma_f32_16x16x32_bf16 v[12:15], v[154:157], v[194:197], v[12:15]
	v_mfma_f32_16x16x32_bf16 v[8:11], v[162:165], v[194:197], v[8:11]
	v_mfma_f32_16x16x32_bf16 v[52:55], v[198:201], v[166:169], v[52:55]
	v_mfma_f32_16x16x32_bf16 v[48:51], v[206:209], v[166:169], v[48:51]
	v_mfma_f32_16x16x32_bf16 v[36:39], v[198:201], v[174:177], v[36:39]
	v_mfma_f32_16x16x32_bf16 v[32:35], v[206:209], v[174:177], v[32:35]
	v_mfma_f32_16x16x32_bf16 v[20:23], v[198:201], v[182:185], v[20:23]
	v_mfma_f32_16x16x32_bf16 v[16:19], v[206:209], v[182:185], v[16:19]
	v_mfma_f32_16x16x32_bf16 v[4:7], v[198:201], v[190:193], v[4:7]
	v_mfma_f32_16x16x32_bf16 v[0:3], v[206:209], v[190:193], v[0:3]
	v_mfma_f32_16x16x32_bf16 v[52:55], v[202:205], v[170:173], v[52:55]
	v_mfma_f32_16x16x32_bf16 v[48:51], v[210:213], v[170:173], v[48:51]
	v_mfma_f32_16x16x32_bf16 v[36:39], v[202:205], v[178:181], v[36:39]
	v_mfma_f32_16x16x32_bf16 v[32:35], v[210:213], v[178:181], v[32:35]
	v_mfma_f32_16x16x32_bf16 v[20:23], v[202:205], v[186:189], v[20:23]
	v_mfma_f32_16x16x32_bf16 v[16:19], v[210:213], v[186:189], v[16:19]
	v_mfma_f32_16x16x32_bf16 v[4:7], v[202:205], v[194:197], v[4:7]
	v_mfma_f32_16x16x32_bf16 v[0:3], v[210:213], v[194:197], v[0:3]
	s_cbranch_scc1 .Lunit_exit_3
	s_barrier
	s_branch .LBB0_397

; #define PG8_STAGE(bufoff, gbase, voff) do { _Pragma("unroll") for (int _i = 0; _i < 2; ++_i) \
;         __builtin_amdgcn_global_load_lds((const unsigned*)((const char*)(gbase) + (voff)[_i]), (PG8_LAS unsigned*)(lds + (bufoff) + ldsw + _i * 8192), 16, 0, 0); } while (0)
; #define PG8_LDA(dst, b, h) do { _Pragma("unroll") for (int m = 0; m < 4; ++m) _Pragma("unroll") for (int k = 0; k < 2; ++k) dst[m][k] = *(const PG8_LAS bf16x8*)(lds + PG8_SA(b, h) + aoff + m * 2048 + k * 1024); } while (0)
; #define PG8_LDB(dst, b, h) do { _Pragma("unroll") for (int n = 0; n < 2; ++n) _Pragma("unroll") for (int k = 0; k < 2; ++k) dst[n][k] = *(const PG8_LAS bf16x8*)(lds + PG8_SB(b, h) + boff + n * 2048 + k * 1024); } while (0)
; #define PG8_MMA(ai, bj, At, Bt) do { __builtin_amdgcn_s_setprio(1); _Pragma("unroll") for (int m = 0; m < 4; ++m) _Pragma("unroll") for (int n = 0; n < 2; ++n) _Pragma("unroll") for (int k = 0; k < 2; ++k) \
;         acc[ai][bj][m][n] = __builtin_amdgcn_mfma_f32_16x16x32_bf16(Bt[n][k], At[m][k], acc[ai][bj][m][n], 0, 0, 0); __builtin_amdgcn_s_setprio(0); } while (0)
; #define PG8_WAIT_L(n) asm volatile("s_waitcnt lgkmcnt(" #n ")" ::: "memory")
; #define PG8_BAR __builtin_amdgcn_s_barrier()
; #define PG8_SCHED __builtin_amdgcn_sched_barrier(0)
; template <class Epi, class Sched>
; __device__ __forceinline__ void gemm_phase(PG8_LAS unsigned char* lds, const Gemm g, const Sched& S, const Epi& E) {
;     ...
;         for (int t = 0; t < nt; t += 2) {
;             const bool last = (t == nt - 2);
;             const char* a1 = cA + (size_t)(t + 1) * kstep;
;             const char* a2 = last ? nA : cA + (size_t)(t + 2) * kstep; const char* b2 = last ? nB : cB + (size_t)(t + 2) * kstepB;
;             const char* a3 = a2 + kstep; const char* b3 = b2 + kstepB;
;             if (last && has_next) S.a_ready(nxt);
;             PG8_LDB(B0, 0, 0); PG8_SCHED; PG8_LDA(At, 0, 0); PG8_STAGE(PG8_SA(1, 1), a1 + hstep, voffA);
;             PG8_WAIT_L(8); PG8_BAR; PG8_WAIT_L(0); PG8_MMA(0, 0, At, B0); PG8_BAR; PG8_SCHED;
;             PG8_LDB(B1, 0, 1); PG8_STAGE(PG8_SB(0, 0), b2, voffB);
;             PG8_BAR; PG8_WAIT_L(0); PG8_MMA(0, 1, At, B1); PG8_BAR;
;             PG8_LDA(At, 0, 1); PG8_STAGE(PG8_SA(0, 0), a2, voffA);
;             PG8_BAR; PG8_WAIT_L(0); PG8_MMA(1, 0, At, B0); PG8_BAR; PG8_SCHED;
;             PG8_STAGE(PG8_SB(0, 1), b2 + hstepB, voffB);
.Lhalf_skip_y_4:
.LBB0_613:
	v_add_u32_e32 v1, s57, v231
	ds_read_b128 v[132:135], v1
	ds_read_b128 v[136:139], v1 offset:1024
	ds_read_b128 v[140:143], v1 offset:2048
	ds_read_b128 v[144:147], v1 offset:3072
	s_add_u32 s26, s24, 0xfffc0080
	s_addc_u32 s27, s25, -1
	s_cmp_eq_u32 s63, 12
	s_cselect_b32 s29, s7, s27
	s_cselect_b32 s28, s15, s26
	s_cselect_b32 s27, s17, s62
	s_cselect_b32 s26, s19, s61
	v_lshl_add_u64 v[2:3], s[24:25], 0, v[204:205]
	s_add_i32 m0, s49, 0xc000
	ds_read_b128 v[148:151], v233
	ds_read_b128 v[152:155], v233 offset:1024
	ds_read_b128 v[156:159], v233 offset:2048
	ds_read_b128 v[160:163], v233 offset:3072
	ds_read_b128 v[164:167], v233 offset:4096
	ds_read_b128 v[168:171], v233 offset:5120
	ds_read_b128 v[172:175], v233 offset:6144
	ds_read_b128 v[176:179], v233 offset:7168
	global_load_lds_dwordx4 v[2:3], off
	v_lshl_add_u64 v[2:3], s[24:25], 0, v[206:207]
	s_add_i32 m0, s49, 0xe000
	s_nop 0
	global_load_lds_dwordx4 v[2:3], off
	s_add_i32 s64, s57, s48
	v_add_u32_e32 v1, s58, v231
	v_lshl_add_u64 v[250:251], s[26:27], 0, v[196:197]
	s_mov_b32 m0, s64
	ds_read_b128 v[180:183], v1
	ds_read_b128 v[184:187], v1 offset:1024
	ds_read_b128 v[188:191], v1 offset:2048
	ds_read_b128 v[192:195], v1 offset:3072
	s_waitcnt vmcnt(8)
	s_waitcnt lgkmcnt(0)
	s_barrier
	v_mfma_f32_16x16x32_bf16 v[2:5], v[132:135], v[148:151], v[4:7]
	v_mfma_f32_16x16x32_bf16 v[6:9], v[140:143], v[148:151], v[8:11]
	v_mfma_f32_16x16x32_bf16 v[32:35], v[132:135], v[156:159], v[32:35]
	v_mfma_f32_16x16x32_bf16 v[28:31], v[140:143], v[156:159], v[28:31]
	v_mfma_f32_16x16x32_bf16 v[24:27], v[132:135], v[164:167], v[24:27]
	v_mfma_f32_16x16x32_bf16 v[20:23], v[140:143], v[164:167], v[20:23]
	v_mfma_f32_16x16x32_bf16 v[16:19], v[132:135], v[172:175], v[16:19]
	v_mfma_f32_16x16x32_bf16 v[12:15], v[140:143], v[172:175], v[12:15]
	v_mfma_f32_16x16x32_bf16 v[2:5], v[136:139], v[152:155], v[2:5]
	v_mfma_f32_16x16x32_bf16 v[8:11], v[144:147], v[152:155], v[6:9]
	v_mfma_f32_16x16x32_bf16 v[32:35], v[136:139], v[160:163], v[32:35]
	v_mfma_f32_16x16x32_bf16 v[28:31], v[144:147], v[160:163], v[28:31]
	v_mfma_f32_16x16x32_bf16 v[24:27], v[136:139], v[168:171], v[24:27]
	v_mfma_f32_16x16x32_bf16 v[20:23], v[144:147], v[168:171], v[20:23]
	v_mfma_f32_16x16x32_bf16 v[16:19], v[136:139], v[176:179], v[16:19]
	v_mfma_f32_16x16x32_bf16 v[12:15], v[144:147], v[176:179], v[12:15]
	v_mfma_f32_16x16x32_bf16 v[128:131], v[180:183], v[148:151], v[128:131]
	v_mfma_f32_16x16x32_bf16 v[124:127], v[188:191], v[148:151], v[124:127]
	v_mfma_f32_16x16x32_bf16 v[120:123], v[180:183], v[156:159], v[120:123]
	v_mfma_f32_16x16x32_bf16 v[116:119], v[188:191], v[156:159], v[116:119]
	v_mfma_f32_16x16x32_bf16 v[112:115], v[180:183], v[164:167], v[112:115]
	v_mfma_f32_16x16x32_bf16 v[108:111], v[188:191], v[164:167], v[108:111]
	v_mfma_f32_16x16x32_bf16 v[104:107], v[180:183], v[172:175], v[104:107]
	v_mfma_f32_16x16x32_bf16 v[100:103], v[188:191], v[172:175], v[100:103]
	v_mfma_f32_16x16x32_bf16 v[128:131], v[184:187], v[152:155], v[128:131]
	v_mfma_f32_16x16x32_bf16 v[124:127], v[192:195], v[152:155], v[124:127]
	v_mfma_f32_16x16x32_bf16 v[120:123], v[184:187], v[160:163], v[120:123]
	v_mfma_f32_16x16x32_bf16 v[116:119], v[192:195], v[160:163], v[116:119]
	v_mfma_f32_16x16x32_bf16 v[112:115], v[184:187], v[168:171], v[112:115]
	v_mfma_f32_16x16x32_bf16 v[108:111], v[192:195], v[168:171], v[108:111]
	v_mfma_f32_16x16x32_bf16 v[104:107], v[184:187], v[176:179], v[104:107]
	v_mfma_f32_16x16x32_bf16 v[100:103], v[192:195], v[176:179], v[100:103]
	s_barrier
	global_load_lds_dwordx4 v[250:251], off
	v_lshl_add_u64 v[250:251], s[26:27], 0, v[200:201]
	s_add_i32 m0, s64, 0x2000
	s_nop 0
	global_load_lds_dwordx4 v[250:251], off
	s_mov_b32 m0, s49
	v_lshl_add_u64 v[212:213], s[28:29], 0, v[198:199]
	ds_read_b128 v[148:151], v233 offset:16384
	ds_read_b128 v[152:155], v233 offset:17408
	ds_read_b128 v[156:159], v233 offset:18432
	ds_read_b128 v[160:163], v233 offset:19456
	ds_read_b128 v[164:167], v233 offset:20480
	ds_read_b128 v[168:171], v233 offset:21504
	ds_read_b128 v[172:175], v233 offset:22528
	ds_read_b128 v[176:179], v233 offset:23552
	global_load_lds_dwordx4 v[212:213], off
	v_lshl_add_u64 v[214:215], s[28:29], 0, v[202:203]
	s_mov_b32 m0, s50
	s_nop 0
	global_load_lds_dwordx4 v[214:215], off
	s_add_u32 s64, s26, 0x4000
	s_addc_u32 s65, s27, 0
	s_add_i32 s66, s58, s48
	v_lshl_add_u64 v[6:7], s[64:65], 0, v[196:197]
	s_mov_b32 m0, s66
	s_nop 0
	global_load_lds_dwordx4 v[6:7], off
	v_lshl_add_u64 v[6:7], s[64:65], 0, v[200:201]
	s_add_i32 m0, s66, 0x2000
	s_nop 0
	global_load_lds_dwordx4 v[6:7], off
	s_waitcnt vmcnt(8)
	s_waitcnt lgkmcnt(0)
	s_barrier
; #define PG8_STAGE(bufoff, gbase, voff) do { _Pragma("unroll") for (int _i = 0; _i < 2; ++_i) \
;         __builtin_amdgcn_global_load_lds((const unsigned*)((const char*)(gbase) + (voff)[_i]), (PG8_LAS unsigned*)(lds + (bufoff) + ldsw + _i * 8192), 16, 0, 0); } while (0)
; #define PG8_LDA(dst, b, h) do { _Pragma("unroll") for (int m = 0; m < 4; ++m) _Pragma("unroll") for (int k = 0; k < 2; ++k) dst[m][k] = *(const PG8_LAS bf16x8*)(lds + PG8_SA(b, h) + aoff + m * 2048 + k * 1024); } while (0)
; #define PG8_LDB(dst, b, h) do { _Pragma("unroll") for (int n = 0; n < 2; ++n) _Pragma("unroll") for (int k = 0; k < 2; ++k) dst[n][k] = *(const PG8_LAS bf16x8*)(lds + PG8_SB(b, h) + boff + n * 2048 + k * 1024); } while (0)
; #define PG8_MMA(ai, bj, At, Bt) do { __builtin_amdgcn_s_setprio(1); _Pragma("unroll") for (int m = 0; m < 4; ++m) _Pragma("unroll") for (int n = 0; n < 2; ++n) _Pragma("unroll") for (int k = 0; k < 2; ++k) \
;         acc[ai][bj][m][n] = __builtin_amdgcn_mfma_f32_16x16x32_bf16(Bt[n][k], At[m][k], acc[ai][bj][m][n], 0, 0, 0); __builtin_amdgcn_s_setprio(0); } while (0)
; #define PG8_WAIT_V(n) asm volatile("s_waitcnt vmcnt(" #n ")" ::: "memory")
; #define PG8_WAIT_L(n) asm volatile("s_waitcnt lgkmcnt(" #n ")" ::: "memory")
; #define PG8_BAR __builtin_amdgcn_s_barrier()
; #define PG8_SCHED __builtin_amdgcn_sched_barrier(0)
; template <class Epi, class Sched>
; __device__ __forceinline__ void gemm_phase(PG8_LAS unsigned char* lds, const Gemm g, const Sched& S, const Epi& E) {
;     ...
;             PG8_WAIT_V(6); PG8_BAR; PG8_MMA(1, 1, At, B1); PG8_BAR;
;             PG8_LDB(B0, 1, 0); PG8_SCHED; PG8_LDA(At, 1, 0); PG8_STAGE(PG8_SA(0, 1), a2 + hstep, voffA);
;             PG8_WAIT_L(8); PG8_BAR; PG8_WAIT_L(0); PG8_MMA(0, 0, At, B0); PG8_BAR; PG8_SCHED;
;             PG8_LDB(B1, 1, 1); PG8_STAGE(PG8_SB(1, 0), b3, voffB);
;             PG8_BAR; PG8_WAIT_L(0); PG8_MMA(0, 1, At, B1); PG8_BAR;
	v_mfma_f32_16x16x32_bf16 v[96:99], v[132:135], v[148:151], v[96:99]
	v_mfma_f32_16x16x32_bf16 v[92:95], v[140:143], v[148:151], v[92:95]
	v_mfma_f32_16x16x32_bf16 v[88:91], v[132:135], v[156:159], v[88:91]
	v_mfma_f32_16x16x32_bf16 v[84:87], v[140:143], v[156:159], v[84:87]
	v_mfma_f32_16x16x32_bf16 v[80:83], v[132:135], v[164:167], v[80:83]
	v_mfma_f32_16x16x32_bf16 v[76:79], v[140:143], v[164:167], v[76:79]
	v_mfma_f32_16x16x32_bf16 v[72:75], v[132:135], v[172:175], v[72:75]
	v_mfma_f32_16x16x32_bf16 v[68:71], v[140:143], v[172:175], v[68:71]
	v_mfma_f32_16x16x32_bf16 v[96:99], v[136:139], v[152:155], v[96:99]
	v_mfma_f32_16x16x32_bf16 v[92:95], v[144:147], v[152:155], v[92:95]
	v_mfma_f32_16x16x32_bf16 v[88:91], v[136:139], v[160:163], v[88:91]
	v_mfma_f32_16x16x32_bf16 v[84:87], v[144:147], v[160:163], v[84:87]
	v_mfma_f32_16x16x32_bf16 v[80:83], v[136:139], v[168:171], v[80:83]
	v_mfma_f32_16x16x32_bf16 v[76:79], v[144:147], v[168:171], v[76:79]
	v_mfma_f32_16x16x32_bf16 v[72:75], v[136:139], v[176:179], v[72:75]
	v_mfma_f32_16x16x32_bf16 v[68:71], v[144:147], v[176:179], v[68:71]
	v_mfma_f32_16x16x32_bf16 v[64:67], v[180:183], v[148:151], v[64:67]
	v_mfma_f32_16x16x32_bf16 v[60:63], v[188:191], v[148:151], v[60:63]
	v_mfma_f32_16x16x32_bf16 v[56:59], v[180:183], v[156:159], v[56:59]
	v_mfma_f32_16x16x32_bf16 v[52:55], v[188:191], v[156:159], v[52:55]
	v_mfma_f32_16x16x32_bf16 v[48:51], v[180:183], v[164:167], v[48:51]
	v_mfma_f32_16x16x32_bf16 v[44:47], v[188:191], v[164:167], v[44:47]
	v_mfma_f32_16x16x32_bf16 v[40:43], v[180:183], v[172:175], v[40:43]
	v_mfma_f32_16x16x32_bf16 v[36:39], v[188:191], v[172:175], v[36:39]
	v_mfma_f32_16x16x32_bf16 v[64:67], v[184:187], v[152:155], v[64:67]
	v_mfma_f32_16x16x32_bf16 v[60:63], v[192:195], v[152:155], v[60:63]
	v_mfma_f32_16x16x32_bf16 v[56:59], v[184:187], v[160:163], v[56:59]
	v_mfma_f32_16x16x32_bf16 v[52:55], v[192:195], v[160:163], v[52:55]
	v_mfma_f32_16x16x32_bf16 v[48:51], v[184:187], v[168:171], v[48:51]
	v_mfma_f32_16x16x32_bf16 v[44:47], v[192:195], v[168:171], v[44:47]
	v_mfma_f32_16x16x32_bf16 v[40:43], v[184:187], v[176:179], v[40:43]
	v_mfma_f32_16x16x32_bf16 v[36:39], v[192:195], v[176:179], v[36:39]
	s_barrier
	s_add_i32 s64, 0, 0x18000
	v_add_u32_e32 v1, s64, v231
	ds_read_b128 v[132:135], v1
	ds_read_b128 v[136:139], v1 offset:1024
	ds_read_b128 v[140:143], v1 offset:2048
	ds_read_b128 v[144:147], v1 offset:3072
	s_add_u32 s28, s28, 0x40000
	s_addc_u32 s29, s29, 0
	s_mov_b32 m0, s51
	v_lshl_add_u64 v[6:7], s[28:29], 0, v[198:199]
	ds_read_b128 v[148:151], v233 offset:32768
	ds_read_b128 v[152:155], v233 offset:33792
	ds_read_b128 v[156:159], v233 offset:34816
	ds_read_b128 v[160:163], v233 offset:35840
	ds_read_b128 v[164:167], v233 offset:36864
	ds_read_b128 v[168:171], v233 offset:37888
	ds_read_b128 v[172:175], v233 offset:38912
	ds_read_b128 v[176:179], v233 offset:39936
	global_load_lds_dwordx4 v[6:7], off
	v_lshl_add_u64 v[6:7], s[28:29], 0, v[202:203]
	s_mov_b32 m0, s52
	s_nop 0
	global_load_lds_dwordx4 v[6:7], off
	s_add_i32 s65, 0, 0x1c000
	s_add_u32 s28, s26, 0x8000
	s_addc_u32 s29, s27, 0
	s_add_i32 s64, s64, s48
	v_add_u32_e32 v1, s65, v231
	v_lshl_add_u64 v[252:253], s[28:29], 0, v[196:197]
	s_mov_b32 m0, s64
	ds_read_b128 v[180:183], v1
	ds_read_b128 v[184:187], v1 offset:1024
	ds_read_b128 v[188:191], v1 offset:2048
	ds_read_b128 v[192:195], v1 offset:3072
	s_waitcnt vmcnt(8)
	s_waitcnt lgkmcnt(0)
	s_barrier
	v_mfma_f32_16x16x32_bf16 v[2:5], v[132:135], v[148:151], v[2:5]
	v_mfma_f32_16x16x32_bf16 v[8:11], v[140:143], v[148:151], v[8:11]
	v_mfma_f32_16x16x32_bf16 v[32:35], v[132:135], v[156:159], v[32:35]
	v_mfma_f32_16x16x32_bf16 v[28:31], v[140:143], v[156:159], v[28:31]
	v_mfma_f32_16x16x32_bf16 v[24:27], v[132:135], v[164:167], v[24:27]
	v_mfma_f32_16x16x32_bf16 v[20:23], v[140:143], v[164:167], v[20:23]
	v_mfma_f32_16x16x32_bf16 v[16:19], v[132:135], v[172:175], v[16:19]
	v_mfma_f32_16x16x32_bf16 v[12:15], v[140:143], v[172:175], v[12:15]
	v_mfma_f32_16x16x32_bf16 v[4:7], v[136:139], v[152:155], v[2:5]
	v_mfma_f32_16x16x32_bf16 v[8:11], v[144:147], v[152:155], v[8:11]
	v_mfma_f32_16x16x32_bf16 v[32:35], v[136:139], v[160:163], v[32:35]
	v_mfma_f32_16x16x32_bf16 v[28:31], v[144:147], v[160:163], v[28:31]
	v_mfma_f32_16x16x32_bf16 v[24:27], v[136:139], v[168:171], v[24:27]
	v_mfma_f32_16x16x32_bf16 v[20:23], v[144:147], v[168:171], v[20:23]
	v_mfma_f32_16x16x32_bf16 v[16:19], v[136:139], v[176:179], v[16:19]
	v_mfma_f32_16x16x32_bf16 v[12:15], v[144:147], v[176:179], v[12:15]
	v_mfma_f32_16x16x32_bf16 v[128:131], v[180:183], v[148:151], v[128:131]
	v_mfma_f32_16x16x32_bf16 v[124:127], v[188:191], v[148:151], v[124:127]
	v_mfma_f32_16x16x32_bf16 v[120:123], v[180:183], v[156:159], v[120:123]
	v_mfma_f32_16x16x32_bf16 v[116:119], v[188:191], v[156:159], v[116:119]
	v_mfma_f32_16x16x32_bf16 v[112:115], v[180:183], v[164:167], v[112:115]
	v_mfma_f32_16x16x32_bf16 v[108:111], v[188:191], v[164:167], v[108:111]
	v_mfma_f32_16x16x32_bf16 v[104:107], v[180:183], v[172:175], v[104:107]
	v_mfma_f32_16x16x32_bf16 v[100:103], v[188:191], v[172:175], v[100:103]
	v_mfma_f32_16x16x32_bf16 v[128:131], v[184:187], v[152:155], v[128:131]
	v_mfma_f32_16x16x32_bf16 v[124:127], v[192:195], v[152:155], v[124:127]
	v_mfma_f32_16x16x32_bf16 v[120:123], v[184:187], v[160:163], v[120:123]
	v_mfma_f32_16x16x32_bf16 v[116:119], v[192:195], v[160:163], v[116:119]
	v_mfma_f32_16x16x32_bf16 v[112:115], v[184:187], v[168:171], v[112:115]
	v_mfma_f32_16x16x32_bf16 v[108:111], v[192:195], v[168:171], v[108:111]
	v_mfma_f32_16x16x32_bf16 v[104:107], v[184:187], v[176:179], v[104:107]
	v_mfma_f32_16x16x32_bf16 v[100:103], v[192:195], v[176:179], v[100:103]
	s_barrier
; #define PG8_STAGE(bufoff, gbase, voff) do { _Pragma("unroll") for (int _i = 0; _i < 2; ++_i) \
;         __builtin_amdgcn_global_load_lds((const unsigned*)((const char*)(gbase) + (voff)[_i]), (PG8_LAS unsigned*)(lds + (bufoff) + ldsw + _i * 8192), 16, 0, 0); } while (0)
; #define PG8_LDA(dst, b, h) do { _Pragma("unroll") for (int m = 0; m < 4; ++m) _Pragma("unroll") for (int k = 0; k < 2; ++k) dst[m][k] = *(const PG8_LAS bf16x8*)(lds + PG8_SA(b, h) + aoff + m * 2048 + k * 1024); } while (0)
; #define PG8_MMA(ai, bj, At, Bt) do { __builtin_amdgcn_s_setprio(1); _Pragma("unroll") for (int m = 0; m < 4; ++m) _Pragma("unroll") for (int n = 0; n < 2; ++n) _Pragma("unroll") for (int k = 0; k < 2; ++k) \
;         acc[ai][bj][m][n] = __builtin_amdgcn_mfma_f32_16x16x32_bf16(Bt[n][k], At[m][k], acc[ai][bj][m][n], 0, 0, 0); __builtin_amdgcn_s_setprio(0); } while (0)
; #define PG8_WAIT_V(n) asm volatile("s_waitcnt vmcnt(" #n ")" ::: "memory")
; #define PG8_WAIT_L(n) asm volatile("s_waitcnt lgkmcnt(" #n ")" ::: "memory")
; #define PG8_BAR __builtin_amdgcn_s_barrier()
; #define PG8_SCHED __builtin_amdgcn_sched_barrier(0)
; template <class Epi, class Sched>
; __device__ __forceinline__ void gemm_phase(PG8_LAS unsigned char* lds, const Gemm g, const Sched& S, const Epi& E) {
;     ...
;             PG8_LDA(At, 1, 1); PG8_STAGE(PG8_SA(1, 0), a3, voffA);
;             PG8_BAR; PG8_WAIT_L(0); PG8_MMA(1, 0, At, B0); PG8_BAR; PG8_SCHED;
;             PG8_STAGE(PG8_SB(1, 1), b3 + hstepB, voffB);
;             PG8_WAIT_V(6); PG8_BAR; PG8_MMA(1, 1, At, B1); PG8_BAR;
	global_load_lds_dwordx4 v[252:253], off
	v_lshl_add_u64 v[252:253], s[28:29], 0, v[200:201]
	s_add_i32 m0, s64, 0x2000
	s_nop 0
	global_load_lds_dwordx4 v[252:253], off
	s_mov_b32 m0, s55
	v_lshl_add_u64 v[2:3], v[212:213], 0, s[12:13]
	ds_read_b128 v[148:151], v233 offset:49152
	ds_read_b128 v[152:155], v233 offset:50176
	ds_read_b128 v[156:159], v233 offset:51200
	ds_read_b128 v[160:163], v233 offset:52224
	ds_read_b128 v[164:167], v233 offset:53248
	ds_read_b128 v[168:171], v233 offset:54272
	ds_read_b128 v[172:175], v233 offset:55296
	ds_read_b128 v[176:179], v233 offset:56320
	global_load_lds_dwordx4 v[2:3], off
	v_lshl_add_u64 v[2:3], v[214:215], 0, s[12:13]
	s_mov_b32 m0, s56
	s_nop 0
	global_load_lds_dwordx4 v[2:3], off
	s_add_u32 s26, s26, 0xc000
	s_addc_u32 s27, s27, 0
	s_add_i32 s28, s65, s48
	v_lshl_add_u64 v[2:3], s[26:27], 0, v[196:197]
	s_mov_b32 m0, s28
	s_nop 0
	global_load_lds_dwordx4 v[2:3], off
	v_lshl_add_u64 v[2:3], s[26:27], 0, v[200:201]
	s_add_i32 m0, s28, 0x2000
	s_nop 0
	global_load_lds_dwordx4 v[2:3], off
	s_add_i32 s63, s63, 2
	s_add_u32 s61, s61, 0x10000
	s_addc_u32 s62, s62, 0
	s_add_u32 s24, s24, 0x100
	s_addc_u32 s25, s25, 0
	s_cmp_gt_u32 s63, 13
	s_waitcnt vmcnt(8)
	s_waitcnt lgkmcnt(0)
	s_barrier
	v_mfma_f32_16x16x32_bf16 v[96:99], v[132:135], v[148:151], v[96:99]
	v_mfma_f32_16x16x32_bf16 v[92:95], v[140:143], v[148:151], v[92:95]
	v_mfma_f32_16x16x32_bf16 v[88:91], v[132:135], v[156:159], v[88:91]
	v_mfma_f32_16x16x32_bf16 v[84:87], v[140:143], v[156:159], v[84:87]
	v_mfma_f32_16x16x32_bf16 v[80:83], v[132:135], v[164:167], v[80:83]
	v_mfma_f32_16x16x32_bf16 v[76:79], v[140:143], v[164:167], v[76:79]
	v_mfma_f32_16x16x32_bf16 v[72:75], v[132:135], v[172:175], v[72:75]
	v_mfma_f32_16x16x32_bf16 v[68:71], v[140:143], v[172:175], v[68:71]
	v_mfma_f32_16x16x32_bf16 v[96:99], v[136:139], v[152:155], v[96:99]
	v_mfma_f32_16x16x32_bf16 v[92:95], v[144:147], v[152:155], v[92:95]
	v_mfma_f32_16x16x32_bf16 v[88:91], v[136:139], v[160:163], v[88:91]
	v_mfma_f32_16x16x32_bf16 v[84:87], v[144:147], v[160:163], v[84:87]
	v_mfma_f32_16x16x32_bf16 v[80:83], v[136:139], v[168:171], v[80:83]
	v_mfma_f32_16x16x32_bf16 v[76:79], v[144:147], v[168:171], v[76:79]
	v_mfma_f32_16x16x32_bf16 v[72:75], v[136:139], v[176:179], v[72:75]
	v_mfma_f32_16x16x32_bf16 v[68:71], v[144:147], v[176:179], v[68:71]
	v_mfma_f32_16x16x32_bf16 v[64:67], v[180:183], v[148:151], v[64:67]
	v_mfma_f32_16x16x32_bf16 v[60:63], v[188:191], v[148:151], v[60:63]
	v_mfma_f32_16x16x32_bf16 v[56:59], v[180:183], v[156:159], v[56:59]
	v_mfma_f32_16x16x32_bf16 v[52:55], v[188:191], v[156:159], v[52:55]
	v_mfma_f32_16x16x32_bf16 v[48:51], v[180:183], v[164:167], v[48:51]
	v_mfma_f32_16x16x32_bf16 v[44:47], v[188:191], v[164:167], v[44:47]
	v_mfma_f32_16x16x32_bf16 v[40:43], v[180:183], v[172:175], v[40:43]
	v_mfma_f32_16x16x32_bf16 v[36:39], v[188:191], v[172:175], v[36:39]
	v_mfma_f32_16x16x32_bf16 v[64:67], v[184:187], v[152:155], v[64:67]
	v_mfma_f32_16x16x32_bf16 v[60:63], v[192:195], v[152:155], v[60:63]
	v_mfma_f32_16x16x32_bf16 v[56:59], v[184:187], v[160:163], v[56:59]
	v_mfma_f32_16x16x32_bf16 v[52:55], v[192:195], v[160:163], v[52:55]
	v_mfma_f32_16x16x32_bf16 v[48:51], v[184:187], v[168:171], v[48:51]
	v_mfma_f32_16x16x32_bf16 v[44:47], v[192:195], v[168:171], v[44:47]
	v_mfma_f32_16x16x32_bf16 v[40:43], v[184:187], v[176:179], v[40:43]
	v_mfma_f32_16x16x32_bf16 v[36:39], v[192:195], v[176:179], v[36:39]
	s_cbranch_scc1 .Lunit_exit_4
	s_barrier
	s_branch .LBB0_613

; #define PG8_STAGE(bufoff, gbase, voff) do { _Pragma("unroll") for (int _i = 0; _i < 2; ++_i) \
;         __builtin_amdgcn_global_load_lds((const unsigned*)((const char*)(gbase) + (voff)[_i]), (PG8_LAS unsigned*)(lds + (bufoff) + ldsw + _i * 8192), 16, 0, 0); } while (0)
; #define PG8_LDA(dst, b, h) do { _Pragma("unroll") for (int m = 0; m < 4; ++m) _Pragma("unroll") for (int k = 0; k < 2; ++k) dst[m][k] = *(const PG8_LAS bf16x8*)(lds + PG8_SA(b, h) + aoff + m * 2048 + k * 1024); } while (0)
; #define PG8_LDB(dst, b, h) do { _Pragma("unroll") for (int n = 0; n < 2; ++n) _Pragma("unroll") for (int k = 0; k < 2; ++k) dst[n][k] = *(const PG8_LAS bf16x8*)(lds + PG8_SB(b, h) + boff + n * 2048 + k * 1024); } while (0)
; #define PG8_MMA(ai, bj, At, Bt) do { __builtin_amdgcn_s_setprio(1); _Pragma("unroll") for (int m = 0; m < 4; ++m) _Pragma("unroll") for (int n = 0; n < 2; ++n) _Pragma("unroll") for (int k = 0; k < 2; ++k) \
;         acc[ai][bj][m][n] = __builtin_amdgcn_mfma_f32_16x16x32_bf16(Bt[n][k], At[m][k], acc[ai][bj][m][n], 0, 0, 0); __builtin_amdgcn_s_setprio(0); } while (0)
; #define PG8_WAIT_L(n) asm volatile("s_waitcnt lgkmcnt(" #n ")" ::: "memory")
; #define PG8_BAR __builtin_amdgcn_s_barrier()
; #define PG8_SCHED __builtin_amdgcn_sched_barrier(0)
; template <class Epi, class Sched>
; __device__ __forceinline__ void gemm_phase(PG8_LAS unsigned char* lds, const Gemm g, const Sched& S, const Epi& E) {
;     ...
;         for (int t = 0; t < nt; t += 2) {
;             const bool last = (t == nt - 2);
;             const char* a1 = cA + (size_t)(t + 1) * kstep;
;             const char* a2 = last ? nA : cA + (size_t)(t + 2) * kstep; const char* b2 = last ? nB : cB + (size_t)(t + 2) * kstepB;
;             const char* a3 = a2 + kstep; const char* b3 = b2 + kstepB;
;             if (last && has_next) S.a_ready(nxt);
;             PG8_LDB(B0, 0, 0); PG8_SCHED; PG8_LDA(At, 0, 0); PG8_STAGE(PG8_SA(1, 1), a1 + hstep, voffA);
;             PG8_WAIT_L(8); PG8_BAR; PG8_WAIT_L(0); PG8_MMA(0, 0, At, B0); PG8_BAR; PG8_SCHED;
;             PG8_LDB(B1, 0, 1); PG8_STAGE(PG8_SB(0, 0), b2, voffB);
;             PG8_BAR; PG8_WAIT_L(0); PG8_MMA(0, 1, At, B1); PG8_BAR;
;             PG8_LDA(At, 0, 1); PG8_STAGE(PG8_SA(0, 0), a2, voffA);
;             PG8_BAR; PG8_WAIT_L(0); PG8_MMA(1, 0, At, B0); PG8_BAR; PG8_SCHED;
;             PG8_STAGE(PG8_SB(0, 1), b2 + hstepB, voffB);
.Lhalf_skip_y_5:
.LBB0_783:
	ds_read_b128 v[128:131], v197
	ds_read_b128 v[132:135], v197 offset:1024
	ds_read_b128 v[136:139], v197 offset:2048
	ds_read_b128 v[140:143], v197 offset:3072
	s_add_u32 s30, s28, 0x100
	s_addc_u32 s31, s29, 0
	s_cmp_eq_u32 s69, 28
	s_cselect_b32 s39, s19, s31
	s_cselect_b32 s38, s65, s30
	s_cselect_b32 s37, s21, s68
	s_cselect_b32 s36, s66, s67
	v_lshl_add_u64 v[192:193], s[28:29], 0, v[172:173]
	s_add_i32 m0, s27, 0xc000
	ds_read_b128 v[144:147], v198
	ds_read_b128 v[148:151], v198 offset:1024
	ds_read_b128 v[152:155], v198 offset:2048
	ds_read_b128 v[156:159], v198 offset:3072
	ds_read_b128 v[160:163], v198 offset:4096
	ds_read_b128 v[180:183], v198 offset:5120
	ds_read_b128 v[184:187], v198 offset:6144
	ds_read_b128 v[188:191], v198 offset:7168
	global_load_lds_dwordx4 v[192:193], off
	v_lshl_add_u64 v[192:193], s[28:29], 0, v[174:175]
	s_add_i32 m0, s27, 0xe000
	s_nop 0
	global_load_lds_dwordx4 v[192:193], off
	s_add_i32 s28, s62, s54
	v_lshl_add_u64 v[192:193], s[36:37], 0, v[164:165]
	s_mov_b32 m0, s28
	ds_read_b128 v[200:203], v199
	ds_read_b128 v[204:207], v199 offset:1024
	ds_read_b128 v[208:211], v199 offset:2048
	ds_read_b128 v[212:215], v199 offset:3072
	s_waitcnt vmcnt(8)
	s_waitcnt lgkmcnt(0)
	s_barrier
	v_mfma_f32_16x16x32_bf16 v[124:127], v[128:131], v[144:147], v[124:127]
	v_mfma_f32_16x16x32_bf16 v[120:123], v[136:139], v[144:147], v[120:123]
	v_mfma_f32_16x16x32_bf16 v[116:119], v[128:131], v[152:155], v[116:119]
	v_mfma_f32_16x16x32_bf16 v[104:107], v[136:139], v[152:155], v[104:107]
	v_mfma_f32_16x16x32_bf16 v[92:95], v[128:131], v[160:163], v[92:95]
	v_mfma_f32_16x16x32_bf16 v[88:91], v[136:139], v[160:163], v[88:91]
	v_mfma_f32_16x16x32_bf16 v[76:79], v[128:131], v[184:187], v[76:79]
	v_mfma_f32_16x16x32_bf16 v[72:75], v[136:139], v[184:187], v[72:75]
	v_mfma_f32_16x16x32_bf16 v[124:127], v[132:135], v[148:151], v[124:127]
	v_mfma_f32_16x16x32_bf16 v[120:123], v[140:143], v[148:151], v[120:123]
	v_mfma_f32_16x16x32_bf16 v[116:119], v[132:135], v[156:159], v[116:119]
	v_mfma_f32_16x16x32_bf16 v[104:107], v[140:143], v[156:159], v[104:107]
	v_mfma_f32_16x16x32_bf16 v[92:95], v[132:135], v[180:183], v[92:95]
	v_mfma_f32_16x16x32_bf16 v[88:91], v[140:143], v[180:183], v[88:91]
	v_mfma_f32_16x16x32_bf16 v[76:79], v[132:135], v[188:191], v[76:79]
	v_mfma_f32_16x16x32_bf16 v[72:75], v[140:143], v[188:191], v[72:75]
	v_mfma_f32_16x16x32_bf16 v[112:115], v[200:203], v[144:147], v[112:115]
	v_mfma_f32_16x16x32_bf16 v[108:111], v[208:211], v[144:147], v[108:111]
	v_mfma_f32_16x16x32_bf16 v[100:103], v[200:203], v[152:155], v[100:103]
	v_mfma_f32_16x16x32_bf16 v[96:99], v[208:211], v[152:155], v[96:99]
	v_mfma_f32_16x16x32_bf16 v[84:87], v[200:203], v[160:163], v[84:87]
	v_mfma_f32_16x16x32_bf16 v[80:83], v[208:211], v[160:163], v[80:83]
	v_mfma_f32_16x16x32_bf16 v[68:71], v[200:203], v[184:187], v[68:71]
	v_mfma_f32_16x16x32_bf16 v[64:67], v[208:211], v[184:187], v[64:67]
	v_mfma_f32_16x16x32_bf16 v[112:115], v[204:207], v[148:151], v[112:115]
	v_mfma_f32_16x16x32_bf16 v[108:111], v[212:215], v[148:151], v[108:111]
	v_mfma_f32_16x16x32_bf16 v[100:103], v[204:207], v[156:159], v[100:103]
	v_mfma_f32_16x16x32_bf16 v[96:99], v[212:215], v[156:159], v[96:99]
	v_mfma_f32_16x16x32_bf16 v[84:87], v[204:207], v[180:183], v[84:87]
	v_mfma_f32_16x16x32_bf16 v[80:83], v[212:215], v[180:183], v[80:83]
	v_mfma_f32_16x16x32_bf16 v[68:71], v[204:207], v[188:191], v[68:71]
	v_mfma_f32_16x16x32_bf16 v[64:67], v[212:215], v[188:191], v[64:67]
	s_barrier
	global_load_lds_dwordx4 v[192:193], off
	v_lshl_add_u64 v[192:193], s[36:37], 0, v[168:169]
	s_add_i32 m0, s28, 0x2000
	s_nop 0
	global_load_lds_dwordx4 v[192:193], off
	s_mov_b32 m0, s27
	v_lshl_add_u64 v[192:193], s[38:39], 0, v[166:167]
	ds_read_b128 v[144:147], v198 offset:16384
	ds_read_b128 v[148:151], v198 offset:17408
	ds_read_b128 v[152:155], v198 offset:18432
	ds_read_b128 v[156:159], v198 offset:19456
	ds_read_b128 v[160:163], v198 offset:20480
	ds_read_b128 v[180:183], v198 offset:21504
	ds_read_b128 v[184:187], v198 offset:22528
	ds_read_b128 v[188:191], v198 offset:23552
	global_load_lds_dwordx4 v[192:193], off
	v_lshl_add_u64 v[216:217], s[38:39], 0, v[170:171]
	s_mov_b32 m0, s55
	s_nop 0
	global_load_lds_dwordx4 v[216:217], off
	s_add_u32 s28, s36, 0x4000
	s_addc_u32 s29, s37, 0
	s_add_i32 s70, s63, s54
	v_lshl_add_u64 v[250:251], s[28:29], 0, v[164:165]
	s_mov_b32 m0, s70
	s_nop 0
	global_load_lds_dwordx4 v[250:251], off
	v_lshl_add_u64 v[250:251], s[28:29], 0, v[168:169]
	s_add_i32 m0, s70, 0x2000
	s_nop 0
	global_load_lds_dwordx4 v[250:251], off
	s_waitcnt vmcnt(8)
	s_waitcnt lgkmcnt(0)
	s_barrier
; #define PG8_STAGE(bufoff, gbase, voff) do { _Pragma("unroll") for (int _i = 0; _i < 2; ++_i) \
;         __builtin_amdgcn_global_load_lds((const unsigned*)((const char*)(gbase) + (voff)[_i]), (PG8_LAS unsigned*)(lds + (bufoff) + ldsw + _i * 8192), 16, 0, 0); } while (0)
; #define PG8_LDA(dst, b, h) do { _Pragma("unroll") for (int m = 0; m < 4; ++m) _Pragma("unroll") for (int k = 0; k < 2; ++k) dst[m][k] = *(const PG8_LAS bf16x8*)(lds + PG8_SA(b, h) + aoff + m * 2048 + k * 1024); } while (0)
; #define PG8_LDB(dst, b, h) do { _Pragma("unroll") for (int n = 0; n < 2; ++n) _Pragma("unroll") for (int k = 0; k < 2; ++k) dst[n][k] = *(const PG8_LAS bf16x8*)(lds + PG8_SB(b, h) + boff + n * 2048 + k * 1024); } while (0)
; #define PG8_MMA(ai, bj, At, Bt) do { __builtin_amdgcn_s_setprio(1); _Pragma("unroll") for (int m = 0; m < 4; ++m) _Pragma("unroll") for (int n = 0; n < 2; ++n) _Pragma("unroll") for (int k = 0; k < 2; ++k) \
;         acc[ai][bj][m][n] = __builtin_amdgcn_mfma_f32_16x16x32_bf16(Bt[n][k], At[m][k], acc[ai][bj][m][n], 0, 0, 0); __builtin_amdgcn_s_setprio(0); } while (0)
; #define PG8_WAIT_V(n) asm volatile("s_waitcnt vmcnt(" #n ")" ::: "memory")
; #define PG8_WAIT_L(n) asm volatile("s_waitcnt lgkmcnt(" #n ")" ::: "memory")
; #define PG8_BAR __builtin_amdgcn_s_barrier()
; #define PG8_SCHED __builtin_amdgcn_sched_barrier(0)
; template <class Epi, class Sched>
; __device__ __forceinline__ void gemm_phase(PG8_LAS unsigned char* lds, const Gemm g, const Sched& S, const Epi& E) {
;     ...
;             PG8_WAIT_V(6); PG8_BAR; PG8_MMA(1, 1, At, B1); PG8_BAR;
;             PG8_LDB(B0, 1, 0); PG8_SCHED; PG8_LDA(At, 1, 0); PG8_STAGE(PG8_SA(0, 1), a2 + hstep, voffA);
;             PG8_WAIT_L(8); PG8_BAR; PG8_WAIT_L(0); PG8_MMA(0, 0, At, B0); PG8_BAR; PG8_SCHED;
;             PG8_LDB(B1, 1, 1); PG8_STAGE(PG8_SB(1, 0), b3, voffB);
;             PG8_BAR; PG8_WAIT_L(0); PG8_MMA(0, 1, At, B1); PG8_BAR;
	v_mfma_f32_16x16x32_bf16 v[60:63], v[128:131], v[144:147], v[60:63]
	v_mfma_f32_16x16x32_bf16 v[56:59], v[136:139], v[144:147], v[56:59]
	v_mfma_f32_16x16x32_bf16 v[44:47], v[128:131], v[152:155], v[44:47]
	v_mfma_f32_16x16x32_bf16 v[40:43], v[136:139], v[152:155], v[40:43]
	v_mfma_f32_16x16x32_bf16 v[28:31], v[128:131], v[160:163], v[28:31]
	v_mfma_f32_16x16x32_bf16 v[24:27], v[136:139], v[160:163], v[24:27]
	v_mfma_f32_16x16x32_bf16 v[12:15], v[128:131], v[184:187], v[12:15]
	v_mfma_f32_16x16x32_bf16 v[8:11], v[136:139], v[184:187], v[8:11]
	v_mfma_f32_16x16x32_bf16 v[60:63], v[132:135], v[148:151], v[60:63]
	v_mfma_f32_16x16x32_bf16 v[56:59], v[140:143], v[148:151], v[56:59]
	v_mfma_f32_16x16x32_bf16 v[44:47], v[132:135], v[156:159], v[44:47]
	v_mfma_f32_16x16x32_bf16 v[40:43], v[140:143], v[156:159], v[40:43]
	v_mfma_f32_16x16x32_bf16 v[28:31], v[132:135], v[180:183], v[28:31]
	v_mfma_f32_16x16x32_bf16 v[24:27], v[140:143], v[180:183], v[24:27]
	v_mfma_f32_16x16x32_bf16 v[12:15], v[132:135], v[188:191], v[12:15]
	v_mfma_f32_16x16x32_bf16 v[8:11], v[140:143], v[188:191], v[8:11]
	v_mfma_f32_16x16x32_bf16 v[52:55], v[200:203], v[144:147], v[52:55]
	v_mfma_f32_16x16x32_bf16 v[48:51], v[208:211], v[144:147], v[48:51]
	v_mfma_f32_16x16x32_bf16 v[36:39], v[200:203], v[152:155], v[36:39]
	v_mfma_f32_16x16x32_bf16 v[32:35], v[208:211], v[152:155], v[32:35]
	v_mfma_f32_16x16x32_bf16 v[20:23], v[200:203], v[160:163], v[20:23]
	v_mfma_f32_16x16x32_bf16 v[16:19], v[208:211], v[160:163], v[16:19]
	v_mfma_f32_16x16x32_bf16 v[4:7], v[200:203], v[184:187], v[4:7]
	v_mfma_f32_16x16x32_bf16 v[0:3], v[208:211], v[184:187], v[0:3]
	v_mfma_f32_16x16x32_bf16 v[52:55], v[204:207], v[148:151], v[52:55]
	v_mfma_f32_16x16x32_bf16 v[48:51], v[212:215], v[148:151], v[48:51]
	v_mfma_f32_16x16x32_bf16 v[36:39], v[204:207], v[156:159], v[36:39]
	v_mfma_f32_16x16x32_bf16 v[32:35], v[212:215], v[156:159], v[32:35]
	v_mfma_f32_16x16x32_bf16 v[20:23], v[204:207], v[180:183], v[20:23]
	v_mfma_f32_16x16x32_bf16 v[16:19], v[212:215], v[180:183], v[16:19]
	v_mfma_f32_16x16x32_bf16 v[4:7], v[204:207], v[188:191], v[4:7]
	v_mfma_f32_16x16x32_bf16 v[0:3], v[212:215], v[188:191], v[0:3]
	s_barrier
	s_add_i32 s70, 0, 0x18000
	v_add_u32_e32 v140, s70, v195
	ds_read_b128 v[128:131], v140
	ds_read_b128 v[132:135], v140 offset:1024
	ds_read_b128 v[136:139], v140 offset:2048
	ds_read_b128 v[140:143], v140 offset:3072
	s_add_u32 s28, s38, 0x80000
	s_addc_u32 s29, s39, 0
	s_mov_b32 m0, s56
	v_lshl_add_u64 v[200:201], s[28:29], 0, v[166:167]
	ds_read_b128 v[144:147], v198 offset:32768
	ds_read_b128 v[148:151], v198 offset:33792
	ds_read_b128 v[152:155], v198 offset:34816
	ds_read_b128 v[156:159], v198 offset:35840
	ds_read_b128 v[160:163], v198 offset:36864
	ds_read_b128 v[180:183], v198 offset:37888
	ds_read_b128 v[184:187], v198 offset:38912
	ds_read_b128 v[188:191], v198 offset:39936
	global_load_lds_dwordx4 v[200:201], off
	v_lshl_add_u64 v[200:201], s[28:29], 0, v[170:171]
	s_mov_b32 m0, s57
	s_nop 0
	global_load_lds_dwordx4 v[200:201], off
	s_add_i32 s38, 0, 0x1c000
	s_add_u32 s28, s36, 0x8000
	s_addc_u32 s29, s37, 0
	s_add_i32 s39, s70, s54
	v_add_u32_e32 v212, s38, v195
	v_lshl_add_u64 v[218:219], s[28:29], 0, v[164:165]
	s_mov_b32 m0, s39
	ds_read_b128 v[200:203], v212
	ds_read_b128 v[204:207], v212 offset:1024
	ds_read_b128 v[208:211], v212 offset:2048
	ds_read_b128 v[212:215], v212 offset:3072
	s_waitcnt vmcnt(8)
	s_waitcnt lgkmcnt(0)
	s_barrier
	v_mfma_f32_16x16x32_bf16 v[124:127], v[128:131], v[144:147], v[124:127]
	v_mfma_f32_16x16x32_bf16 v[120:123], v[136:139], v[144:147], v[120:123]
	v_mfma_f32_16x16x32_bf16 v[116:119], v[128:131], v[152:155], v[116:119]
	v_mfma_f32_16x16x32_bf16 v[104:107], v[136:139], v[152:155], v[104:107]
	v_mfma_f32_16x16x32_bf16 v[92:95], v[128:131], v[160:163], v[92:95]
	v_mfma_f32_16x16x32_bf16 v[88:91], v[136:139], v[160:163], v[88:91]
	v_mfma_f32_16x16x32_bf16 v[76:79], v[128:131], v[184:187], v[76:79]
	v_mfma_f32_16x16x32_bf16 v[72:75], v[136:139], v[184:187], v[72:75]
	v_mfma_f32_16x16x32_bf16 v[124:127], v[132:135], v[148:151], v[124:127]
	v_mfma_f32_16x16x32_bf16 v[120:123], v[140:143], v[148:151], v[120:123]
	v_mfma_f32_16x16x32_bf16 v[116:119], v[132:135], v[156:159], v[116:119]
	v_mfma_f32_16x16x32_bf16 v[104:107], v[140:143], v[156:159], v[104:107]
	v_mfma_f32_16x16x32_bf16 v[92:95], v[132:135], v[180:183], v[92:95]
	v_mfma_f32_16x16x32_bf16 v[88:91], v[140:143], v[180:183], v[88:91]
	v_mfma_f32_16x16x32_bf16 v[76:79], v[132:135], v[188:191], v[76:79]
	v_mfma_f32_16x16x32_bf16 v[72:75], v[140:143], v[188:191], v[72:75]
	v_mfma_f32_16x16x32_bf16 v[112:115], v[200:203], v[144:147], v[112:115]
	v_mfma_f32_16x16x32_bf16 v[108:111], v[208:211], v[144:147], v[108:111]
	v_mfma_f32_16x16x32_bf16 v[100:103], v[200:203], v[152:155], v[100:103]
	v_mfma_f32_16x16x32_bf16 v[96:99], v[208:211], v[152:155], v[96:99]
	v_mfma_f32_16x16x32_bf16 v[84:87], v[200:203], v[160:163], v[84:87]
	v_mfma_f32_16x16x32_bf16 v[80:83], v[208:211], v[160:163], v[80:83]
	v_mfma_f32_16x16x32_bf16 v[68:71], v[200:203], v[184:187], v[68:71]
	v_mfma_f32_16x16x32_bf16 v[64:67], v[208:211], v[184:187], v[64:67]
	v_mfma_f32_16x16x32_bf16 v[112:115], v[204:207], v[148:151], v[112:115]
	v_mfma_f32_16x16x32_bf16 v[108:111], v[212:215], v[148:151], v[108:111]
	v_mfma_f32_16x16x32_bf16 v[100:103], v[204:207], v[156:159], v[100:103]
	v_mfma_f32_16x16x32_bf16 v[96:99], v[212:215], v[156:159], v[96:99]
	v_mfma_f32_16x16x32_bf16 v[84:87], v[204:207], v[180:183], v[84:87]
	v_mfma_f32_16x16x32_bf16 v[80:83], v[212:215], v[180:183], v[80:83]
	v_mfma_f32_16x16x32_bf16 v[68:71], v[204:207], v[188:191], v[68:71]
	v_mfma_f32_16x16x32_bf16 v[64:67], v[212:215], v[188:191], v[64:67]
	s_barrier
; #define PG8_STAGE(bufoff, gbase, voff) do { _Pragma("unroll") for (int _i = 0; _i < 2; ++_i) \
;         __builtin_amdgcn_global_load_lds((const unsigned*)((const char*)(gbase) + (voff)[_i]), (PG8_LAS unsigned*)(lds + (bufoff) + ldsw + _i * 8192), 16, 0, 0); } while (0)
; #define PG8_LDA(dst, b, h) do { _Pragma("unroll") for (int m = 0; m < 4; ++m) _Pragma("unroll") for (int k = 0; k < 2; ++k) dst[m][k] = *(const PG8_LAS bf16x8*)(lds + PG8_SA(b, h) + aoff + m * 2048 + k * 1024); } while (0)
; #define PG8_MMA(ai, bj, At, Bt) do { __builtin_amdgcn_s_setprio(1); _Pragma("unroll") for (int m = 0; m < 4; ++m) _Pragma("unroll") for (int n = 0; n < 2; ++n) _Pragma("unroll") for (int k = 0; k < 2; ++k) \
;         acc[ai][bj][m][n] = __builtin_amdgcn_mfma_f32_16x16x32_bf16(Bt[n][k], At[m][k], acc[ai][bj][m][n], 0, 0, 0); __builtin_amdgcn_s_setprio(0); } while (0)
; #define PG8_WAIT_V(n) asm volatile("s_waitcnt vmcnt(" #n ")" ::: "memory")
; #define PG8_WAIT_L(n) asm volatile("s_waitcnt lgkmcnt(" #n ")" ::: "memory")
; #define PG8_BAR __builtin_amdgcn_s_barrier()
; #define PG8_SCHED __builtin_amdgcn_sched_barrier(0)
; template <class Epi, class Sched>
; __device__ __forceinline__ void gemm_phase(PG8_LAS unsigned char* lds, const Gemm g, const Sched& S, const Epi& E) {
;     ...
;             PG8_LDA(At, 1, 1); PG8_STAGE(PG8_SA(1, 0), a3, voffA);
;             PG8_BAR; PG8_WAIT_L(0); PG8_MMA(1, 0, At, B0); PG8_BAR; PG8_SCHED;
;             PG8_STAGE(PG8_SB(1, 1), b3 + hstepB, voffB);
;             PG8_WAIT_V(6); PG8_BAR; PG8_MMA(1, 1, At, B1); PG8_BAR;
	global_load_lds_dwordx4 v[218:219], off
	v_lshl_add_u64 v[218:219], s[28:29], 0, v[168:169]
	s_add_i32 m0, s39, 0x2000
	s_nop 0
	global_load_lds_dwordx4 v[218:219], off
	s_mov_b32 m0, s59
	v_lshl_add_u64 v[192:193], v[192:193], 0, s[10:11]
	ds_read_b128 v[144:147], v198 offset:49152
	ds_read_b128 v[148:151], v198 offset:50176
	ds_read_b128 v[152:155], v198 offset:51200
	ds_read_b128 v[156:159], v198 offset:52224
	ds_read_b128 v[160:163], v198 offset:53248
	ds_read_b128 v[180:183], v198 offset:54272
	ds_read_b128 v[184:187], v198 offset:55296
	ds_read_b128 v[188:191], v198 offset:56320
	global_load_lds_dwordx4 v[192:193], off
	v_lshl_add_u64 v[192:193], v[216:217], 0, s[10:11]
	s_mov_b32 m0, s60
	s_nop 0
	global_load_lds_dwordx4 v[192:193], off
	s_add_u32 s28, s36, 0xc000
	s_addc_u32 s29, s37, 0
	s_add_i32 s36, s38, s54
	v_lshl_add_u64 v[252:253], s[28:29], 0, v[164:165]
	s_mov_b32 m0, s36
	s_nop 0
	global_load_lds_dwordx4 v[252:253], off
	v_lshl_add_u64 v[252:253], s[28:29], 0, v[168:169]
	s_add_i32 m0, s36, 0x2000
	s_nop 0
	global_load_lds_dwordx4 v[252:253], off
	s_add_i32 s69, s69, 2
	s_add_u32 s67, s67, 0x10000
	s_addc_u32 s68, s68, 0
	s_cmp_gt_u32 s69, 29
	s_mov_b64 s[28:29], s[30:31]
	s_waitcnt vmcnt(8)
	s_waitcnt lgkmcnt(0)
	s_barrier
	v_mfma_f32_16x16x32_bf16 v[60:63], v[128:131], v[144:147], v[60:63]
	v_mfma_f32_16x16x32_bf16 v[56:59], v[136:139], v[144:147], v[56:59]
	v_mfma_f32_16x16x32_bf16 v[44:47], v[128:131], v[152:155], v[44:47]
	v_mfma_f32_16x16x32_bf16 v[40:43], v[136:139], v[152:155], v[40:43]
	v_mfma_f32_16x16x32_bf16 v[28:31], v[128:131], v[160:163], v[28:31]
	v_mfma_f32_16x16x32_bf16 v[24:27], v[136:139], v[160:163], v[24:27]
	v_mfma_f32_16x16x32_bf16 v[12:15], v[128:131], v[184:187], v[12:15]
	v_mfma_f32_16x16x32_bf16 v[8:11], v[136:139], v[184:187], v[8:11]
	v_mfma_f32_16x16x32_bf16 v[60:63], v[132:135], v[148:151], v[60:63]
	v_mfma_f32_16x16x32_bf16 v[56:59], v[140:143], v[148:151], v[56:59]
	v_mfma_f32_16x16x32_bf16 v[44:47], v[132:135], v[156:159], v[44:47]
	v_mfma_f32_16x16x32_bf16 v[40:43], v[140:143], v[156:159], v[40:43]
	v_mfma_f32_16x16x32_bf16 v[28:31], v[132:135], v[180:183], v[28:31]
	v_mfma_f32_16x16x32_bf16 v[24:27], v[140:143], v[180:183], v[24:27]
	v_mfma_f32_16x16x32_bf16 v[12:15], v[132:135], v[188:191], v[12:15]
	v_mfma_f32_16x16x32_bf16 v[8:11], v[140:143], v[188:191], v[8:11]
	v_mfma_f32_16x16x32_bf16 v[52:55], v[200:203], v[144:147], v[52:55]
	v_mfma_f32_16x16x32_bf16 v[48:51], v[208:211], v[144:147], v[48:51]
	v_mfma_f32_16x16x32_bf16 v[36:39], v[200:203], v[152:155], v[36:39]
	v_mfma_f32_16x16x32_bf16 v[32:35], v[208:211], v[152:155], v[32:35]
	v_mfma_f32_16x16x32_bf16 v[20:23], v[200:203], v[160:163], v[20:23]
	v_mfma_f32_16x16x32_bf16 v[16:19], v[208:211], v[160:163], v[16:19]
	v_mfma_f32_16x16x32_bf16 v[4:7], v[200:203], v[184:187], v[4:7]
	v_mfma_f32_16x16x32_bf16 v[0:3], v[208:211], v[184:187], v[0:3]
	v_mfma_f32_16x16x32_bf16 v[52:55], v[204:207], v[148:151], v[52:55]
	v_mfma_f32_16x16x32_bf16 v[48:51], v[212:215], v[148:151], v[48:51]
	v_mfma_f32_16x16x32_bf16 v[36:39], v[204:207], v[156:159], v[36:39]
	v_mfma_f32_16x16x32_bf16 v[32:35], v[212:215], v[156:159], v[32:35]
	v_mfma_f32_16x16x32_bf16 v[20:23], v[204:207], v[180:183], v[20:23]
	v_mfma_f32_16x16x32_bf16 v[16:19], v[212:215], v[180:183], v[16:19]
	v_mfma_f32_16x16x32_bf16 v[4:7], v[204:207], v[188:191], v[4:7]
	v_mfma_f32_16x16x32_bf16 v[0:3], v[212:215], v[188:191], v[0:3]
	s_cbranch_scc1 .Lunit_exit_5
	s_barrier
	s_branch .LBB0_783

; #define PG8_STAGE(bufoff, gbase, voff) do { _Pragma("unroll") for (int _i = 0; _i < 2; ++_i) \
;         __builtin_amdgcn_global_load_lds((const unsigned*)((const char*)(gbase) + (voff)[_i]), (PG8_LAS unsigned*)(lds + (bufoff) + ldsw + _i * 8192), 16, 0, 0); } while (0)
; #define PG8_LDA(dst, b, h) do { _Pragma("unroll") for (int m = 0; m < 4; ++m) _Pragma("unroll") for (int k = 0; k < 2; ++k) dst[m][k] = *(const PG8_LAS bf16x8*)(lds + PG8_SA(b, h) + aoff + m * 2048 + k * 1024); } while (0)
; #define PG8_LDB(dst, b, h) do { _Pragma("unroll") for (int n = 0; n < 2; ++n) _Pragma("unroll") for (int k = 0; k < 2; ++k) dst[n][k] = *(const PG8_LAS bf16x8*)(lds + PG8_SB(b, h) + boff + n * 2048 + k * 1024); } while (0)
; #define PG8_MMA(ai, bj, At, Bt) do { __builtin_amdgcn_s_setprio(1); _Pragma("unroll") for (int m = 0; m < 4; ++m) _Pragma("unroll") for (int n = 0; n < 2; ++n) _Pragma("unroll") for (int k = 0; k < 2; ++k) \
;         acc[ai][bj][m][n] = __builtin_amdgcn_mfma_f32_16x16x32_bf16(Bt[n][k], At[m][k], acc[ai][bj][m][n], 0, 0, 0); __builtin_amdgcn_s_setprio(0); } while (0)
; #define PG8_WAIT_L(n) asm volatile("s_waitcnt lgkmcnt(" #n ")" ::: "memory")
; #define PG8_BAR __builtin_amdgcn_s_barrier()
; #define PG8_SCHED __builtin_amdgcn_sched_barrier(0)
; template <class Epi, class Sched>
; __device__ __forceinline__ void gemm_phase(PG8_LAS unsigned char* lds, const Gemm g, const Sched& S, const Epi& E) {
;     ...
;         for (int t = 0; t < nt; t += 2) {
;             const bool last = (t == nt - 2);
;             const char* a1 = cA + (size_t)(t + 1) * kstep;
;             const char* a2 = last ? nA : cA + (size_t)(t + 2) * kstep; const char* b2 = last ? nB : cB + (size_t)(t + 2) * kstepB;
;             const char* a3 = a2 + kstep; const char* b3 = b2 + kstepB;
;             if (last && has_next) S.a_ready(nxt);
;             PG8_LDB(B0, 0, 0); PG8_SCHED; PG8_LDA(At, 0, 0); PG8_STAGE(PG8_SA(1, 1), a1 + hstep, voffA);
;             PG8_WAIT_L(8); PG8_BAR; PG8_WAIT_L(0); PG8_MMA(0, 0, At, B0); PG8_BAR; PG8_SCHED;
;             PG8_LDB(B1, 0, 1); PG8_STAGE(PG8_SB(0, 0), b2, voffB);
;             PG8_BAR; PG8_WAIT_L(0); PG8_MMA(0, 1, At, B1); PG8_BAR;
;             PG8_LDA(At, 0, 1); PG8_STAGE(PG8_SA(0, 0), a2, voffA);
;             PG8_BAR; PG8_WAIT_L(0); PG8_MMA(1, 0, At, B0); PG8_BAR; PG8_SCHED;
;             PG8_STAGE(PG8_SB(0, 1), b2 + hstepB, voffB);
.Lhalf_skip_y_6:
.LBB0_904:
	ds_read_b128 v[152:155], v149
	ds_read_b128 v[156:159], v149 offset:1024
	ds_read_b128 v[160:163], v149 offset:2048
	ds_read_b128 v[164:167], v149 offset:3072
	s_add_u32 s22, s20, 0xfff80080
	s_addc_u32 s23, s21, -1
	s_cmp_eq_u32 s61, 28
	s_cselect_b32 s25, s11, s23
	s_cselect_b32 s24, s57, s22
	s_cselect_b32 s23, s13, s60
	s_cselect_b32 s22, s58, s59
	v_lshl_add_u64 v[144:145], s[20:21], 0, v[136:137]
	s_add_i32 m0, s19, 0xc000
	ds_read_b128 v[168:171], v150
	ds_read_b128 v[172:175], v150 offset:1024
	ds_read_b128 v[176:179], v150 offset:2048
	ds_read_b128 v[180:183], v150 offset:3072
	ds_read_b128 v[184:187], v150 offset:4096
	ds_read_b128 v[188:191], v150 offset:5120
	ds_read_b128 v[192:195], v150 offset:6144
	ds_read_b128 v[196:199], v150 offset:7168
	global_load_lds_dwordx4 v[144:145], off
	v_lshl_add_u64 v[144:145], s[20:21], 0, v[138:139]
	s_add_i32 m0, s19, 0xe000
	s_nop 0
	global_load_lds_dwordx4 v[144:145], off
	s_add_i32 s62, s53, s38
	v_lshl_add_u64 v[144:145], s[22:23], 0, v[128:129]
	s_mov_b32 m0, s62
	ds_read_b128 v[200:203], v151
	ds_read_b128 v[204:207], v151 offset:1024
	ds_read_b128 v[208:211], v151 offset:2048
	ds_read_b128 v[212:215], v151 offset:3072
	s_waitcnt vmcnt(8)
	s_waitcnt lgkmcnt(0)
	s_barrier
	v_mfma_f32_16x16x32_bf16 v[124:127], v[152:155], v[168:171], v[124:127]
	v_mfma_f32_16x16x32_bf16 v[120:123], v[160:163], v[168:171], v[120:123]
	v_mfma_f32_16x16x32_bf16 v[108:111], v[152:155], v[176:179], v[108:111]
	v_mfma_f32_16x16x32_bf16 v[104:107], v[160:163], v[176:179], v[104:107]
	v_mfma_f32_16x16x32_bf16 v[92:95], v[152:155], v[184:187], v[92:95]
	v_mfma_f32_16x16x32_bf16 v[88:91], v[160:163], v[184:187], v[88:91]
	v_mfma_f32_16x16x32_bf16 v[76:79], v[152:155], v[192:195], v[76:79]
	v_mfma_f32_16x16x32_bf16 v[72:75], v[160:163], v[192:195], v[72:75]
	v_mfma_f32_16x16x32_bf16 v[124:127], v[156:159], v[172:175], v[124:127]
	v_mfma_f32_16x16x32_bf16 v[120:123], v[164:167], v[172:175], v[120:123]
	v_mfma_f32_16x16x32_bf16 v[108:111], v[156:159], v[180:183], v[108:111]
	v_mfma_f32_16x16x32_bf16 v[104:107], v[164:167], v[180:183], v[104:107]
	v_mfma_f32_16x16x32_bf16 v[92:95], v[156:159], v[188:191], v[92:95]
	v_mfma_f32_16x16x32_bf16 v[88:91], v[164:167], v[188:191], v[88:91]
	v_mfma_f32_16x16x32_bf16 v[76:79], v[156:159], v[196:199], v[76:79]
	v_mfma_f32_16x16x32_bf16 v[72:75], v[164:167], v[196:199], v[72:75]
	v_mfma_f32_16x16x32_bf16 v[116:119], v[200:203], v[168:171], v[116:119]
	v_mfma_f32_16x16x32_bf16 v[112:115], v[208:211], v[168:171], v[112:115]
	v_mfma_f32_16x16x32_bf16 v[100:103], v[200:203], v[176:179], v[100:103]
	v_mfma_f32_16x16x32_bf16 v[96:99], v[208:211], v[176:179], v[96:99]
	v_mfma_f32_16x16x32_bf16 v[84:87], v[200:203], v[184:187], v[84:87]
	v_mfma_f32_16x16x32_bf16 v[80:83], v[208:211], v[184:187], v[80:83]
	v_mfma_f32_16x16x32_bf16 v[68:71], v[200:203], v[192:195], v[68:71]
	v_mfma_f32_16x16x32_bf16 v[64:67], v[208:211], v[192:195], v[64:67]
	v_mfma_f32_16x16x32_bf16 v[116:119], v[204:207], v[172:175], v[116:119]
	v_mfma_f32_16x16x32_bf16 v[112:115], v[212:215], v[172:175], v[112:115]
	v_mfma_f32_16x16x32_bf16 v[100:103], v[204:207], v[180:183], v[100:103]
	v_mfma_f32_16x16x32_bf16 v[96:99], v[212:215], v[180:183], v[96:99]
	v_mfma_f32_16x16x32_bf16 v[84:87], v[204:207], v[188:191], v[84:87]
	v_mfma_f32_16x16x32_bf16 v[80:83], v[212:215], v[188:191], v[80:83]
	v_mfma_f32_16x16x32_bf16 v[68:71], v[204:207], v[196:199], v[68:71]
	v_mfma_f32_16x16x32_bf16 v[64:67], v[212:215], v[196:199], v[64:67]
	s_barrier
	global_load_lds_dwordx4 v[144:145], off
	v_lshl_add_u64 v[144:145], s[22:23], 0, v[130:131]
	s_add_i32 m0, s62, 0x2000
	s_nop 0
	global_load_lds_dwordx4 v[144:145], off
	s_mov_b32 m0, s19
	v_lshl_add_u64 v[144:145], s[24:25], 0, v[134:135]
	ds_read_b128 v[168:171], v150 offset:16384
	ds_read_b128 v[172:175], v150 offset:17408
	ds_read_b128 v[176:179], v150 offset:18432
	ds_read_b128 v[180:183], v150 offset:19456
	ds_read_b128 v[184:187], v150 offset:20480
	ds_read_b128 v[188:191], v150 offset:21504
	ds_read_b128 v[192:195], v150 offset:22528
	ds_read_b128 v[196:199], v150 offset:23552
	global_load_lds_dwordx4 v[144:145], off
	v_lshl_add_u64 v[216:217], s[24:25], 0, v[132:133]
	s_mov_b32 m0, s46
	s_nop 0
	global_load_lds_dwordx4 v[216:217], off
	s_add_u32 s62, s22, 0x4000
	s_addc_u32 s63, s23, 0
	s_add_i32 s64, s54, s38
	v_lshl_add_u64 v[250:251], s[62:63], 0, v[128:129]
	s_mov_b32 m0, s64
	s_nop 0
	global_load_lds_dwordx4 v[250:251], off
	v_lshl_add_u64 v[250:251], s[62:63], 0, v[130:131]
	s_add_i32 m0, s64, 0x2000
	s_nop 0
	global_load_lds_dwordx4 v[250:251], off
	s_waitcnt vmcnt(8)
	s_waitcnt lgkmcnt(0)
	s_barrier
; #define PG8_STAGE(bufoff, gbase, voff) do { _Pragma("unroll") for (int _i = 0; _i < 2; ++_i) \
;         __builtin_amdgcn_global_load_lds((const unsigned*)((const char*)(gbase) + (voff)[_i]), (PG8_LAS unsigned*)(lds + (bufoff) + ldsw + _i * 8192), 16, 0, 0); } while (0)
; #define PG8_LDA(dst, b, h) do { _Pragma("unroll") for (int m = 0; m < 4; ++m) _Pragma("unroll") for (int k = 0; k < 2; ++k) dst[m][k] = *(const PG8_LAS bf16x8*)(lds + PG8_SA(b, h) + aoff + m * 2048 + k * 1024); } while (0)
; #define PG8_LDB(dst, b, h) do { _Pragma("unroll") for (int n = 0; n < 2; ++n) _Pragma("unroll") for (int k = 0; k < 2; ++k) dst[n][k] = *(const PG8_LAS bf16x8*)(lds + PG8_SB(b, h) + boff + n * 2048 + k * 1024); } while (0)
; #define PG8_MMA(ai, bj, At, Bt) do { __builtin_amdgcn_s_setprio(1); _Pragma("unroll") for (int m = 0; m < 4; ++m) _Pragma("unroll") for (int n = 0; n < 2; ++n) _Pragma("unroll") for (int k = 0; k < 2; ++k) \
;         acc[ai][bj][m][n] = __builtin_amdgcn_mfma_f32_16x16x32_bf16(Bt[n][k], At[m][k], acc[ai][bj][m][n], 0, 0, 0); __builtin_amdgcn_s_setprio(0); } while (0)
; #define PG8_WAIT_V(n) asm volatile("s_waitcnt vmcnt(" #n ")" ::: "memory")
; #define PG8_WAIT_L(n) asm volatile("s_waitcnt lgkmcnt(" #n ")" ::: "memory")
; #define PG8_BAR __builtin_amdgcn_s_barrier()
; #define PG8_SCHED __builtin_amdgcn_sched_barrier(0)
; template <class Epi, class Sched>
; __device__ __forceinline__ void gemm_phase(PG8_LAS unsigned char* lds, const Gemm g, const Sched& S, const Epi& E) {
;     ...
;             PG8_WAIT_V(6); PG8_BAR; PG8_MMA(1, 1, At, B1); PG8_BAR;
;             PG8_LDB(B0, 1, 0); PG8_SCHED; PG8_LDA(At, 1, 0); PG8_STAGE(PG8_SA(0, 1), a2 + hstep, voffA);
;             PG8_WAIT_L(8); PG8_BAR; PG8_WAIT_L(0); PG8_MMA(0, 0, At, B0); PG8_BAR; PG8_SCHED;
;             PG8_LDB(B1, 1, 1); PG8_STAGE(PG8_SB(1, 0), b3, voffB);
;             PG8_BAR; PG8_WAIT_L(0); PG8_MMA(0, 1, At, B1); PG8_BAR;
	v_mfma_f32_16x16x32_bf16 v[60:63], v[152:155], v[168:171], v[60:63]
	v_mfma_f32_16x16x32_bf16 v[56:59], v[160:163], v[168:171], v[56:59]
	v_mfma_f32_16x16x32_bf16 v[44:47], v[152:155], v[176:179], v[44:47]
	v_mfma_f32_16x16x32_bf16 v[40:43], v[160:163], v[176:179], v[40:43]
	v_mfma_f32_16x16x32_bf16 v[28:31], v[152:155], v[184:187], v[28:31]
	v_mfma_f32_16x16x32_bf16 v[24:27], v[160:163], v[184:187], v[24:27]
	v_mfma_f32_16x16x32_bf16 v[12:15], v[152:155], v[192:195], v[12:15]
	v_mfma_f32_16x16x32_bf16 v[8:11], v[160:163], v[192:195], v[8:11]
	v_mfma_f32_16x16x32_bf16 v[60:63], v[156:159], v[172:175], v[60:63]
	v_mfma_f32_16x16x32_bf16 v[56:59], v[164:167], v[172:175], v[56:59]
	v_mfma_f32_16x16x32_bf16 v[44:47], v[156:159], v[180:183], v[44:47]
	v_mfma_f32_16x16x32_bf16 v[40:43], v[164:167], v[180:183], v[40:43]
	v_mfma_f32_16x16x32_bf16 v[28:31], v[156:159], v[188:191], v[28:31]
	v_mfma_f32_16x16x32_bf16 v[24:27], v[164:167], v[188:191], v[24:27]
	v_mfma_f32_16x16x32_bf16 v[12:15], v[156:159], v[196:199], v[12:15]
	v_mfma_f32_16x16x32_bf16 v[8:11], v[164:167], v[196:199], v[8:11]
	v_mfma_f32_16x16x32_bf16 v[52:55], v[200:203], v[168:171], v[52:55]
	v_mfma_f32_16x16x32_bf16 v[48:51], v[208:211], v[168:171], v[48:51]
	v_mfma_f32_16x16x32_bf16 v[36:39], v[200:203], v[176:179], v[36:39]
	v_mfma_f32_16x16x32_bf16 v[32:35], v[208:211], v[176:179], v[32:35]
	v_mfma_f32_16x16x32_bf16 v[20:23], v[200:203], v[184:187], v[20:23]
	v_mfma_f32_16x16x32_bf16 v[16:19], v[208:211], v[184:187], v[16:19]
	v_mfma_f32_16x16x32_bf16 v[4:7], v[200:203], v[192:195], v[4:7]
	v_mfma_f32_16x16x32_bf16 v[0:3], v[208:211], v[192:195], v[0:3]
	v_mfma_f32_16x16x32_bf16 v[52:55], v[204:207], v[172:175], v[52:55]
	v_mfma_f32_16x16x32_bf16 v[48:51], v[212:215], v[172:175], v[48:51]
	v_mfma_f32_16x16x32_bf16 v[36:39], v[204:207], v[180:183], v[36:39]
	v_mfma_f32_16x16x32_bf16 v[32:35], v[212:215], v[180:183], v[32:35]
	v_mfma_f32_16x16x32_bf16 v[20:23], v[204:207], v[188:191], v[20:23]
	v_mfma_f32_16x16x32_bf16 v[16:19], v[212:215], v[188:191], v[16:19]
	v_mfma_f32_16x16x32_bf16 v[4:7], v[204:207], v[196:199], v[4:7]
	v_mfma_f32_16x16x32_bf16 v[0:3], v[212:215], v[196:199], v[0:3]
	s_barrier
	s_add_i32 s62, 0, 0x18000
	v_add_u32_e32 v164, s62, v147
	ds_read_b128 v[152:155], v164
	ds_read_b128 v[156:159], v164 offset:1024
	ds_read_b128 v[160:163], v164 offset:2048
	ds_read_b128 v[164:167], v164 offset:3072
	s_add_u32 s24, s24, 0x80000
	s_addc_u32 s25, s25, 0
	s_mov_b32 m0, s47
	v_lshl_add_u64 v[200:201], s[24:25], 0, v[134:135]
	ds_read_b128 v[168:171], v150 offset:32768
	ds_read_b128 v[172:175], v150 offset:33792
	ds_read_b128 v[176:179], v150 offset:34816
	ds_read_b128 v[180:183], v150 offset:35840
	ds_read_b128 v[184:187], v150 offset:36864
	ds_read_b128 v[188:191], v150 offset:37888
	ds_read_b128 v[192:195], v150 offset:38912
	ds_read_b128 v[196:199], v150 offset:39936
	global_load_lds_dwordx4 v[200:201], off
	v_lshl_add_u64 v[200:201], s[24:25], 0, v[132:133]
	s_mov_b32 m0, s48
	s_nop 0
	global_load_lds_dwordx4 v[200:201], off
	s_add_i32 s63, 0, 0x1c000
	s_add_u32 s24, s22, 0x8000
	s_addc_u32 s25, s23, 0
	s_add_i32 s62, s62, s38
	v_add_u32_e32 v212, s63, v147
	v_lshl_add_u64 v[218:219], s[24:25], 0, v[128:129]
	s_mov_b32 m0, s62
	ds_read_b128 v[200:203], v212
	ds_read_b128 v[204:207], v212 offset:1024
	ds_read_b128 v[208:211], v212 offset:2048
	ds_read_b128 v[212:215], v212 offset:3072
	s_waitcnt vmcnt(8)
	s_waitcnt lgkmcnt(0)
	s_barrier
	v_mfma_f32_16x16x32_bf16 v[124:127], v[152:155], v[168:171], v[124:127]
	v_mfma_f32_16x16x32_bf16 v[120:123], v[160:163], v[168:171], v[120:123]
	v_mfma_f32_16x16x32_bf16 v[108:111], v[152:155], v[176:179], v[108:111]
	v_mfma_f32_16x16x32_bf16 v[104:107], v[160:163], v[176:179], v[104:107]
	v_mfma_f32_16x16x32_bf16 v[92:95], v[152:155], v[184:187], v[92:95]
	v_mfma_f32_16x16x32_bf16 v[88:91], v[160:163], v[184:187], v[88:91]
	v_mfma_f32_16x16x32_bf16 v[76:79], v[152:155], v[192:195], v[76:79]
	v_mfma_f32_16x16x32_bf16 v[72:75], v[160:163], v[192:195], v[72:75]
	v_mfma_f32_16x16x32_bf16 v[124:127], v[156:159], v[172:175], v[124:127]
	v_mfma_f32_16x16x32_bf16 v[120:123], v[164:167], v[172:175], v[120:123]
	v_mfma_f32_16x16x32_bf16 v[108:111], v[156:159], v[180:183], v[108:111]
	v_mfma_f32_16x16x32_bf16 v[104:107], v[164:167], v[180:183], v[104:107]
	v_mfma_f32_16x16x32_bf16 v[92:95], v[156:159], v[188:191], v[92:95]
	v_mfma_f32_16x16x32_bf16 v[88:91], v[164:167], v[188:191], v[88:91]
	v_mfma_f32_16x16x32_bf16 v[76:79], v[156:159], v[196:199], v[76:79]
	v_mfma_f32_16x16x32_bf16 v[72:75], v[164:167], v[196:199], v[72:75]
	v_mfma_f32_16x16x32_bf16 v[116:119], v[200:203], v[168:171], v[116:119]
	v_mfma_f32_16x16x32_bf16 v[112:115], v[208:211], v[168:171], v[112:115]
	v_mfma_f32_16x16x32_bf16 v[100:103], v[200:203], v[176:179], v[100:103]
	v_mfma_f32_16x16x32_bf16 v[96:99], v[208:211], v[176:179], v[96:99]
	v_mfma_f32_16x16x32_bf16 v[84:87], v[200:203], v[184:187], v[84:87]
	v_mfma_f32_16x16x32_bf16 v[80:83], v[208:211], v[184:187], v[80:83]
	v_mfma_f32_16x16x32_bf16 v[68:71], v[200:203], v[192:195], v[68:71]
	v_mfma_f32_16x16x32_bf16 v[64:67], v[208:211], v[192:195], v[64:67]
	v_mfma_f32_16x16x32_bf16 v[116:119], v[204:207], v[172:175], v[116:119]
	v_mfma_f32_16x16x32_bf16 v[112:115], v[212:215], v[172:175], v[112:115]
	v_mfma_f32_16x16x32_bf16 v[100:103], v[204:207], v[180:183], v[100:103]
	v_mfma_f32_16x16x32_bf16 v[96:99], v[212:215], v[180:183], v[96:99]
	v_mfma_f32_16x16x32_bf16 v[84:87], v[204:207], v[188:191], v[84:87]
	v_mfma_f32_16x16x32_bf16 v[80:83], v[212:215], v[188:191], v[80:83]
	v_mfma_f32_16x16x32_bf16 v[68:71], v[204:207], v[196:199], v[68:71]
	v_mfma_f32_16x16x32_bf16 v[64:67], v[212:215], v[196:199], v[64:67]
	s_barrier
; #define PG8_STAGE(bufoff, gbase, voff) do { _Pragma("unroll") for (int _i = 0; _i < 2; ++_i) \
;         __builtin_amdgcn_global_load_lds((const unsigned*)((const char*)(gbase) + (voff)[_i]), (PG8_LAS unsigned*)(lds + (bufoff) + ldsw + _i * 8192), 16, 0, 0); } while (0)
; #define PG8_LDA(dst, b, h) do { _Pragma("unroll") for (int m = 0; m < 4; ++m) _Pragma("unroll") for (int k = 0; k < 2; ++k) dst[m][k] = *(const PG8_LAS bf16x8*)(lds + PG8_SA(b, h) + aoff + m * 2048 + k * 1024); } while (0)
; #define PG8_MMA(ai, bj, At, Bt) do { __builtin_amdgcn_s_setprio(1); _Pragma("unroll") for (int m = 0; m < 4; ++m) _Pragma("unroll") for (int n = 0; n < 2; ++n) _Pragma("unroll") for (int k = 0; k < 2; ++k) \
;         acc[ai][bj][m][n] = __builtin_amdgcn_mfma_f32_16x16x32_bf16(Bt[n][k], At[m][k], acc[ai][bj][m][n], 0, 0, 0); __builtin_amdgcn_s_setprio(0); } while (0)
; #define PG8_WAIT_V(n) asm volatile("s_waitcnt vmcnt(" #n ")" ::: "memory")
; #define PG8_WAIT_L(n) asm volatile("s_waitcnt lgkmcnt(" #n ")" ::: "memory")
; #define PG8_BAR __builtin_amdgcn_s_barrier()
; #define PG8_SCHED __builtin_amdgcn_sched_barrier(0)
; template <class Epi, class Sched>
; __device__ __forceinline__ void gemm_phase(PG8_LAS unsigned char* lds, const Gemm g, const Sched& S, const Epi& E) {
;     ...
;             PG8_LDA(At, 1, 1); PG8_STAGE(PG8_SA(1, 0), a3, voffA);
;             PG8_BAR; PG8_WAIT_L(0); PG8_MMA(1, 0, At, B0); PG8_BAR; PG8_SCHED;
;             PG8_STAGE(PG8_SB(1, 1), b3 + hstepB, voffB);
;             PG8_WAIT_V(6); PG8_BAR; PG8_MMA(1, 1, At, B1); PG8_BAR;
	global_load_lds_dwordx4 v[218:219], off
	v_lshl_add_u64 v[218:219], s[24:25], 0, v[130:131]
	s_add_i32 m0, s62, 0x2000
	s_nop 0
	global_load_lds_dwordx4 v[218:219], off
	s_mov_b32 m0, s50
	v_lshl_add_u64 v[144:145], v[144:145], 0, s[8:9]
	ds_read_b128 v[168:171], v150 offset:49152
	ds_read_b128 v[172:175], v150 offset:50176
	ds_read_b128 v[176:179], v150 offset:51200
	ds_read_b128 v[180:183], v150 offset:52224
	ds_read_b128 v[184:187], v150 offset:53248
	ds_read_b128 v[188:191], v150 offset:54272
	ds_read_b128 v[192:195], v150 offset:55296
	ds_read_b128 v[196:199], v150 offset:56320
	global_load_lds_dwordx4 v[144:145], off
	v_lshl_add_u64 v[144:145], v[216:217], 0, s[8:9]
	s_mov_b32 m0, s51
	s_nop 0
	global_load_lds_dwordx4 v[144:145], off
	s_add_u32 s22, s22, 0xc000
	s_addc_u32 s23, s23, 0
	s_add_i32 s24, s63, s38
	v_lshl_add_u64 v[144:145], s[22:23], 0, v[128:129]
	s_mov_b32 m0, s24
	s_nop 0
	global_load_lds_dwordx4 v[144:145], off
	v_lshl_add_u64 v[144:145], s[22:23], 0, v[130:131]
	s_add_i32 m0, s24, 0x2000
	s_nop 0
	global_load_lds_dwordx4 v[144:145], off
	s_add_i32 s61, s61, 2
	s_add_u32 s59, s59, 0x10000
	s_addc_u32 s60, s60, 0
	s_add_u32 s20, s20, 0x100
	s_addc_u32 s21, s21, 0
	s_cmp_gt_u32 s61, 29
	s_waitcnt vmcnt(8)
	s_waitcnt lgkmcnt(0)
	s_barrier
	v_mfma_f32_16x16x32_bf16 v[60:63], v[152:155], v[168:171], v[60:63]
	v_mfma_f32_16x16x32_bf16 v[56:59], v[160:163], v[168:171], v[56:59]
	v_mfma_f32_16x16x32_bf16 v[44:47], v[152:155], v[176:179], v[44:47]
	v_mfma_f32_16x16x32_bf16 v[40:43], v[160:163], v[176:179], v[40:43]
	v_mfma_f32_16x16x32_bf16 v[28:31], v[152:155], v[184:187], v[28:31]
	v_mfma_f32_16x16x32_bf16 v[24:27], v[160:163], v[184:187], v[24:27]
	v_mfma_f32_16x16x32_bf16 v[12:15], v[152:155], v[192:195], v[12:15]
	v_mfma_f32_16x16x32_bf16 v[8:11], v[160:163], v[192:195], v[8:11]
	v_mfma_f32_16x16x32_bf16 v[60:63], v[156:159], v[172:175], v[60:63]
	v_mfma_f32_16x16x32_bf16 v[56:59], v[164:167], v[172:175], v[56:59]
	v_mfma_f32_16x16x32_bf16 v[44:47], v[156:159], v[180:183], v[44:47]
	v_mfma_f32_16x16x32_bf16 v[40:43], v[164:167], v[180:183], v[40:43]
	v_mfma_f32_16x16x32_bf16 v[28:31], v[156:159], v[188:191], v[28:31]
	v_mfma_f32_16x16x32_bf16 v[24:27], v[164:167], v[188:191], v[24:27]
	v_mfma_f32_16x16x32_bf16 v[12:15], v[156:159], v[196:199], v[12:15]
	v_mfma_f32_16x16x32_bf16 v[8:11], v[164:167], v[196:199], v[8:11]
	v_mfma_f32_16x16x32_bf16 v[52:55], v[200:203], v[168:171], v[52:55]
	v_mfma_f32_16x16x32_bf16 v[48:51], v[208:211], v[168:171], v[48:51]
	v_mfma_f32_16x16x32_bf16 v[36:39], v[200:203], v[176:179], v[36:39]
	v_mfma_f32_16x16x32_bf16 v[32:35], v[208:211], v[176:179], v[32:35]
	v_mfma_f32_16x16x32_bf16 v[20:23], v[200:203], v[184:187], v[20:23]
	v_mfma_f32_16x16x32_bf16 v[16:19], v[208:211], v[184:187], v[16:19]
	v_mfma_f32_16x16x32_bf16 v[4:7], v[200:203], v[192:195], v[4:7]
	v_mfma_f32_16x16x32_bf16 v[0:3], v[208:211], v[192:195], v[0:3]
	v_mfma_f32_16x16x32_bf16 v[52:55], v[204:207], v[172:175], v[52:55]
	v_mfma_f32_16x16x32_bf16 v[48:51], v[212:215], v[172:175], v[48:51]
	v_mfma_f32_16x16x32_bf16 v[36:39], v[204:207], v[180:183], v[36:39]
	v_mfma_f32_16x16x32_bf16 v[32:35], v[212:215], v[180:183], v[32:35]
	v_mfma_f32_16x16x32_bf16 v[20:23], v[204:207], v[188:191], v[20:23]
	v_mfma_f32_16x16x32_bf16 v[16:19], v[212:215], v[188:191], v[16:19]
	v_mfma_f32_16x16x32_bf16 v[4:7], v[204:207], v[196:199], v[4:7]
	v_mfma_f32_16x16x32_bf16 v[0:3], v[212:215], v[196:199], v[0:3]
	s_cbranch_scc1 .Lunit_exit_6
	s_barrier
	s_branch .LBB0_904

; #define PG8_STAGE(bufoff, gbase, voff) do { _Pragma("unroll") for (int _i = 0; _i < 2; ++_i) \
;         __builtin_amdgcn_global_load_lds((const unsigned*)((const char*)(gbase) + (voff)[_i]), (PG8_LAS unsigned*)(lds + (bufoff) + ldsw + _i * 8192), 16, 0, 0); } while (0)
; #define PG8_LDA(dst, b, h) do { _Pragma("unroll") for (int m = 0; m < 4; ++m) _Pragma("unroll") for (int k = 0; k < 2; ++k) dst[m][k] = *(const PG8_LAS bf16x8*)(lds + PG8_SA(b, h) + aoff + m * 2048 + k * 1024); } while (0)
; #define PG8_LDB(dst, b, h) do { _Pragma("unroll") for (int n = 0; n < 2; ++n) _Pragma("unroll") for (int k = 0; k < 2; ++k) dst[n][k] = *(const PG8_LAS bf16x8*)(lds + PG8_SB(b, h) + boff + n * 2048 + k * 1024); } while (0)
; #define PG8_MMA(ai, bj, At, Bt) do { __builtin_amdgcn_s_setprio(1); _Pragma("unroll") for (int m = 0; m < 4; ++m) _Pragma("unroll") for (int n = 0; n < 2; ++n) _Pragma("unroll") for (int k = 0; k < 2; ++k) \
;         acc[ai][bj][m][n] = __builtin_amdgcn_mfma_f32_16x16x32_bf16(Bt[n][k], At[m][k], acc[ai][bj][m][n], 0, 0, 0); __builtin_amdgcn_s_setprio(0); } while (0)
; #define PG8_WAIT_L(n) asm volatile("s_waitcnt lgkmcnt(" #n ")" ::: "memory")
; #define PG8_BAR __builtin_amdgcn_s_barrier()
; #define PG8_SCHED __builtin_amdgcn_sched_barrier(0)
; template <class Epi, class Sched>
; __device__ __forceinline__ void gemm_phase(PG8_LAS unsigned char* lds, const Gemm g, const Sched& S, const Epi& E) {
;     ...
;         for (int t = 0; t < nt; t += 2) {
;             const bool last = (t == nt - 2);
;             const char* a1 = cA + (size_t)(t + 1) * kstep;
;             const char* a2 = last ? nA : cA + (size_t)(t + 2) * kstep; const char* b2 = last ? nB : cB + (size_t)(t + 2) * kstepB;
;             const char* a3 = a2 + kstep; const char* b3 = b2 + kstepB;
;             if (last && has_next) S.a_ready(nxt);
;             PG8_LDB(B0, 0, 0); PG8_SCHED; PG8_LDA(At, 0, 0); PG8_STAGE(PG8_SA(1, 1), a1 + hstep, voffA);
;             PG8_WAIT_L(8); PG8_BAR; PG8_WAIT_L(0); PG8_MMA(0, 0, At, B0); PG8_BAR; PG8_SCHED;
;             PG8_LDB(B1, 0, 1); PG8_STAGE(PG8_SB(0, 0), b2, voffB);
;             PG8_BAR; PG8_WAIT_L(0); PG8_MMA(0, 1, At, B1); PG8_BAR;
;             PG8_LDA(At, 0, 1); PG8_STAGE(PG8_SA(0, 0), a2, voffA);
;             PG8_BAR; PG8_WAIT_L(0); PG8_MMA(1, 0, At, B0); PG8_BAR; PG8_SCHED;
;             PG8_STAGE(PG8_SB(0, 1), b2 + hstepB, voffB);
.Lhalf_skip_y_7:
.LBB0_980:
	ds_read_b128 v[128:131], v197
	ds_read_b128 v[132:135], v197 offset:1024
	ds_read_b128 v[136:139], v197 offset:2048
	ds_read_b128 v[140:143], v197 offset:3072
	s_add_u32 s24, s22, 0x100
	s_addc_u32 s25, s23, 0
	s_cmpk_eq_i32 s65, 0x52
	s_cselect_b32 s29, s7, s25
	s_cselect_b32 s28, s6, s24
	s_cselect_b32 s27, s9, s64
	s_cselect_b32 s26, s8, s63
	v_lshl_add_u64 v[192:193], s[22:23], 0, v[172:173]
	s_add_i32 m0, s49, 0xc000
	ds_read_b128 v[144:147], v198
	ds_read_b128 v[148:151], v198 offset:1024
	ds_read_b128 v[152:155], v198 offset:2048
	ds_read_b128 v[156:159], v198 offset:3072
	ds_read_b128 v[160:163], v198 offset:4096
	ds_read_b128 v[180:183], v198 offset:5120
	ds_read_b128 v[184:187], v198 offset:6144
	ds_read_b128 v[188:191], v198 offset:7168
	global_load_lds_dwordx4 v[192:193], off
	v_lshl_add_u64 v[192:193], s[22:23], 0, v[174:175]
	s_add_i32 m0, s49, 0xe000
	s_nop 0
	global_load_lds_dwordx4 v[192:193], off
	s_add_i32 s22, s57, s48
	v_lshl_add_u64 v[192:193], s[26:27], 0, v[164:165]
	s_mov_b32 m0, s22
	ds_read_b128 v[200:203], v199
	ds_read_b128 v[204:207], v199 offset:1024
	ds_read_b128 v[208:211], v199 offset:2048
	ds_read_b128 v[212:215], v199 offset:3072
	s_waitcnt vmcnt(8)
	s_waitcnt lgkmcnt(0)
	s_barrier
	v_mfma_f32_16x16x32_bf16 v[124:127], v[128:131], v[144:147], v[124:127]
	v_mfma_f32_16x16x32_bf16 v[120:123], v[136:139], v[144:147], v[120:123]
	v_mfma_f32_16x16x32_bf16 v[116:119], v[128:131], v[152:155], v[116:119]
	v_mfma_f32_16x16x32_bf16 v[104:107], v[136:139], v[152:155], v[104:107]
	v_mfma_f32_16x16x32_bf16 v[92:95], v[128:131], v[160:163], v[92:95]
	v_mfma_f32_16x16x32_bf16 v[88:91], v[136:139], v[160:163], v[88:91]
	v_mfma_f32_16x16x32_bf16 v[76:79], v[128:131], v[184:187], v[76:79]
	v_mfma_f32_16x16x32_bf16 v[72:75], v[136:139], v[184:187], v[72:75]
	v_mfma_f32_16x16x32_bf16 v[124:127], v[132:135], v[148:151], v[124:127]
	v_mfma_f32_16x16x32_bf16 v[120:123], v[140:143], v[148:151], v[120:123]
	v_mfma_f32_16x16x32_bf16 v[116:119], v[132:135], v[156:159], v[116:119]
	v_mfma_f32_16x16x32_bf16 v[104:107], v[140:143], v[156:159], v[104:107]
	v_mfma_f32_16x16x32_bf16 v[92:95], v[132:135], v[180:183], v[92:95]
	v_mfma_f32_16x16x32_bf16 v[88:91], v[140:143], v[180:183], v[88:91]
	v_mfma_f32_16x16x32_bf16 v[76:79], v[132:135], v[188:191], v[76:79]
	v_mfma_f32_16x16x32_bf16 v[72:75], v[140:143], v[188:191], v[72:75]
	v_mfma_f32_16x16x32_bf16 v[112:115], v[200:203], v[144:147], v[112:115]
	v_mfma_f32_16x16x32_bf16 v[108:111], v[208:211], v[144:147], v[108:111]
	v_mfma_f32_16x16x32_bf16 v[100:103], v[200:203], v[152:155], v[100:103]
	v_mfma_f32_16x16x32_bf16 v[96:99], v[208:211], v[152:155], v[96:99]
	v_mfma_f32_16x16x32_bf16 v[84:87], v[200:203], v[160:163], v[84:87]
	v_mfma_f32_16x16x32_bf16 v[80:83], v[208:211], v[160:163], v[80:83]
	v_mfma_f32_16x16x32_bf16 v[68:71], v[200:203], v[184:187], v[68:71]
	v_mfma_f32_16x16x32_bf16 v[64:67], v[208:211], v[184:187], v[64:67]
	v_mfma_f32_16x16x32_bf16 v[112:115], v[204:207], v[148:151], v[112:115]
	v_mfma_f32_16x16x32_bf16 v[108:111], v[212:215], v[148:151], v[108:111]
	v_mfma_f32_16x16x32_bf16 v[100:103], v[204:207], v[156:159], v[100:103]
	v_mfma_f32_16x16x32_bf16 v[96:99], v[212:215], v[156:159], v[96:99]
	v_mfma_f32_16x16x32_bf16 v[84:87], v[204:207], v[180:183], v[84:87]
	v_mfma_f32_16x16x32_bf16 v[80:83], v[212:215], v[180:183], v[80:83]
	v_mfma_f32_16x16x32_bf16 v[68:71], v[204:207], v[188:191], v[68:71]
	v_mfma_f32_16x16x32_bf16 v[64:67], v[212:215], v[188:191], v[64:67]
	s_barrier
	global_load_lds_dwordx4 v[192:193], off
	v_lshl_add_u64 v[192:193], s[26:27], 0, v[168:169]
	s_add_i32 m0, s22, 0x2000
	s_nop 0
	global_load_lds_dwordx4 v[192:193], off
	s_mov_b32 m0, s49
	v_lshl_add_u64 v[192:193], s[28:29], 0, v[166:167]
	ds_read_b128 v[144:147], v198 offset:16384
	ds_read_b128 v[148:151], v198 offset:17408
	ds_read_b128 v[152:155], v198 offset:18432
	ds_read_b128 v[156:159], v198 offset:19456
	ds_read_b128 v[160:163], v198 offset:20480
	ds_read_b128 v[180:183], v198 offset:21504
	ds_read_b128 v[184:187], v198 offset:22528
	ds_read_b128 v[188:191], v198 offset:23552
	global_load_lds_dwordx4 v[192:193], off
	v_lshl_add_u64 v[216:217], s[28:29], 0, v[170:171]
	s_mov_b32 m0, s50
	s_nop 0
	global_load_lds_dwordx4 v[216:217], off
	s_add_u32 s22, s26, 0x4000
	s_addc_u32 s23, s27, 0
	s_add_i32 s66, s58, s48
	v_lshl_add_u64 v[250:251], s[22:23], 0, v[164:165]
	s_mov_b32 m0, s66
	s_nop 0
	global_load_lds_dwordx4 v[250:251], off
	v_lshl_add_u64 v[250:251], s[22:23], 0, v[168:169]
	s_add_i32 m0, s66, 0x2000
	s_nop 0
	global_load_lds_dwordx4 v[250:251], off
	s_waitcnt vmcnt(8)
	s_waitcnt lgkmcnt(0)
	s_barrier
; #define PG8_STAGE(bufoff, gbase, voff) do { _Pragma("unroll") for (int _i = 0; _i < 2; ++_i) \
;         __builtin_amdgcn_global_load_lds((const unsigned*)((const char*)(gbase) + (voff)[_i]), (PG8_LAS unsigned*)(lds + (bufoff) + ldsw + _i * 8192), 16, 0, 0); } while (0)
; #define PG8_LDA(dst, b, h) do { _Pragma("unroll") for (int m = 0; m < 4; ++m) _Pragma("unroll") for (int k = 0; k < 2; ++k) dst[m][k] = *(const PG8_LAS bf16x8*)(lds + PG8_SA(b, h) + aoff + m * 2048 + k * 1024); } while (0)
; #define PG8_LDB(dst, b, h) do { _Pragma("unroll") for (int n = 0; n < 2; ++n) _Pragma("unroll") for (int k = 0; k < 2; ++k) dst[n][k] = *(const PG8_LAS bf16x8*)(lds + PG8_SB(b, h) + boff + n * 2048 + k * 1024); } while (0)
; #define PG8_MMA(ai, bj, At, Bt) do { __builtin_amdgcn_s_setprio(1); _Pragma("unroll") for (int m = 0; m < 4; ++m) _Pragma("unroll") for (int n = 0; n < 2; ++n) _Pragma("unroll") for (int k = 0; k < 2; ++k) \
;         acc[ai][bj][m][n] = __builtin_amdgcn_mfma_f32_16x16x32_bf16(Bt[n][k], At[m][k], acc[ai][bj][m][n], 0, 0, 0); __builtin_amdgcn_s_setprio(0); } while (0)
; #define PG8_WAIT_V(n) asm volatile("s_waitcnt vmcnt(" #n ")" ::: "memory")
; #define PG8_WAIT_L(n) asm volatile("s_waitcnt lgkmcnt(" #n ")" ::: "memory")
; #define PG8_BAR __builtin_amdgcn_s_barrier()
; #define PG8_SCHED __builtin_amdgcn_sched_barrier(0)
; template <class Epi, class Sched>
; __device__ __forceinline__ void gemm_phase(PG8_LAS unsigned char* lds, const Gemm g, const Sched& S, const Epi& E) {
;     ...
;             PG8_BAR; PG8_WAIT_L(0); PG8_MMA(1, 0, At, B0); PG8_BAR; PG8_SCHED;
;             PG8_STAGE(PG8_SB(0, 1), b2 + hstepB, voffB);
;             PG8_WAIT_V(6); PG8_BAR; PG8_MMA(1, 1, At, B1); PG8_BAR;
;             PG8_LDB(B0, 1, 0); PG8_SCHED; PG8_LDA(At, 1, 0); PG8_STAGE(PG8_SA(0, 1), a2 + hstep, voffA);
;             PG8_WAIT_L(8); PG8_BAR; PG8_WAIT_L(0); PG8_MMA(0, 0, At, B0); PG8_BAR; PG8_SCHED;
;             PG8_LDB(B1, 1, 1); PG8_STAGE(PG8_SB(1, 0), b3, voffB);
;             PG8_BAR; PG8_WAIT_L(0); PG8_MMA(0, 1, At, B1); PG8_BAR;
	v_mfma_f32_16x16x32_bf16 v[60:63], v[128:131], v[144:147], v[60:63]
	v_mfma_f32_16x16x32_bf16 v[56:59], v[136:139], v[144:147], v[56:59]
	v_mfma_f32_16x16x32_bf16 v[44:47], v[128:131], v[152:155], v[44:47]
	v_mfma_f32_16x16x32_bf16 v[40:43], v[136:139], v[152:155], v[40:43]
	v_mfma_f32_16x16x32_bf16 v[28:31], v[128:131], v[160:163], v[28:31]
	v_mfma_f32_16x16x32_bf16 v[24:27], v[136:139], v[160:163], v[24:27]
	v_mfma_f32_16x16x32_bf16 v[12:15], v[128:131], v[184:187], v[12:15]
	v_mfma_f32_16x16x32_bf16 v[8:11], v[136:139], v[184:187], v[8:11]
	v_mfma_f32_16x16x32_bf16 v[60:63], v[132:135], v[148:151], v[60:63]
	v_mfma_f32_16x16x32_bf16 v[56:59], v[140:143], v[148:151], v[56:59]
	v_mfma_f32_16x16x32_bf16 v[44:47], v[132:135], v[156:159], v[44:47]
	v_mfma_f32_16x16x32_bf16 v[40:43], v[140:143], v[156:159], v[40:43]
	v_mfma_f32_16x16x32_bf16 v[28:31], v[132:135], v[180:183], v[28:31]
	v_mfma_f32_16x16x32_bf16 v[24:27], v[140:143], v[180:183], v[24:27]
	v_mfma_f32_16x16x32_bf16 v[12:15], v[132:135], v[188:191], v[12:15]
	v_mfma_f32_16x16x32_bf16 v[8:11], v[140:143], v[188:191], v[8:11]
	v_mfma_f32_16x16x32_bf16 v[52:55], v[200:203], v[144:147], v[52:55]
	v_mfma_f32_16x16x32_bf16 v[48:51], v[208:211], v[144:147], v[48:51]
	v_mfma_f32_16x16x32_bf16 v[36:39], v[200:203], v[152:155], v[36:39]
	v_mfma_f32_16x16x32_bf16 v[32:35], v[208:211], v[152:155], v[32:35]
	v_mfma_f32_16x16x32_bf16 v[20:23], v[200:203], v[160:163], v[20:23]
	v_mfma_f32_16x16x32_bf16 v[16:19], v[208:211], v[160:163], v[16:19]
	v_mfma_f32_16x16x32_bf16 v[4:7], v[200:203], v[184:187], v[4:7]
	v_mfma_f32_16x16x32_bf16 v[0:3], v[208:211], v[184:187], v[0:3]
	v_mfma_f32_16x16x32_bf16 v[52:55], v[204:207], v[148:151], v[52:55]
	v_mfma_f32_16x16x32_bf16 v[48:51], v[212:215], v[148:151], v[48:51]
	v_mfma_f32_16x16x32_bf16 v[36:39], v[204:207], v[156:159], v[36:39]
	v_mfma_f32_16x16x32_bf16 v[32:35], v[212:215], v[156:159], v[32:35]
	v_mfma_f32_16x16x32_bf16 v[20:23], v[204:207], v[180:183], v[20:23]
	v_mfma_f32_16x16x32_bf16 v[16:19], v[212:215], v[180:183], v[16:19]
	v_mfma_f32_16x16x32_bf16 v[4:7], v[204:207], v[188:191], v[4:7]
	v_mfma_f32_16x16x32_bf16 v[0:3], v[212:215], v[188:191], v[0:3]
	s_barrier
	s_add_i32 s66, 0, 0x18000
	v_add_u32_e32 v140, s66, v195
	ds_read_b128 v[128:131], v140
	ds_read_b128 v[132:135], v140 offset:1024
	ds_read_b128 v[136:139], v140 offset:2048
	ds_read_b128 v[140:143], v140 offset:3072
	s_add_u32 s22, s28, 0x158000
	s_addc_u32 s23, s29, 0
	s_mov_b32 m0, s51
	v_lshl_add_u64 v[200:201], s[22:23], 0, v[166:167]
	ds_read_b128 v[144:147], v198 offset:32768
	ds_read_b128 v[148:151], v198 offset:33792
	ds_read_b128 v[152:155], v198 offset:34816
	ds_read_b128 v[156:159], v198 offset:35840
	ds_read_b128 v[160:163], v198 offset:36864
	ds_read_b128 v[180:183], v198 offset:37888
	ds_read_b128 v[184:187], v198 offset:38912
	ds_read_b128 v[188:191], v198 offset:39936
	global_load_lds_dwordx4 v[200:201], off
	v_lshl_add_u64 v[200:201], s[22:23], 0, v[170:171]
	s_mov_b32 m0, s52
	s_nop 0
	global_load_lds_dwordx4 v[200:201], off
	s_add_i32 s28, 0, 0x1c000
	s_add_u32 s22, s26, 0x8000
	s_addc_u32 s23, s27, 0
	s_add_i32 s29, s66, s48
	v_add_u32_e32 v212, s28, v195
	v_lshl_add_u64 v[218:219], s[22:23], 0, v[164:165]
	s_mov_b32 m0, s29
	ds_read_b128 v[200:203], v212
	ds_read_b128 v[204:207], v212 offset:1024
	ds_read_b128 v[208:211], v212 offset:2048
	ds_read_b128 v[212:215], v212 offset:3072
	s_waitcnt vmcnt(8)
	s_waitcnt lgkmcnt(0)
	s_barrier
	v_mfma_f32_16x16x32_bf16 v[124:127], v[128:131], v[144:147], v[124:127]
	v_mfma_f32_16x16x32_bf16 v[120:123], v[136:139], v[144:147], v[120:123]
	v_mfma_f32_16x16x32_bf16 v[116:119], v[128:131], v[152:155], v[116:119]
	v_mfma_f32_16x16x32_bf16 v[104:107], v[136:139], v[152:155], v[104:107]
	v_mfma_f32_16x16x32_bf16 v[92:95], v[128:131], v[160:163], v[92:95]
	v_mfma_f32_16x16x32_bf16 v[88:91], v[136:139], v[160:163], v[88:91]
	v_mfma_f32_16x16x32_bf16 v[76:79], v[128:131], v[184:187], v[76:79]
	v_mfma_f32_16x16x32_bf16 v[72:75], v[136:139], v[184:187], v[72:75]
	v_mfma_f32_16x16x32_bf16 v[124:127], v[132:135], v[148:151], v[124:127]
	v_mfma_f32_16x16x32_bf16 v[120:123], v[140:143], v[148:151], v[120:123]
	v_mfma_f32_16x16x32_bf16 v[116:119], v[132:135], v[156:159], v[116:119]
	v_mfma_f32_16x16x32_bf16 v[104:107], v[140:143], v[156:159], v[104:107]
	v_mfma_f32_16x16x32_bf16 v[92:95], v[132:135], v[180:183], v[92:95]
	v_mfma_f32_16x16x32_bf16 v[88:91], v[140:143], v[180:183], v[88:91]
	v_mfma_f32_16x16x32_bf16 v[76:79], v[132:135], v[188:191], v[76:79]
	v_mfma_f32_16x16x32_bf16 v[72:75], v[140:143], v[188:191], v[72:75]
	v_mfma_f32_16x16x32_bf16 v[112:115], v[200:203], v[144:147], v[112:115]
	v_mfma_f32_16x16x32_bf16 v[108:111], v[208:211], v[144:147], v[108:111]
	v_mfma_f32_16x16x32_bf16 v[100:103], v[200:203], v[152:155], v[100:103]
	v_mfma_f32_16x16x32_bf16 v[96:99], v[208:211], v[152:155], v[96:99]
	v_mfma_f32_16x16x32_bf16 v[84:87], v[200:203], v[160:163], v[84:87]
	v_mfma_f32_16x16x32_bf16 v[80:83], v[208:211], v[160:163], v[80:83]
	v_mfma_f32_16x16x32_bf16 v[68:71], v[200:203], v[184:187], v[68:71]
	v_mfma_f32_16x16x32_bf16 v[64:67], v[208:211], v[184:187], v[64:67]
	v_mfma_f32_16x16x32_bf16 v[112:115], v[204:207], v[148:151], v[112:115]
	v_mfma_f32_16x16x32_bf16 v[108:111], v[212:215], v[148:151], v[108:111]
	v_mfma_f32_16x16x32_bf16 v[100:103], v[204:207], v[156:159], v[100:103]
	v_mfma_f32_16x16x32_bf16 v[96:99], v[212:215], v[156:159], v[96:99]
	v_mfma_f32_16x16x32_bf16 v[84:87], v[204:207], v[180:183], v[84:87]
	v_mfma_f32_16x16x32_bf16 v[80:83], v[212:215], v[180:183], v[80:83]
	v_mfma_f32_16x16x32_bf16 v[68:71], v[204:207], v[188:191], v[68:71]
	v_mfma_f32_16x16x32_bf16 v[64:67], v[212:215], v[188:191], v[64:67]
	s_barrier
; #define PG8_STAGE(bufoff, gbase, voff) do { _Pragma("unroll") for (int _i = 0; _i < 2; ++_i) \
;         __builtin_amdgcn_global_load_lds((const unsigned*)((const char*)(gbase) + (voff)[_i]), (PG8_LAS unsigned*)(lds + (bufoff) + ldsw + _i * 8192), 16, 0, 0); } while (0)
; #define PG8_LDA(dst, b, h) do { _Pragma("unroll") for (int m = 0; m < 4; ++m) _Pragma("unroll") for (int k = 0; k < 2; ++k) dst[m][k] = *(const PG8_LAS bf16x8*)(lds + PG8_SA(b, h) + aoff + m * 2048 + k * 1024); } while (0)
; #define PG8_MMA(ai, bj, At, Bt) do { __builtin_amdgcn_s_setprio(1); _Pragma("unroll") for (int m = 0; m < 4; ++m) _Pragma("unroll") for (int n = 0; n < 2; ++n) _Pragma("unroll") for (int k = 0; k < 2; ++k) \
;         acc[ai][bj][m][n] = __builtin_amdgcn_mfma_f32_16x16x32_bf16(Bt[n][k], At[m][k], acc[ai][bj][m][n], 0, 0, 0); __builtin_amdgcn_s_setprio(0); } while (0)
; #define PG8_WAIT_V(n) asm volatile("s_waitcnt vmcnt(" #n ")" ::: "memory")
; #define PG8_WAIT_L(n) asm volatile("s_waitcnt lgkmcnt(" #n ")" ::: "memory")
; #define PG8_BAR __builtin_amdgcn_s_barrier()
; #define PG8_SCHED __builtin_amdgcn_sched_barrier(0)
; template <class Epi, class Sched>
; __device__ __forceinline__ void gemm_phase(PG8_LAS unsigned char* lds, const Gemm g, const Sched& S, const Epi& E) {
;     ...
;             PG8_LDA(At, 1, 1); PG8_STAGE(PG8_SA(1, 0), a3, voffA);
;             PG8_BAR; PG8_WAIT_L(0); PG8_MMA(1, 0, At, B0); PG8_BAR; PG8_SCHED;
;             PG8_STAGE(PG8_SB(1, 1), b3 + hstepB, voffB);
;             PG8_WAIT_V(6); PG8_BAR; PG8_MMA(1, 1, At, B1); PG8_BAR;
	global_load_lds_dwordx4 v[218:219], off
	v_lshl_add_u64 v[218:219], s[22:23], 0, v[168:169]
	s_add_i32 m0, s29, 0x2000
	s_nop 0
	global_load_lds_dwordx4 v[218:219], off
	s_mov_b32 m0, s54
	v_lshl_add_u64 v[192:193], v[192:193], 0, s[12:13]
	ds_read_b128 v[144:147], v198 offset:49152
	ds_read_b128 v[148:151], v198 offset:50176
	ds_read_b128 v[152:155], v198 offset:51200
	ds_read_b128 v[156:159], v198 offset:52224
	ds_read_b128 v[160:163], v198 offset:53248
	ds_read_b128 v[180:183], v198 offset:54272
	ds_read_b128 v[184:187], v198 offset:55296
	ds_read_b128 v[188:191], v198 offset:56320
	global_load_lds_dwordx4 v[192:193], off
	v_lshl_add_u64 v[192:193], v[216:217], 0, s[12:13]
	s_mov_b32 m0, s55
	s_nop 0
	global_load_lds_dwordx4 v[192:193], off
	s_add_u32 s22, s26, 0xc000
	s_addc_u32 s23, s27, 0
	s_add_i32 s26, s28, s48
	v_lshl_add_u64 v[252:253], s[22:23], 0, v[164:165]
	s_mov_b32 m0, s26
	s_nop 0
	global_load_lds_dwordx4 v[252:253], off
	v_lshl_add_u64 v[252:253], s[22:23], 0, v[168:169]
	s_add_i32 m0, s26, 0x2000
	s_nop 0
	global_load_lds_dwordx4 v[252:253], off
	s_add_i32 s65, s65, 2
	s_add_u32 s63, s63, 0x10000
	s_addc_u32 s64, s64, 0
	s_cmpk_gt_u32 s65, 0x53
	s_mov_b64 s[22:23], s[24:25]
	s_waitcnt vmcnt(8)
	s_waitcnt lgkmcnt(0)
	s_barrier
	v_mfma_f32_16x16x32_bf16 v[60:63], v[128:131], v[144:147], v[60:63]
	v_mfma_f32_16x16x32_bf16 v[56:59], v[136:139], v[144:147], v[56:59]
	v_mfma_f32_16x16x32_bf16 v[44:47], v[128:131], v[152:155], v[44:47]
	v_mfma_f32_16x16x32_bf16 v[40:43], v[136:139], v[152:155], v[40:43]
	v_mfma_f32_16x16x32_bf16 v[28:31], v[128:131], v[160:163], v[28:31]
	v_mfma_f32_16x16x32_bf16 v[24:27], v[136:139], v[160:163], v[24:27]
	v_mfma_f32_16x16x32_bf16 v[12:15], v[128:131], v[184:187], v[12:15]
	v_mfma_f32_16x16x32_bf16 v[8:11], v[136:139], v[184:187], v[8:11]
	v_mfma_f32_16x16x32_bf16 v[60:63], v[132:135], v[148:151], v[60:63]
	v_mfma_f32_16x16x32_bf16 v[56:59], v[140:143], v[148:151], v[56:59]
	v_mfma_f32_16x16x32_bf16 v[44:47], v[132:135], v[156:159], v[44:47]
	v_mfma_f32_16x16x32_bf16 v[40:43], v[140:143], v[156:159], v[40:43]
	v_mfma_f32_16x16x32_bf16 v[28:31], v[132:135], v[180:183], v[28:31]
	v_mfma_f32_16x16x32_bf16 v[24:27], v[140:143], v[180:183], v[24:27]
	v_mfma_f32_16x16x32_bf16 v[12:15], v[132:135], v[188:191], v[12:15]
	v_mfma_f32_16x16x32_bf16 v[8:11], v[140:143], v[188:191], v[8:11]
	v_mfma_f32_16x16x32_bf16 v[52:55], v[200:203], v[144:147], v[52:55]
	v_mfma_f32_16x16x32_bf16 v[48:51], v[208:211], v[144:147], v[48:51]
	v_mfma_f32_16x16x32_bf16 v[36:39], v[200:203], v[152:155], v[36:39]
	v_mfma_f32_16x16x32_bf16 v[32:35], v[208:211], v[152:155], v[32:35]
	v_mfma_f32_16x16x32_bf16 v[20:23], v[200:203], v[160:163], v[20:23]
	v_mfma_f32_16x16x32_bf16 v[16:19], v[208:211], v[160:163], v[16:19]
	v_mfma_f32_16x16x32_bf16 v[4:7], v[200:203], v[184:187], v[4:7]
	v_mfma_f32_16x16x32_bf16 v[0:3], v[208:211], v[184:187], v[0:3]
	v_mfma_f32_16x16x32_bf16 v[52:55], v[204:207], v[148:151], v[52:55]
	v_mfma_f32_16x16x32_bf16 v[48:51], v[212:215], v[148:151], v[48:51]
	v_mfma_f32_16x16x32_bf16 v[36:39], v[204:207], v[156:159], v[36:39]
	v_mfma_f32_16x16x32_bf16 v[32:35], v[212:215], v[156:159], v[32:35]
	v_mfma_f32_16x16x32_bf16 v[20:23], v[204:207], v[180:183], v[20:23]
	v_mfma_f32_16x16x32_bf16 v[16:19], v[212:215], v[180:183], v[16:19]
	v_mfma_f32_16x16x32_bf16 v[4:7], v[204:207], v[188:191], v[4:7]
	v_mfma_f32_16x16x32_bf16 v[0:3], v[212:215], v[188:191], v[0:3]
	s_cbranch_scc1 .Lunit_exit_7
	s_barrier
	s_branch .LBB0_980
